# v43 + K-loop MFMA order: the two k-steps of each accumulator issued back to back (SrcC accumulate chain) instead of 8 apart
# speedup vs baseline: 1.0067x; 1.0014x over previous
.LBB0_496:
	s_cmp_lg_u32 s100, 0
	s_cbranch_scc1 .Lpeel_0
	ds_read_b128 v[150:153], v245
	ds_read_b128 v[162:165], v246
	ds_read_b128 v[166:169], v245 offset:2048
	ds_read_b128 v[170:173], v246 offset:2048
	ds_read_b128 v[174:177], v245 offset:16384
	ds_read_b128 v[178:181], v246 offset:16384
	ds_read_b128 v[182:185], v245 offset:18432
	ds_read_b128 v[186:189], v246 offset:18432
	s_add_u32 s44, s56, 0xfffc0080
	s_addc_u32 s45, s57, -1
	s_and_b64 s[42:43], s[58:59], exec
	s_cselect_b32 s61, s13, s45
	s_cselect_b32 s60, s81, s44
	s_cselect_b32 s59, s11, s85
	s_cselect_b32 s58, s82, s84
	s_add_i32 m0, s62, 0xc000
	ds_read_b128 v[190:193], v158
	ds_read_b128 v[194:197], v158 offset:2048
	ds_read_b128 v[198:201], v159
	ds_read_b128 v[202:205], v159 offset:2048
	ds_read_b128 v[206:209], v158 offset:4096
	ds_read_b128 v[210:213], v158 offset:6144
	ds_read_b128 v[214:217], v159 offset:4096
	ds_read_b128 v[218:221], v159 offset:6144
	global_load_lds_dwordx4 v140, s[56:57]
	s_add_i32 m0, s62, 0xe000
	s_nop 0
	global_load_lds_dwordx4 v142, s[56:57]
	s_waitcnt vmcnt(8)
	s_waitcnt lgkmcnt(0)
	s_barrier
	s_setprio 1
	s_waitcnt lgkmcnt(0)
	v_mfma_f32_16x16x32_bf16 v[126:129], v[150:153], v[190:193], v[126:129]
	v_mfma_f32_16x16x32_bf16 v[126:129], v[162:165], v[198:201], v[126:129]
	v_mfma_f32_16x16x32_bf16 v[118:121], v[166:169], v[190:193], v[118:121]
	v_mfma_f32_16x16x32_bf16 v[118:121], v[170:173], v[198:201], v[118:121]
	v_mfma_f32_16x16x32_bf16 v[110:113], v[150:153], v[194:197], v[110:113]
	v_mfma_f32_16x16x32_bf16 v[110:113], v[162:165], v[202:205], v[110:113]
	v_mfma_f32_16x16x32_bf16 v[102:105], v[166:169], v[194:197], v[102:105]
	v_mfma_f32_16x16x32_bf16 v[102:105], v[170:173], v[202:205], v[102:105]
	v_mfma_f32_16x16x32_bf16 v[94:97], v[150:153], v[206:209], v[94:97]
	v_mfma_f32_16x16x32_bf16 v[94:97], v[162:165], v[214:217], v[94:97]
	v_mfma_f32_16x16x32_bf16 v[86:89], v[166:169], v[206:209], v[86:89]
	v_mfma_f32_16x16x32_bf16 v[86:89], v[170:173], v[214:217], v[86:89]
	v_mfma_f32_16x16x32_bf16 v[78:81], v[150:153], v[210:213], v[78:81]
	v_mfma_f32_16x16x32_bf16 v[78:81], v[162:165], v[218:221], v[78:81]
	v_mfma_f32_16x16x32_bf16 v[70:73], v[166:169], v[210:213], v[70:73]
	v_mfma_f32_16x16x32_bf16 v[70:73], v[170:173], v[218:221], v[70:73]
	s_setprio 0
	s_setprio 1
	v_mfma_f32_16x16x32_bf16 v[122:125], v[174:177], v[190:193], v[122:125]
	v_mfma_f32_16x16x32_bf16 v[122:125], v[178:181], v[198:201], v[122:125]
	v_mfma_f32_16x16x32_bf16 v[114:117], v[182:185], v[190:193], v[114:117]
	v_mfma_f32_16x16x32_bf16 v[114:117], v[186:189], v[198:201], v[114:117]
	v_mfma_f32_16x16x32_bf16 v[106:109], v[174:177], v[194:197], v[106:109]
	v_mfma_f32_16x16x32_bf16 v[106:109], v[178:181], v[202:205], v[106:109]
	v_mfma_f32_16x16x32_bf16 v[98:101], v[182:185], v[194:197], v[98:101]
	v_mfma_f32_16x16x32_bf16 v[98:101], v[186:189], v[202:205], v[98:101]
	v_mfma_f32_16x16x32_bf16 v[90:93], v[174:177], v[206:209], v[90:93]
	v_mfma_f32_16x16x32_bf16 v[90:93], v[178:181], v[214:217], v[90:93]
	v_mfma_f32_16x16x32_bf16 v[82:85], v[182:185], v[206:209], v[82:85]
	v_mfma_f32_16x16x32_bf16 v[82:85], v[186:189], v[214:217], v[82:85]
	v_mfma_f32_16x16x32_bf16 v[74:77], v[174:177], v[210:213], v[74:77]
	v_mfma_f32_16x16x32_bf16 v[74:77], v[178:181], v[218:221], v[74:77]
	v_mfma_f32_16x16x32_bf16 v[66:69], v[182:185], v[210:213], v[66:69]
	v_mfma_f32_16x16x32_bf16 v[66:69], v[186:189], v[218:221], v[66:69]
	s_setprio 0
	s_barrier
	s_add_i32 s42, s72, s55
	s_mov_b32 m0, s42
	ds_read_b128 v[190:193], v158 offset:16384
	ds_read_b128 v[194:197], v158 offset:18432
	ds_read_b128 v[198:201], v159 offset:16384
	ds_read_b128 v[202:205], v159 offset:18432
	ds_read_b128 v[206:209], v158 offset:20480
	ds_read_b128 v[210:213], v158 offset:22528
	ds_read_b128 v[214:217], v159 offset:20480
	ds_read_b128 v[218:221], v159 offset:22528
	global_load_lds_dwordx4 v130, s[58:59]
	s_add_i32 m0, s42, 0x2000
	s_add_u32 s42, s58, 0x40000
	s_addc_u32 s43, s59, 0
	s_add_i32 s44, s74, s55
	global_load_lds_dwordx4 v138, s[58:59]
	s_mov_b32 m0, s44
	s_nop 0
	global_load_lds_dwordx4 v130, s[42:43]
	s_add_i32 m0, s44, 0x2000
	s_nop 0
	global_load_lds_dwordx4 v138, s[42:43]
	s_mov_b32 m0, s62
	s_nop 0
	global_load_lds_dwordx4 v134, s[60:61]
	s_mov_b32 m0, s63
	s_nop 0
	global_load_lds_dwordx4 v136, s[60:61]
	s_waitcnt vmcnt(8)
	s_waitcnt lgkmcnt(0)
	s_barrier
	s_setprio 1
	s_waitcnt lgkmcnt(0)
	v_mfma_f32_16x16x32_bf16 v[62:65], v[150:153], v[190:193], v[62:65]
	v_mfma_f32_16x16x32_bf16 v[62:65], v[162:165], v[198:201], v[62:65]
	v_mfma_f32_16x16x32_bf16 v[54:57], v[166:169], v[190:193], v[54:57]
	v_mfma_f32_16x16x32_bf16 v[54:57], v[170:173], v[198:201], v[54:57]
	v_mfma_f32_16x16x32_bf16 v[46:49], v[150:153], v[194:197], v[46:49]
	v_mfma_f32_16x16x32_bf16 v[46:49], v[162:165], v[202:205], v[46:49]
	v_mfma_f32_16x16x32_bf16 v[38:41], v[166:169], v[194:197], v[38:41]
	v_mfma_f32_16x16x32_bf16 v[38:41], v[170:173], v[202:205], v[38:41]
	v_mfma_f32_16x16x32_bf16 v[30:33], v[150:153], v[206:209], v[30:33]
	v_mfma_f32_16x16x32_bf16 v[30:33], v[162:165], v[214:217], v[30:33]
	v_mfma_f32_16x16x32_bf16 v[22:25], v[166:169], v[206:209], v[22:25]
	v_mfma_f32_16x16x32_bf16 v[22:25], v[170:173], v[214:217], v[22:25]
	v_mfma_f32_16x16x32_bf16 v[14:17], v[150:153], v[210:213], v[14:17]
	v_mfma_f32_16x16x32_bf16 v[14:17], v[162:165], v[218:221], v[14:17]
	v_mfma_f32_16x16x32_bf16 v[6:9], v[166:169], v[210:213], v[6:9]
	v_mfma_f32_16x16x32_bf16 v[6:9], v[170:173], v[218:221], v[6:9]
	s_setprio 0
	s_setprio 1
	v_mfma_f32_16x16x32_bf16 v[58:61], v[174:177], v[190:193], v[58:61]
	v_mfma_f32_16x16x32_bf16 v[58:61], v[178:181], v[198:201], v[58:61]
	v_mfma_f32_16x16x32_bf16 v[50:53], v[182:185], v[190:193], v[50:53]
	v_mfma_f32_16x16x32_bf16 v[50:53], v[186:189], v[198:201], v[50:53]
	v_mfma_f32_16x16x32_bf16 v[42:45], v[174:177], v[194:197], v[42:45]
	v_mfma_f32_16x16x32_bf16 v[42:45], v[178:181], v[202:205], v[42:45]
	v_mfma_f32_16x16x32_bf16 v[34:37], v[182:185], v[194:197], v[34:37]
	v_mfma_f32_16x16x32_bf16 v[34:37], v[186:189], v[202:205], v[34:37]
	v_mfma_f32_16x16x32_bf16 v[26:29], v[174:177], v[206:209], v[26:29]
	v_mfma_f32_16x16x32_bf16 v[26:29], v[178:181], v[214:217], v[26:29]
	v_mfma_f32_16x16x32_bf16 v[18:21], v[182:185], v[206:209], v[18:21]
	v_mfma_f32_16x16x32_bf16 v[18:21], v[186:189], v[214:217], v[18:21]
	v_mfma_f32_16x16x32_bf16 v[10:13], v[174:177], v[210:213], v[10:13]
	v_mfma_f32_16x16x32_bf16 v[10:13], v[178:181], v[218:221], v[10:13]
	v_mfma_f32_16x16x32_bf16 v[2:5], v[182:185], v[210:213], v[2:5]
	v_mfma_f32_16x16x32_bf16 v[2:5], v[186:189], v[218:221], v[2:5]
	s_setprio 0
	s_barrier
	s_add_i32 s44, 0, 0x18000
	ds_read_b128 v[150:153], v245 offset:32768
	ds_read_b128 v[162:165], v246 offset:32768
	s_add_i32 s45, 0, 0x1c000
	ds_read_b128 v[166:169], v245 offset:34816
	ds_read_b128 v[170:173], v246 offset:34816
	ds_read_b128 v[174:177], v245 offset:49152
	ds_read_b128 v[178:181], v246 offset:49152
	ds_read_b128 v[182:185], v245 offset:51200
	ds_read_b128 v[186:189], v246 offset:51200
	s_add_u32 s42, s60, 0x40000
	s_addc_u32 s43, s61, 0
	s_mov_b32 m0, s64
	ds_read_b128 v[190:193], v158 offset:32768
	ds_read_b128 v[194:197], v158 offset:34816
	ds_read_b128 v[198:201], v159 offset:32768
	ds_read_b128 v[202:205], v159 offset:34816
	ds_read_b128 v[206:209], v158 offset:36864
	ds_read_b128 v[210:213], v158 offset:38912
	ds_read_b128 v[214:217], v159 offset:36864
	ds_read_b128 v[218:221], v159 offset:38912
	global_load_lds_dwordx4 v134, s[42:43]
	s_mov_b32 m0, s65
	s_nop 0
	global_load_lds_dwordx4 v136, s[42:43]
	s_waitcnt vmcnt(8)
	s_waitcnt lgkmcnt(0)
	s_barrier
	s_setprio 1
	s_waitcnt lgkmcnt(0)
	v_mfma_f32_16x16x32_bf16 v[126:129], v[150:153], v[190:193], v[126:129]
	v_mfma_f32_16x16x32_bf16 v[126:129], v[162:165], v[198:201], v[126:129]
	v_mfma_f32_16x16x32_bf16 v[118:121], v[166:169], v[190:193], v[118:121]
	v_mfma_f32_16x16x32_bf16 v[118:121], v[170:173], v[198:201], v[118:121]
	v_mfma_f32_16x16x32_bf16 v[110:113], v[150:153], v[194:197], v[110:113]
	v_mfma_f32_16x16x32_bf16 v[110:113], v[162:165], v[202:205], v[110:113]
	v_mfma_f32_16x16x32_bf16 v[102:105], v[166:169], v[194:197], v[102:105]
	v_mfma_f32_16x16x32_bf16 v[102:105], v[170:173], v[202:205], v[102:105]
	v_mfma_f32_16x16x32_bf16 v[94:97], v[150:153], v[206:209], v[94:97]
	v_mfma_f32_16x16x32_bf16 v[94:97], v[162:165], v[214:217], v[94:97]
	v_mfma_f32_16x16x32_bf16 v[86:89], v[166:169], v[206:209], v[86:89]
	v_mfma_f32_16x16x32_bf16 v[86:89], v[170:173], v[214:217], v[86:89]
	v_mfma_f32_16x16x32_bf16 v[78:81], v[150:153], v[210:213], v[78:81]
	v_mfma_f32_16x16x32_bf16 v[78:81], v[162:165], v[218:221], v[78:81]
	v_mfma_f32_16x16x32_bf16 v[70:73], v[166:169], v[210:213], v[70:73]
	v_mfma_f32_16x16x32_bf16 v[70:73], v[170:173], v[218:221], v[70:73]
	s_setprio 0
	s_setprio 1
	v_mfma_f32_16x16x32_bf16 v[122:125], v[174:177], v[190:193], v[122:125]
	v_mfma_f32_16x16x32_bf16 v[122:125], v[178:181], v[198:201], v[122:125]
	v_mfma_f32_16x16x32_bf16 v[114:117], v[182:185], v[190:193], v[114:117]
	v_mfma_f32_16x16x32_bf16 v[114:117], v[186:189], v[198:201], v[114:117]
	v_mfma_f32_16x16x32_bf16 v[106:109], v[174:177], v[194:197], v[106:109]
	v_mfma_f32_16x16x32_bf16 v[106:109], v[178:181], v[202:205], v[106:109]
	v_mfma_f32_16x16x32_bf16 v[98:101], v[182:185], v[194:197], v[98:101]
	v_mfma_f32_16x16x32_bf16 v[98:101], v[186:189], v[202:205], v[98:101]
	v_mfma_f32_16x16x32_bf16 v[90:93], v[174:177], v[206:209], v[90:93]
	v_mfma_f32_16x16x32_bf16 v[90:93], v[178:181], v[214:217], v[90:93]
	v_mfma_f32_16x16x32_bf16 v[82:85], v[182:185], v[206:209], v[82:85]
	v_mfma_f32_16x16x32_bf16 v[82:85], v[186:189], v[214:217], v[82:85]
	v_mfma_f32_16x16x32_bf16 v[74:77], v[174:177], v[210:213], v[74:77]
	v_mfma_f32_16x16x32_bf16 v[74:77], v[178:181], v[218:221], v[74:77]
	v_mfma_f32_16x16x32_bf16 v[66:69], v[182:185], v[210:213], v[66:69]
	v_mfma_f32_16x16x32_bf16 v[66:69], v[186:189], v[218:221], v[66:69]
	s_setprio 0
	s_barrier
	s_add_i32 s42, s44, s55
	s_add_i32 m0, s42, 0xffffff80
	ds_read_b128 v[190:193], v158 offset:49152
	ds_read_b128 v[194:197], v158 offset:51200
	ds_read_b128 v[198:201], v159 offset:49152
	ds_read_b128 v[202:205], v159 offset:51200
	ds_read_b128 v[206:209], v158 offset:53248
	ds_read_b128 v[210:213], v158 offset:55296
	ds_read_b128 v[214:217], v159 offset:53248
	ds_read_b128 v[218:221], v159 offset:55296
	global_load_lds_dwordx4 v130, s[58:59] offset:128
	s_add_i32 m0, s42, 0x1f80
	s_add_u32 s42, s58, 0x40080
	s_addc_u32 s43, s59, 0
	s_add_i32 s44, s45, s55
	global_load_lds_dwordx4 v138, s[58:59] offset:128
	s_mov_b32 m0, s44
	s_nop 0
	global_load_lds_dwordx4 v130, s[42:43]
	s_add_i32 m0, s44, 0x2000
	s_nop 0
	global_load_lds_dwordx4 v138, s[42:43]
	s_add_i32 m0, s69, 0xffffff80
	s_nop 0
	global_load_lds_dwordx4 v134, s[60:61] offset:128
	s_add_i32 m0, s70, 0xffffff80
	s_nop 0
	global_load_lds_dwordx4 v136, s[60:61] offset:128
	s_waitcnt vmcnt(8)
	s_waitcnt lgkmcnt(0)
	s_barrier
	s_setprio 1
	s_waitcnt lgkmcnt(0)
	v_mfma_f32_16x16x32_bf16 v[62:65], v[150:153], v[190:193], v[62:65]
	v_mfma_f32_16x16x32_bf16 v[62:65], v[162:165], v[198:201], v[62:65]
	v_mfma_f32_16x16x32_bf16 v[54:57], v[166:169], v[190:193], v[54:57]
	v_mfma_f32_16x16x32_bf16 v[54:57], v[170:173], v[198:201], v[54:57]
	v_mfma_f32_16x16x32_bf16 v[46:49], v[150:153], v[194:197], v[46:49]
	v_mfma_f32_16x16x32_bf16 v[46:49], v[162:165], v[202:205], v[46:49]
	v_mfma_f32_16x16x32_bf16 v[38:41], v[166:169], v[194:197], v[38:41]
	v_mfma_f32_16x16x32_bf16 v[38:41], v[170:173], v[202:205], v[38:41]
	v_mfma_f32_16x16x32_bf16 v[30:33], v[150:153], v[206:209], v[30:33]
	v_mfma_f32_16x16x32_bf16 v[30:33], v[162:165], v[214:217], v[30:33]
	v_mfma_f32_16x16x32_bf16 v[22:25], v[166:169], v[206:209], v[22:25]
	v_mfma_f32_16x16x32_bf16 v[22:25], v[170:173], v[214:217], v[22:25]
	v_mfma_f32_16x16x32_bf16 v[14:17], v[150:153], v[210:213], v[14:17]
	v_mfma_f32_16x16x32_bf16 v[14:17], v[162:165], v[218:221], v[14:17]
	v_mfma_f32_16x16x32_bf16 v[6:9], v[166:169], v[210:213], v[6:9]
	v_mfma_f32_16x16x32_bf16 v[6:9], v[170:173], v[218:221], v[6:9]
	s_setprio 0
	s_setprio 1
	v_mfma_f32_16x16x32_bf16 v[58:61], v[174:177], v[190:193], v[58:61]
	v_mfma_f32_16x16x32_bf16 v[58:61], v[178:181], v[198:201], v[58:61]
	v_mfma_f32_16x16x32_bf16 v[50:53], v[182:185], v[190:193], v[50:53]
	v_mfma_f32_16x16x32_bf16 v[50:53], v[186:189], v[198:201], v[50:53]
	v_mfma_f32_16x16x32_bf16 v[42:45], v[174:177], v[194:197], v[42:45]
	v_mfma_f32_16x16x32_bf16 v[42:45], v[178:181], v[202:205], v[42:45]
	v_mfma_f32_16x16x32_bf16 v[34:37], v[182:185], v[194:197], v[34:37]
	v_mfma_f32_16x16x32_bf16 v[34:37], v[186:189], v[202:205], v[34:37]
	v_mfma_f32_16x16x32_bf16 v[26:29], v[174:177], v[206:209], v[26:29]
	v_mfma_f32_16x16x32_bf16 v[26:29], v[178:181], v[214:217], v[26:29]
	v_mfma_f32_16x16x32_bf16 v[18:21], v[182:185], v[206:209], v[18:21]
	v_mfma_f32_16x16x32_bf16 v[18:21], v[186:189], v[214:217], v[18:21]
	v_mfma_f32_16x16x32_bf16 v[10:13], v[174:177], v[210:213], v[10:13]
	v_mfma_f32_16x16x32_bf16 v[10:13], v[178:181], v[218:221], v[10:13]
	v_mfma_f32_16x16x32_bf16 v[2:5], v[182:185], v[210:213], v[2:5]
	v_mfma_f32_16x16x32_bf16 v[2:5], v[186:189], v[218:221], v[2:5]
	s_setprio 0
	s_barrier
	s_add_i32 s86, s86, 2
	s_add_u32 s56, s56, 0x100
	s_addc_u32 s57, s57, 0
	s_add_u32 s84, s84, 0x100
	s_addc_u32 s85, s85, 0
	s_cmp_gt_u32 s86, 13
	s_cbranch_scc1 .LBB0_500

.Lpeel_0:
	s_mov_b32 s100, 0
	ds_read_b128 v[150:153], v245
	ds_read_b128 v[162:165], v246
	ds_read_b128 v[166:169], v245 offset:2048
	ds_read_b128 v[170:173], v246 offset:2048
	ds_read_b128 v[174:177], v245 offset:16384
	ds_read_b128 v[178:181], v246 offset:16384
	ds_read_b128 v[182:185], v245 offset:18432
	ds_read_b128 v[186:189], v246 offset:18432
	s_add_u32 s44, s56, 0xfffc0080
	s_addc_u32 s45, s57, -1
	s_and_b64 s[42:43], s[58:59], exec
	s_cselect_b32 s61, s13, s45
	s_cselect_b32 s60, s81, s44
	s_cselect_b32 s59, s11, s85
	s_cselect_b32 s58, s82, s84
	s_add_i32 m0, s62, 0xc000
	ds_read_b128 v[190:193], v158
	ds_read_b128 v[194:197], v158 offset:2048
	ds_read_b128 v[198:201], v159
	ds_read_b128 v[202:205], v159 offset:2048
	ds_read_b128 v[206:209], v158 offset:4096
	ds_read_b128 v[210:213], v158 offset:6144
	ds_read_b128 v[214:217], v159 offset:4096
	ds_read_b128 v[218:221], v159 offset:6144
	global_load_lds_dwordx4 v140, s[56:57]
	s_add_i32 m0, s62, 0xe000
	s_nop 0
	global_load_lds_dwordx4 v142, s[56:57]
	s_waitcnt vmcnt(8)
	s_waitcnt lgkmcnt(0)
	s_barrier
	s_setprio 1
	s_waitcnt lgkmcnt(0)
	v_mfma_f32_16x16x32_bf16 v[126:129], v[150:153], v[190:193], 0
	v_mfma_f32_16x16x32_bf16 v[126:129], v[162:165], v[198:201], v[126:129]
	v_mfma_f32_16x16x32_bf16 v[118:121], v[166:169], v[190:193], 0
	v_mfma_f32_16x16x32_bf16 v[118:121], v[170:173], v[198:201], v[118:121]
	v_mfma_f32_16x16x32_bf16 v[110:113], v[150:153], v[194:197], 0
	v_mfma_f32_16x16x32_bf16 v[110:113], v[162:165], v[202:205], v[110:113]
	v_mfma_f32_16x16x32_bf16 v[102:105], v[166:169], v[194:197], 0
	v_mfma_f32_16x16x32_bf16 v[102:105], v[170:173], v[202:205], v[102:105]
	v_mfma_f32_16x16x32_bf16 v[94:97], v[150:153], v[206:209], 0
	v_mfma_f32_16x16x32_bf16 v[94:97], v[162:165], v[214:217], v[94:97]
	v_mfma_f32_16x16x32_bf16 v[86:89], v[166:169], v[206:209], 0
	v_mfma_f32_16x16x32_bf16 v[86:89], v[170:173], v[214:217], v[86:89]
	v_mfma_f32_16x16x32_bf16 v[78:81], v[150:153], v[210:213], 0
	v_mfma_f32_16x16x32_bf16 v[78:81], v[162:165], v[218:221], v[78:81]
	v_mfma_f32_16x16x32_bf16 v[70:73], v[166:169], v[210:213], 0
	v_mfma_f32_16x16x32_bf16 v[70:73], v[170:173], v[218:221], v[70:73]
	s_setprio 0
	s_setprio 1
	v_mfma_f32_16x16x32_bf16 v[122:125], v[174:177], v[190:193], 0
	v_mfma_f32_16x16x32_bf16 v[122:125], v[178:181], v[198:201], v[122:125]
	v_mfma_f32_16x16x32_bf16 v[114:117], v[182:185], v[190:193], 0
	v_mfma_f32_16x16x32_bf16 v[114:117], v[186:189], v[198:201], v[114:117]
	v_mfma_f32_16x16x32_bf16 v[106:109], v[174:177], v[194:197], 0
	v_mfma_f32_16x16x32_bf16 v[106:109], v[178:181], v[202:205], v[106:109]
	v_mfma_f32_16x16x32_bf16 v[98:101], v[182:185], v[194:197], 0
	v_mfma_f32_16x16x32_bf16 v[98:101], v[186:189], v[202:205], v[98:101]
	v_mfma_f32_16x16x32_bf16 v[90:93], v[174:177], v[206:209], 0
	v_mfma_f32_16x16x32_bf16 v[90:93], v[178:181], v[214:217], v[90:93]
	v_mfma_f32_16x16x32_bf16 v[82:85], v[182:185], v[206:209], 0
	v_mfma_f32_16x16x32_bf16 v[82:85], v[186:189], v[214:217], v[82:85]
	v_mfma_f32_16x16x32_bf16 v[74:77], v[174:177], v[210:213], 0
	v_mfma_f32_16x16x32_bf16 v[74:77], v[178:181], v[218:221], v[74:77]
	v_mfma_f32_16x16x32_bf16 v[66:69], v[182:185], v[210:213], 0
	v_mfma_f32_16x16x32_bf16 v[66:69], v[186:189], v[218:221], v[66:69]
	s_setprio 0
	s_barrier
	s_add_i32 s42, s72, s55
	s_mov_b32 m0, s42
	ds_read_b128 v[190:193], v158 offset:16384
	ds_read_b128 v[194:197], v158 offset:18432
	ds_read_b128 v[198:201], v159 offset:16384
	ds_read_b128 v[202:205], v159 offset:18432
	ds_read_b128 v[206:209], v158 offset:20480
	ds_read_b128 v[210:213], v158 offset:22528
	ds_read_b128 v[214:217], v159 offset:20480
	ds_read_b128 v[218:221], v159 offset:22528
	global_load_lds_dwordx4 v130, s[58:59]
	s_add_i32 m0, s42, 0x2000
	s_add_u32 s42, s58, 0x40000
	s_addc_u32 s43, s59, 0
	s_add_i32 s44, s74, s55
	global_load_lds_dwordx4 v138, s[58:59]
	s_mov_b32 m0, s44
	s_nop 0
	global_load_lds_dwordx4 v130, s[42:43]
	s_add_i32 m0, s44, 0x2000
	s_nop 0
	global_load_lds_dwordx4 v138, s[42:43]
	s_mov_b32 m0, s62
	s_nop 0
	global_load_lds_dwordx4 v134, s[60:61]
	s_mov_b32 m0, s63
	s_nop 0
	global_load_lds_dwordx4 v136, s[60:61]
	s_waitcnt vmcnt(8)
	s_waitcnt lgkmcnt(0)
	s_barrier
	s_setprio 1
	s_waitcnt lgkmcnt(0)
	v_mfma_f32_16x16x32_bf16 v[62:65], v[150:153], v[190:193], 0
	v_mfma_f32_16x16x32_bf16 v[62:65], v[162:165], v[198:201], v[62:65]
	v_mfma_f32_16x16x32_bf16 v[54:57], v[166:169], v[190:193], 0
	v_mfma_f32_16x16x32_bf16 v[54:57], v[170:173], v[198:201], v[54:57]
	v_mfma_f32_16x16x32_bf16 v[46:49], v[150:153], v[194:197], 0
	v_mfma_f32_16x16x32_bf16 v[46:49], v[162:165], v[202:205], v[46:49]
	v_mfma_f32_16x16x32_bf16 v[38:41], v[166:169], v[194:197], 0
	v_mfma_f32_16x16x32_bf16 v[38:41], v[170:173], v[202:205], v[38:41]
	v_mfma_f32_16x16x32_bf16 v[30:33], v[150:153], v[206:209], 0
	v_mfma_f32_16x16x32_bf16 v[30:33], v[162:165], v[214:217], v[30:33]
	v_mfma_f32_16x16x32_bf16 v[22:25], v[166:169], v[206:209], 0
	v_mfma_f32_16x16x32_bf16 v[22:25], v[170:173], v[214:217], v[22:25]
	v_mfma_f32_16x16x32_bf16 v[14:17], v[150:153], v[210:213], 0
	v_mfma_f32_16x16x32_bf16 v[14:17], v[162:165], v[218:221], v[14:17]
	v_mfma_f32_16x16x32_bf16 v[6:9], v[166:169], v[210:213], 0
	v_mfma_f32_16x16x32_bf16 v[6:9], v[170:173], v[218:221], v[6:9]
	s_setprio 0
	s_setprio 1
	v_mfma_f32_16x16x32_bf16 v[58:61], v[174:177], v[190:193], 0
	v_mfma_f32_16x16x32_bf16 v[58:61], v[178:181], v[198:201], v[58:61]
	v_mfma_f32_16x16x32_bf16 v[50:53], v[182:185], v[190:193], 0
	v_mfma_f32_16x16x32_bf16 v[50:53], v[186:189], v[198:201], v[50:53]
	v_mfma_f32_16x16x32_bf16 v[42:45], v[174:177], v[194:197], 0
	v_mfma_f32_16x16x32_bf16 v[42:45], v[178:181], v[202:205], v[42:45]
	v_mfma_f32_16x16x32_bf16 v[34:37], v[182:185], v[194:197], 0
	v_mfma_f32_16x16x32_bf16 v[34:37], v[186:189], v[202:205], v[34:37]
	v_mfma_f32_16x16x32_bf16 v[26:29], v[174:177], v[206:209], 0
	v_mfma_f32_16x16x32_bf16 v[26:29], v[178:181], v[214:217], v[26:29]
	v_mfma_f32_16x16x32_bf16 v[18:21], v[182:185], v[206:209], 0
	v_mfma_f32_16x16x32_bf16 v[18:21], v[186:189], v[214:217], v[18:21]
	v_mfma_f32_16x16x32_bf16 v[10:13], v[174:177], v[210:213], 0
	v_mfma_f32_16x16x32_bf16 v[10:13], v[178:181], v[218:221], v[10:13]
	v_mfma_f32_16x16x32_bf16 v[2:5], v[182:185], v[210:213], 0
	v_mfma_f32_16x16x32_bf16 v[2:5], v[186:189], v[218:221], v[2:5]
	s_setprio 0
	s_barrier
	s_add_i32 s44, 0, 0x18000
	ds_read_b128 v[150:153], v245 offset:32768
	ds_read_b128 v[162:165], v246 offset:32768
	s_add_i32 s45, 0, 0x1c000
	ds_read_b128 v[166:169], v245 offset:34816
	ds_read_b128 v[170:173], v246 offset:34816
	ds_read_b128 v[174:177], v245 offset:49152
	ds_read_b128 v[178:181], v246 offset:49152
	ds_read_b128 v[182:185], v245 offset:51200
	ds_read_b128 v[186:189], v246 offset:51200
	s_add_u32 s42, s60, 0x40000
	s_addc_u32 s43, s61, 0
	s_mov_b32 m0, s64
	ds_read_b128 v[190:193], v158 offset:32768
	ds_read_b128 v[194:197], v158 offset:34816
	ds_read_b128 v[198:201], v159 offset:32768
	ds_read_b128 v[202:205], v159 offset:34816
	ds_read_b128 v[206:209], v158 offset:36864
	ds_read_b128 v[210:213], v158 offset:38912
	ds_read_b128 v[214:217], v159 offset:36864
	ds_read_b128 v[218:221], v159 offset:38912
	global_load_lds_dwordx4 v134, s[42:43]
	s_mov_b32 m0, s65
	s_nop 0
	global_load_lds_dwordx4 v136, s[42:43]
	s_waitcnt vmcnt(8)
	s_waitcnt lgkmcnt(0)
	s_barrier
	s_setprio 1
	s_waitcnt lgkmcnt(0)
	v_mfma_f32_16x16x32_bf16 v[126:129], v[150:153], v[190:193], v[126:129]
	v_mfma_f32_16x16x32_bf16 v[126:129], v[162:165], v[198:201], v[126:129]
	v_mfma_f32_16x16x32_bf16 v[118:121], v[166:169], v[190:193], v[118:121]
	v_mfma_f32_16x16x32_bf16 v[118:121], v[170:173], v[198:201], v[118:121]
	v_mfma_f32_16x16x32_bf16 v[110:113], v[150:153], v[194:197], v[110:113]
	v_mfma_f32_16x16x32_bf16 v[110:113], v[162:165], v[202:205], v[110:113]
	v_mfma_f32_16x16x32_bf16 v[102:105], v[166:169], v[194:197], v[102:105]
	v_mfma_f32_16x16x32_bf16 v[102:105], v[170:173], v[202:205], v[102:105]
	v_mfma_f32_16x16x32_bf16 v[94:97], v[150:153], v[206:209], v[94:97]
	v_mfma_f32_16x16x32_bf16 v[94:97], v[162:165], v[214:217], v[94:97]
	v_mfma_f32_16x16x32_bf16 v[86:89], v[166:169], v[206:209], v[86:89]
	v_mfma_f32_16x16x32_bf16 v[86:89], v[170:173], v[214:217], v[86:89]
	v_mfma_f32_16x16x32_bf16 v[78:81], v[150:153], v[210:213], v[78:81]
	v_mfma_f32_16x16x32_bf16 v[78:81], v[162:165], v[218:221], v[78:81]
	v_mfma_f32_16x16x32_bf16 v[70:73], v[166:169], v[210:213], v[70:73]
	v_mfma_f32_16x16x32_bf16 v[70:73], v[170:173], v[218:221], v[70:73]
	s_setprio 0
	s_setprio 1
	v_mfma_f32_16x16x32_bf16 v[122:125], v[174:177], v[190:193], v[122:125]
	v_mfma_f32_16x16x32_bf16 v[122:125], v[178:181], v[198:201], v[122:125]
	v_mfma_f32_16x16x32_bf16 v[114:117], v[182:185], v[190:193], v[114:117]
	v_mfma_f32_16x16x32_bf16 v[114:117], v[186:189], v[198:201], v[114:117]
	v_mfma_f32_16x16x32_bf16 v[106:109], v[174:177], v[194:197], v[106:109]
	v_mfma_f32_16x16x32_bf16 v[106:109], v[178:181], v[202:205], v[106:109]
	v_mfma_f32_16x16x32_bf16 v[98:101], v[182:185], v[194:197], v[98:101]
	v_mfma_f32_16x16x32_bf16 v[98:101], v[186:189], v[202:205], v[98:101]
	v_mfma_f32_16x16x32_bf16 v[90:93], v[174:177], v[206:209], v[90:93]
	v_mfma_f32_16x16x32_bf16 v[90:93], v[178:181], v[214:217], v[90:93]
	v_mfma_f32_16x16x32_bf16 v[82:85], v[182:185], v[206:209], v[82:85]
	v_mfma_f32_16x16x32_bf16 v[82:85], v[186:189], v[214:217], v[82:85]
	v_mfma_f32_16x16x32_bf16 v[74:77], v[174:177], v[210:213], v[74:77]
	v_mfma_f32_16x16x32_bf16 v[74:77], v[178:181], v[218:221], v[74:77]
	v_mfma_f32_16x16x32_bf16 v[66:69], v[182:185], v[210:213], v[66:69]
	v_mfma_f32_16x16x32_bf16 v[66:69], v[186:189], v[218:221], v[66:69]
	s_setprio 0
	s_barrier
	s_add_i32 s42, s44, s55
	s_add_i32 m0, s42, 0xffffff80
	ds_read_b128 v[190:193], v158 offset:49152
	ds_read_b128 v[194:197], v158 offset:51200
	ds_read_b128 v[198:201], v159 offset:49152
	ds_read_b128 v[202:205], v159 offset:51200
	ds_read_b128 v[206:209], v158 offset:53248
	ds_read_b128 v[210:213], v158 offset:55296
	ds_read_b128 v[214:217], v159 offset:53248
	ds_read_b128 v[218:221], v159 offset:55296
	global_load_lds_dwordx4 v130, s[58:59] offset:128
	s_add_i32 m0, s42, 0x1f80
	s_add_u32 s42, s58, 0x40080
	s_addc_u32 s43, s59, 0
	s_add_i32 s44, s45, s55
	global_load_lds_dwordx4 v138, s[58:59] offset:128
	s_mov_b32 m0, s44
	s_nop 0
	global_load_lds_dwordx4 v130, s[42:43]
	s_add_i32 m0, s44, 0x2000
	s_nop 0
	global_load_lds_dwordx4 v138, s[42:43]
	s_add_i32 m0, s69, 0xffffff80
	s_nop 0
	global_load_lds_dwordx4 v134, s[60:61] offset:128
	s_add_i32 m0, s70, 0xffffff80
	s_nop 0
	global_load_lds_dwordx4 v136, s[60:61] offset:128
	s_waitcnt vmcnt(8)
	s_waitcnt lgkmcnt(0)
	s_barrier
	s_setprio 1
	s_waitcnt lgkmcnt(0)
	v_mfma_f32_16x16x32_bf16 v[62:65], v[150:153], v[190:193], v[62:65]
	v_mfma_f32_16x16x32_bf16 v[62:65], v[162:165], v[198:201], v[62:65]
	v_mfma_f32_16x16x32_bf16 v[54:57], v[166:169], v[190:193], v[54:57]
	v_mfma_f32_16x16x32_bf16 v[54:57], v[170:173], v[198:201], v[54:57]
	v_mfma_f32_16x16x32_bf16 v[46:49], v[150:153], v[194:197], v[46:49]
	v_mfma_f32_16x16x32_bf16 v[46:49], v[162:165], v[202:205], v[46:49]
	v_mfma_f32_16x16x32_bf16 v[38:41], v[166:169], v[194:197], v[38:41]
	v_mfma_f32_16x16x32_bf16 v[38:41], v[170:173], v[202:205], v[38:41]
	v_mfma_f32_16x16x32_bf16 v[30:33], v[150:153], v[206:209], v[30:33]
	v_mfma_f32_16x16x32_bf16 v[30:33], v[162:165], v[214:217], v[30:33]
	v_mfma_f32_16x16x32_bf16 v[22:25], v[166:169], v[206:209], v[22:25]
	v_mfma_f32_16x16x32_bf16 v[22:25], v[170:173], v[214:217], v[22:25]
	v_mfma_f32_16x16x32_bf16 v[14:17], v[150:153], v[210:213], v[14:17]
	v_mfma_f32_16x16x32_bf16 v[14:17], v[162:165], v[218:221], v[14:17]
	v_mfma_f32_16x16x32_bf16 v[6:9], v[166:169], v[210:213], v[6:9]
	v_mfma_f32_16x16x32_bf16 v[6:9], v[170:173], v[218:221], v[6:9]
	s_setprio 0
	s_setprio 1
	v_mfma_f32_16x16x32_bf16 v[58:61], v[174:177], v[190:193], v[58:61]
	v_mfma_f32_16x16x32_bf16 v[58:61], v[178:181], v[198:201], v[58:61]
	v_mfma_f32_16x16x32_bf16 v[50:53], v[182:185], v[190:193], v[50:53]
	v_mfma_f32_16x16x32_bf16 v[50:53], v[186:189], v[198:201], v[50:53]
	v_mfma_f32_16x16x32_bf16 v[42:45], v[174:177], v[194:197], v[42:45]
	v_mfma_f32_16x16x32_bf16 v[42:45], v[178:181], v[202:205], v[42:45]
	v_mfma_f32_16x16x32_bf16 v[34:37], v[182:185], v[194:197], v[34:37]
	v_mfma_f32_16x16x32_bf16 v[34:37], v[186:189], v[202:205], v[34:37]
	v_mfma_f32_16x16x32_bf16 v[26:29], v[174:177], v[206:209], v[26:29]
	v_mfma_f32_16x16x32_bf16 v[26:29], v[178:181], v[214:217], v[26:29]
	v_mfma_f32_16x16x32_bf16 v[18:21], v[182:185], v[206:209], v[18:21]
	v_mfma_f32_16x16x32_bf16 v[18:21], v[186:189], v[214:217], v[18:21]
	v_mfma_f32_16x16x32_bf16 v[10:13], v[174:177], v[210:213], v[10:13]
	v_mfma_f32_16x16x32_bf16 v[10:13], v[178:181], v[218:221], v[10:13]
	v_mfma_f32_16x16x32_bf16 v[2:5], v[182:185], v[210:213], v[2:5]
	v_mfma_f32_16x16x32_bf16 v[2:5], v[186:189], v[218:221], v[2:5]
	s_setprio 0
	s_barrier
	s_add_i32 s86, s86, 2
	s_add_u32 s56, s56, 0x100
	s_addc_u32 s57, s57, 0
	s_add_u32 s84, s84, 0x100
	s_addc_u32 s85, s85, 0
	s_cmp_gt_u32 s86, 13
	s_cbranch_scc1 .LBB0_500
	s_branch .LBB0_497

.LBB0_589:
	s_cmp_lg_u32 s100, 0
	s_cbranch_scc1 .Lpeel_1
	ds_read_b128 v[90:93], v212
	ds_read_b128 v[102:105], v213
	ds_read_b128 v[114:117], v214
	ds_read_b128 v[126:129], v215
	ds_read_b128 v[138:141], v216
	ds_read_b128 v[150:153], v217
	ds_read_b128 v[154:157], v218
	ds_read_b128 v[158:161], v219
	s_add_u32 s45, s40, 0xfff50080
	s_addc_u32 s46, s41, -1
	s_cmp_eq_u32 s44, 40
	s_cselect_b32 s55, s1, s46
	s_cselect_b32 s54, s0, s45
	s_cselect_b32 s53, s15, s43
	s_cselect_b32 s52, s14, s42
	s_add_i32 m0, s56, 0xc000
	ds_read_b128 v[162:165], v220
	ds_read_b128 v[166:169], v220 offset:2048
	ds_read_b128 v[170:173], v221
	ds_read_b128 v[174:177], v221 offset:2048
	ds_read_b128 v[178:181], v220 offset:4096
	ds_read_b128 v[182:185], v220 offset:6144
	ds_read_b128 v[204:207], v221 offset:4096
	ds_read_b128 v[226:229], v221 offset:6144
	global_load_lds_dwordx4 v196, s[40:41]
	s_add_i32 m0, s56, 0xe000
	s_nop 0
	global_load_lds_dwordx4 v198, s[40:41]
	s_waitcnt vmcnt(8)
	s_waitcnt lgkmcnt(0)
	s_barrier
	s_setprio 1
	s_waitcnt lgkmcnt(0)
	v_mfma_f32_16x16x32_bf16 v[146:149], v[90:93], v[162:165], v[146:149]
	v_mfma_f32_16x16x32_bf16 v[146:149], v[102:105], v[170:173], v[146:149]
	v_mfma_f32_16x16x32_bf16 v[142:145], v[114:117], v[162:165], v[142:145]
	v_mfma_f32_16x16x32_bf16 v[142:145], v[126:129], v[170:173], v[142:145]
	v_mfma_f32_16x16x32_bf16 v[122:125], v[90:93], v[166:169], v[122:125]
	v_mfma_f32_16x16x32_bf16 v[122:125], v[102:105], v[174:177], v[122:125]
	v_mfma_f32_16x16x32_bf16 v[118:121], v[114:117], v[166:169], v[118:121]
	v_mfma_f32_16x16x32_bf16 v[118:121], v[126:129], v[174:177], v[118:121]
	v_mfma_f32_16x16x32_bf16 v[98:101], v[90:93], v[178:181], v[98:101]
	v_mfma_f32_16x16x32_bf16 v[98:101], v[102:105], v[204:207], v[98:101]
	v_mfma_f32_16x16x32_bf16 v[94:97], v[114:117], v[178:181], v[94:97]
	v_mfma_f32_16x16x32_bf16 v[94:97], v[126:129], v[204:207], v[94:97]
	v_mfma_f32_16x16x32_bf16 v[78:81], v[90:93], v[182:185], v[78:81]
	v_mfma_f32_16x16x32_bf16 v[78:81], v[102:105], v[226:229], v[78:81]
	v_mfma_f32_16x16x32_bf16 v[74:77], v[114:117], v[182:185], v[74:77]
	v_mfma_f32_16x16x32_bf16 v[74:77], v[126:129], v[226:229], v[74:77]
	s_setprio 0
	s_setprio 1
	v_mfma_f32_16x16x32_bf16 v[134:137], v[138:141], v[162:165], v[134:137]
	v_mfma_f32_16x16x32_bf16 v[134:137], v[150:153], v[170:173], v[134:137]
	v_mfma_f32_16x16x32_bf16 v[130:133], v[154:157], v[162:165], v[130:133]
	v_mfma_f32_16x16x32_bf16 v[130:133], v[158:161], v[170:173], v[130:133]
	v_mfma_f32_16x16x32_bf16 v[110:113], v[138:141], v[166:169], v[110:113]
	v_mfma_f32_16x16x32_bf16 v[110:113], v[150:153], v[174:177], v[110:113]
	v_mfma_f32_16x16x32_bf16 v[106:109], v[154:157], v[166:169], v[106:109]
	v_mfma_f32_16x16x32_bf16 v[106:109], v[158:161], v[174:177], v[106:109]
	v_mfma_f32_16x16x32_bf16 v[86:89], v[138:141], v[178:181], v[86:89]
	v_mfma_f32_16x16x32_bf16 v[86:89], v[150:153], v[204:207], v[86:89]
	v_mfma_f32_16x16x32_bf16 v[82:85], v[154:157], v[178:181], v[82:85]
	v_mfma_f32_16x16x32_bf16 v[82:85], v[158:161], v[204:207], v[82:85]
	v_mfma_f32_16x16x32_bf16 v[70:73], v[138:141], v[182:185], v[70:73]
	v_mfma_f32_16x16x32_bf16 v[70:73], v[150:153], v[226:229], v[70:73]
	v_mfma_f32_16x16x32_bf16 v[66:69], v[154:157], v[182:185], v[66:69]
	v_mfma_f32_16x16x32_bf16 v[66:69], v[158:161], v[226:229], v[66:69]
	s_setprio 0
	s_barrier
	s_add_i32 s45, s68, s39
	s_mov_b32 m0, s45
	ds_read_b128 v[162:165], v220 offset:16384
	ds_read_b128 v[166:169], v220 offset:18432
	ds_read_b128 v[170:173], v221 offset:16384
	ds_read_b128 v[174:177], v221 offset:18432
	ds_read_b128 v[178:181], v220 offset:20480
	ds_read_b128 v[182:185], v220 offset:22528
	ds_read_b128 v[204:207], v221 offset:20480
	ds_read_b128 v[226:229], v221 offset:22528
	global_load_lds_dwordx4 v188, s[52:53]
	s_add_i32 m0, s45, 0x2000
	s_add_u32 s46, s52, 0xb0000
	s_addc_u32 s47, s53, 0
	s_add_i32 s45, s69, s39
	global_load_lds_dwordx4 v192, s[52:53]
	s_mov_b32 m0, s45
	s_nop 0
	global_load_lds_dwordx4 v188, s[46:47]
	s_add_i32 m0, s45, 0x2000
	s_nop 0
	global_load_lds_dwordx4 v192, s[46:47]
	s_mov_b32 m0, s56
	s_nop 0
	global_load_lds_dwordx4 v186, s[54:55]
	s_mov_b32 m0, s57
	s_nop 0
	global_load_lds_dwordx4 v190, s[54:55]
	s_waitcnt vmcnt(8)
	s_waitcnt lgkmcnt(0)
	s_barrier
	s_setprio 1
	s_waitcnt lgkmcnt(0)
	v_mfma_f32_16x16x32_bf16 v[62:65], v[90:93], v[162:165], v[62:65]
	v_mfma_f32_16x16x32_bf16 v[62:65], v[102:105], v[170:173], v[62:65]
	v_mfma_f32_16x16x32_bf16 v[58:61], v[114:117], v[162:165], v[58:61]
	v_mfma_f32_16x16x32_bf16 v[58:61], v[126:129], v[170:173], v[58:61]
	v_mfma_f32_16x16x32_bf16 v[46:49], v[90:93], v[166:169], v[46:49]
	v_mfma_f32_16x16x32_bf16 v[46:49], v[102:105], v[174:177], v[46:49]
	v_mfma_f32_16x16x32_bf16 v[42:45], v[114:117], v[166:169], v[42:45]
	v_mfma_f32_16x16x32_bf16 v[42:45], v[126:129], v[174:177], v[42:45]
	v_mfma_f32_16x16x32_bf16 v[30:33], v[90:93], v[178:181], v[30:33]
	v_mfma_f32_16x16x32_bf16 v[30:33], v[102:105], v[204:207], v[30:33]
	v_mfma_f32_16x16x32_bf16 v[26:29], v[114:117], v[178:181], v[26:29]
	v_mfma_f32_16x16x32_bf16 v[26:29], v[126:129], v[204:207], v[26:29]
	v_mfma_f32_16x16x32_bf16 v[14:17], v[90:93], v[182:185], v[14:17]
	v_mfma_f32_16x16x32_bf16 v[14:17], v[102:105], v[226:229], v[14:17]
	v_mfma_f32_16x16x32_bf16 v[10:13], v[114:117], v[182:185], v[10:13]
	v_mfma_f32_16x16x32_bf16 v[10:13], v[126:129], v[226:229], v[10:13]
	s_setprio 0
	s_setprio 1
	v_mfma_f32_16x16x32_bf16 v[54:57], v[138:141], v[162:165], v[54:57]
	v_mfma_f32_16x16x32_bf16 v[54:57], v[150:153], v[170:173], v[54:57]
	v_mfma_f32_16x16x32_bf16 v[50:53], v[154:157], v[162:165], v[50:53]
	v_mfma_f32_16x16x32_bf16 v[50:53], v[158:161], v[170:173], v[50:53]
	v_mfma_f32_16x16x32_bf16 v[38:41], v[138:141], v[166:169], v[38:41]
	v_mfma_f32_16x16x32_bf16 v[38:41], v[150:153], v[174:177], v[38:41]
	v_mfma_f32_16x16x32_bf16 v[34:37], v[154:157], v[166:169], v[34:37]
	v_mfma_f32_16x16x32_bf16 v[34:37], v[158:161], v[174:177], v[34:37]
	v_mfma_f32_16x16x32_bf16 v[22:25], v[138:141], v[178:181], v[22:25]
	v_mfma_f32_16x16x32_bf16 v[22:25], v[150:153], v[204:207], v[22:25]
	v_mfma_f32_16x16x32_bf16 v[18:21], v[154:157], v[178:181], v[18:21]
	v_mfma_f32_16x16x32_bf16 v[18:21], v[158:161], v[204:207], v[18:21]
	v_mfma_f32_16x16x32_bf16 v[6:9], v[138:141], v[182:185], v[6:9]
	v_mfma_f32_16x16x32_bf16 v[6:9], v[150:153], v[226:229], v[6:9]
	v_mfma_f32_16x16x32_bf16 v[2:5], v[154:157], v[182:185], v[2:5]
	v_mfma_f32_16x16x32_bf16 v[2:5], v[158:161], v[226:229], v[2:5]
	s_setprio 0
	s_barrier
	s_add_i32 s45, 0, 0x18000
	s_add_i32 s48, 0, 0x1c000
	ds_read_b128 v[90:93], v245 offset:32768
	ds_read_b128 v[102:105], v246 offset:32768
	ds_read_b128 v[114:117], v222
	ds_read_b128 v[126:129], v223
	ds_read_b128 v[138:141], v245 offset:49152
	ds_read_b128 v[150:153], v246 offset:49152
	ds_read_b128 v[154:157], v224
	ds_read_b128 v[158:161], v225
	s_add_u32 s46, s54, 0xb0000
	s_addc_u32 s47, s55, 0
	s_mov_b32 m0, s58
	ds_read_b128 v[162:165], v220 offset:32768
	ds_read_b128 v[166:169], v220 offset:34816
	ds_read_b128 v[170:173], v221 offset:32768
	ds_read_b128 v[174:177], v221 offset:34816
	ds_read_b128 v[178:181], v220 offset:36864
	ds_read_b128 v[182:185], v220 offset:38912
	ds_read_b128 v[204:207], v221 offset:36864
	ds_read_b128 v[226:229], v221 offset:38912
	global_load_lds_dwordx4 v186, s[46:47]
	s_mov_b32 m0, s59
	s_nop 0
	global_load_lds_dwordx4 v190, s[46:47]
	s_waitcnt vmcnt(8)
	s_waitcnt lgkmcnt(0)
	s_barrier
	s_setprio 1
	s_waitcnt lgkmcnt(0)
	v_mfma_f32_16x16x32_bf16 v[146:149], v[90:93], v[162:165], v[146:149]
	v_mfma_f32_16x16x32_bf16 v[146:149], v[102:105], v[170:173], v[146:149]
	v_mfma_f32_16x16x32_bf16 v[142:145], v[114:117], v[162:165], v[142:145]
	v_mfma_f32_16x16x32_bf16 v[142:145], v[126:129], v[170:173], v[142:145]
	v_mfma_f32_16x16x32_bf16 v[122:125], v[90:93], v[166:169], v[122:125]
	v_mfma_f32_16x16x32_bf16 v[122:125], v[102:105], v[174:177], v[122:125]
	v_mfma_f32_16x16x32_bf16 v[118:121], v[114:117], v[166:169], v[118:121]
	v_mfma_f32_16x16x32_bf16 v[118:121], v[126:129], v[174:177], v[118:121]
	v_mfma_f32_16x16x32_bf16 v[98:101], v[90:93], v[178:181], v[98:101]
	v_mfma_f32_16x16x32_bf16 v[98:101], v[102:105], v[204:207], v[98:101]
	v_mfma_f32_16x16x32_bf16 v[94:97], v[114:117], v[178:181], v[94:97]
	v_mfma_f32_16x16x32_bf16 v[94:97], v[126:129], v[204:207], v[94:97]
	v_mfma_f32_16x16x32_bf16 v[78:81], v[90:93], v[182:185], v[78:81]
	v_mfma_f32_16x16x32_bf16 v[78:81], v[102:105], v[226:229], v[78:81]
	v_mfma_f32_16x16x32_bf16 v[74:77], v[114:117], v[182:185], v[74:77]
	v_mfma_f32_16x16x32_bf16 v[74:77], v[126:129], v[226:229], v[74:77]
	s_setprio 0
	s_setprio 1
	v_mfma_f32_16x16x32_bf16 v[134:137], v[138:141], v[162:165], v[134:137]
	v_mfma_f32_16x16x32_bf16 v[134:137], v[150:153], v[170:173], v[134:137]
	v_mfma_f32_16x16x32_bf16 v[130:133], v[154:157], v[162:165], v[130:133]
	v_mfma_f32_16x16x32_bf16 v[130:133], v[158:161], v[170:173], v[130:133]
	v_mfma_f32_16x16x32_bf16 v[110:113], v[138:141], v[166:169], v[110:113]
	v_mfma_f32_16x16x32_bf16 v[110:113], v[150:153], v[174:177], v[110:113]
	v_mfma_f32_16x16x32_bf16 v[106:109], v[154:157], v[166:169], v[106:109]
	v_mfma_f32_16x16x32_bf16 v[106:109], v[158:161], v[174:177], v[106:109]
	v_mfma_f32_16x16x32_bf16 v[86:89], v[138:141], v[178:181], v[86:89]
	v_mfma_f32_16x16x32_bf16 v[86:89], v[150:153], v[204:207], v[86:89]
	v_mfma_f32_16x16x32_bf16 v[82:85], v[154:157], v[178:181], v[82:85]
	v_mfma_f32_16x16x32_bf16 v[82:85], v[158:161], v[204:207], v[82:85]
	v_mfma_f32_16x16x32_bf16 v[70:73], v[138:141], v[182:185], v[70:73]
	v_mfma_f32_16x16x32_bf16 v[70:73], v[150:153], v[226:229], v[70:73]
	v_mfma_f32_16x16x32_bf16 v[66:69], v[154:157], v[182:185], v[66:69]
	v_mfma_f32_16x16x32_bf16 v[66:69], v[158:161], v[226:229], v[66:69]
	s_setprio 0
	s_barrier
	s_add_i32 s45, s45, s39
	s_add_i32 m0, s45, 0xffffff80
	ds_read_b128 v[162:165], v220 offset:49152
	ds_read_b128 v[166:169], v220 offset:51200
	ds_read_b128 v[170:173], v221 offset:49152
	ds_read_b128 v[174:177], v221 offset:51200
	ds_read_b128 v[178:181], v220 offset:53248
	ds_read_b128 v[182:185], v220 offset:55296
	ds_read_b128 v[204:207], v221 offset:53248
	ds_read_b128 v[226:229], v221 offset:55296
	global_load_lds_dwordx4 v188, s[52:53] offset:128
	s_add_i32 m0, s45, 0x1f80
	s_add_u32 s46, s52, 0xb0080
	s_addc_u32 s47, s53, 0
	s_add_i32 s45, s48, s39
	global_load_lds_dwordx4 v192, s[52:53] offset:128
	s_mov_b32 m0, s45
	s_nop 0
	global_load_lds_dwordx4 v188, s[46:47]
	s_add_i32 m0, s45, 0x2000
	s_nop 0
	global_load_lds_dwordx4 v192, s[46:47]
	s_add_i32 m0, s63, 0xffffff80
	s_nop 0
	global_load_lds_dwordx4 v186, s[54:55] offset:128
	s_add_i32 m0, s64, 0xffffff80
	s_nop 0
	global_load_lds_dwordx4 v190, s[54:55] offset:128
	s_waitcnt vmcnt(8)
	s_waitcnt lgkmcnt(0)
	s_barrier
	s_setprio 1
	s_waitcnt lgkmcnt(0)
	v_mfma_f32_16x16x32_bf16 v[62:65], v[90:93], v[162:165], v[62:65]
	v_mfma_f32_16x16x32_bf16 v[62:65], v[102:105], v[170:173], v[62:65]
	v_mfma_f32_16x16x32_bf16 v[58:61], v[114:117], v[162:165], v[58:61]
	v_mfma_f32_16x16x32_bf16 v[58:61], v[126:129], v[170:173], v[58:61]
	v_mfma_f32_16x16x32_bf16 v[46:49], v[90:93], v[166:169], v[46:49]
	v_mfma_f32_16x16x32_bf16 v[46:49], v[102:105], v[174:177], v[46:49]
	v_mfma_f32_16x16x32_bf16 v[42:45], v[114:117], v[166:169], v[42:45]
	v_mfma_f32_16x16x32_bf16 v[42:45], v[126:129], v[174:177], v[42:45]
	v_mfma_f32_16x16x32_bf16 v[30:33], v[90:93], v[178:181], v[30:33]
	v_mfma_f32_16x16x32_bf16 v[30:33], v[102:105], v[204:207], v[30:33]
	v_mfma_f32_16x16x32_bf16 v[26:29], v[114:117], v[178:181], v[26:29]
	v_mfma_f32_16x16x32_bf16 v[26:29], v[126:129], v[204:207], v[26:29]
	v_mfma_f32_16x16x32_bf16 v[14:17], v[90:93], v[182:185], v[14:17]
	v_mfma_f32_16x16x32_bf16 v[14:17], v[102:105], v[226:229], v[14:17]
	v_mfma_f32_16x16x32_bf16 v[10:13], v[114:117], v[182:185], v[10:13]
	v_mfma_f32_16x16x32_bf16 v[10:13], v[126:129], v[226:229], v[10:13]
	s_setprio 0
	s_setprio 1
	v_mfma_f32_16x16x32_bf16 v[54:57], v[138:141], v[162:165], v[54:57]
	v_mfma_f32_16x16x32_bf16 v[54:57], v[150:153], v[170:173], v[54:57]
	v_mfma_f32_16x16x32_bf16 v[50:53], v[154:157], v[162:165], v[50:53]
	v_mfma_f32_16x16x32_bf16 v[50:53], v[158:161], v[170:173], v[50:53]
	v_mfma_f32_16x16x32_bf16 v[38:41], v[138:141], v[166:169], v[38:41]
	v_mfma_f32_16x16x32_bf16 v[38:41], v[150:153], v[174:177], v[38:41]
	v_mfma_f32_16x16x32_bf16 v[34:37], v[154:157], v[166:169], v[34:37]
	v_mfma_f32_16x16x32_bf16 v[34:37], v[158:161], v[174:177], v[34:37]
	v_mfma_f32_16x16x32_bf16 v[22:25], v[138:141], v[178:181], v[22:25]
	v_mfma_f32_16x16x32_bf16 v[22:25], v[150:153], v[204:207], v[22:25]
	v_mfma_f32_16x16x32_bf16 v[18:21], v[154:157], v[178:181], v[18:21]
	v_mfma_f32_16x16x32_bf16 v[18:21], v[158:161], v[204:207], v[18:21]
	v_mfma_f32_16x16x32_bf16 v[6:9], v[138:141], v[182:185], v[6:9]
	v_mfma_f32_16x16x32_bf16 v[6:9], v[150:153], v[226:229], v[6:9]
	v_mfma_f32_16x16x32_bf16 v[2:5], v[154:157], v[182:185], v[2:5]
	v_mfma_f32_16x16x32_bf16 v[2:5], v[158:161], v[226:229], v[2:5]
	s_setprio 0
	s_barrier
	s_add_i32 s44, s44, 2
	s_add_u32 s40, s40, 0x100
	s_addc_u32 s41, s41, 0
	s_add_u32 s42, s42, 0x100
	s_addc_u32 s43, s43, 0
	s_cmp_gt_u32 s44, 41
	s_cbranch_scc0 .LBB0_589
	s_branch .Lpx_1
.Lpeel_1:
	s_mov_b32 s100, 0
	ds_read_b128 v[90:93], v212
	ds_read_b128 v[102:105], v213
	ds_read_b128 v[114:117], v214
	ds_read_b128 v[126:129], v215
	ds_read_b128 v[138:141], v216
	ds_read_b128 v[150:153], v217
	ds_read_b128 v[154:157], v218
	ds_read_b128 v[158:161], v219
	s_add_u32 s45, s40, 0xfff50080
	s_addc_u32 s46, s41, -1
	s_cmp_eq_u32 s44, 40
	s_cselect_b32 s55, s1, s46
	s_cselect_b32 s54, s0, s45
	s_cselect_b32 s53, s15, s43
	s_cselect_b32 s52, s14, s42
	s_add_i32 m0, s56, 0xc000
	ds_read_b128 v[162:165], v220
	ds_read_b128 v[166:169], v220 offset:2048
	ds_read_b128 v[170:173], v221
	ds_read_b128 v[174:177], v221 offset:2048
	ds_read_b128 v[178:181], v220 offset:4096
	ds_read_b128 v[182:185], v220 offset:6144
	ds_read_b128 v[204:207], v221 offset:4096
	ds_read_b128 v[226:229], v221 offset:6144
	global_load_lds_dwordx4 v196, s[40:41]
	s_add_i32 m0, s56, 0xe000
	s_nop 0
	global_load_lds_dwordx4 v198, s[40:41]
	s_waitcnt vmcnt(8)
	s_waitcnt lgkmcnt(0)
	s_barrier
	s_setprio 1
	s_waitcnt lgkmcnt(0)
	v_mfma_f32_16x16x32_bf16 v[146:149], v[90:93], v[162:165], 0
	v_mfma_f32_16x16x32_bf16 v[146:149], v[102:105], v[170:173], v[146:149]
	v_mfma_f32_16x16x32_bf16 v[142:145], v[114:117], v[162:165], 0
	v_mfma_f32_16x16x32_bf16 v[142:145], v[126:129], v[170:173], v[142:145]
	v_mfma_f32_16x16x32_bf16 v[122:125], v[90:93], v[166:169], 0
	v_mfma_f32_16x16x32_bf16 v[122:125], v[102:105], v[174:177], v[122:125]
	v_mfma_f32_16x16x32_bf16 v[118:121], v[114:117], v[166:169], 0
	v_mfma_f32_16x16x32_bf16 v[118:121], v[126:129], v[174:177], v[118:121]
	v_mfma_f32_16x16x32_bf16 v[98:101], v[90:93], v[178:181], 0
	v_mfma_f32_16x16x32_bf16 v[98:101], v[102:105], v[204:207], v[98:101]
	v_mfma_f32_16x16x32_bf16 v[94:97], v[114:117], v[178:181], 0
	v_mfma_f32_16x16x32_bf16 v[94:97], v[126:129], v[204:207], v[94:97]
	v_mfma_f32_16x16x32_bf16 v[78:81], v[90:93], v[182:185], 0
	v_mfma_f32_16x16x32_bf16 v[78:81], v[102:105], v[226:229], v[78:81]
	v_mfma_f32_16x16x32_bf16 v[74:77], v[114:117], v[182:185], 0
	v_mfma_f32_16x16x32_bf16 v[74:77], v[126:129], v[226:229], v[74:77]
	s_setprio 0
	s_setprio 1
	v_mfma_f32_16x16x32_bf16 v[134:137], v[138:141], v[162:165], 0
	v_mfma_f32_16x16x32_bf16 v[134:137], v[150:153], v[170:173], v[134:137]
	v_mfma_f32_16x16x32_bf16 v[130:133], v[154:157], v[162:165], 0
	v_mfma_f32_16x16x32_bf16 v[130:133], v[158:161], v[170:173], v[130:133]
	v_mfma_f32_16x16x32_bf16 v[110:113], v[138:141], v[166:169], 0
	v_mfma_f32_16x16x32_bf16 v[110:113], v[150:153], v[174:177], v[110:113]
	v_mfma_f32_16x16x32_bf16 v[106:109], v[154:157], v[166:169], 0
	v_mfma_f32_16x16x32_bf16 v[106:109], v[158:161], v[174:177], v[106:109]
	v_mfma_f32_16x16x32_bf16 v[86:89], v[138:141], v[178:181], 0
	v_mfma_f32_16x16x32_bf16 v[86:89], v[150:153], v[204:207], v[86:89]
	v_mfma_f32_16x16x32_bf16 v[82:85], v[154:157], v[178:181], 0
	v_mfma_f32_16x16x32_bf16 v[82:85], v[158:161], v[204:207], v[82:85]
	v_mfma_f32_16x16x32_bf16 v[70:73], v[138:141], v[182:185], 0
	v_mfma_f32_16x16x32_bf16 v[70:73], v[150:153], v[226:229], v[70:73]
	v_mfma_f32_16x16x32_bf16 v[66:69], v[154:157], v[182:185], 0
	v_mfma_f32_16x16x32_bf16 v[66:69], v[158:161], v[226:229], v[66:69]
	s_setprio 0
	s_barrier
	s_add_i32 s45, s68, s39
	s_mov_b32 m0, s45
	ds_read_b128 v[162:165], v220 offset:16384
	ds_read_b128 v[166:169], v220 offset:18432
	ds_read_b128 v[170:173], v221 offset:16384
	ds_read_b128 v[174:177], v221 offset:18432
	ds_read_b128 v[178:181], v220 offset:20480
	ds_read_b128 v[182:185], v220 offset:22528
	ds_read_b128 v[204:207], v221 offset:20480
	ds_read_b128 v[226:229], v221 offset:22528
	global_load_lds_dwordx4 v188, s[52:53]
	s_add_i32 m0, s45, 0x2000
	s_add_u32 s46, s52, 0xb0000
	s_addc_u32 s47, s53, 0
	s_add_i32 s45, s69, s39
	global_load_lds_dwordx4 v192, s[52:53]
	s_mov_b32 m0, s45
	s_nop 0
	global_load_lds_dwordx4 v188, s[46:47]
	s_add_i32 m0, s45, 0x2000
	s_nop 0
	global_load_lds_dwordx4 v192, s[46:47]
	s_mov_b32 m0, s56
	s_nop 0
	global_load_lds_dwordx4 v186, s[54:55]
	s_mov_b32 m0, s57
	s_nop 0
	global_load_lds_dwordx4 v190, s[54:55]
	s_waitcnt vmcnt(8)
	s_waitcnt lgkmcnt(0)
	s_barrier
	s_setprio 1
	s_waitcnt lgkmcnt(0)
	v_mfma_f32_16x16x32_bf16 v[62:65], v[90:93], v[162:165], 0
	v_mfma_f32_16x16x32_bf16 v[62:65], v[102:105], v[170:173], v[62:65]
	v_mfma_f32_16x16x32_bf16 v[58:61], v[114:117], v[162:165], 0
	v_mfma_f32_16x16x32_bf16 v[58:61], v[126:129], v[170:173], v[58:61]
	v_mfma_f32_16x16x32_bf16 v[46:49], v[90:93], v[166:169], 0
	v_mfma_f32_16x16x32_bf16 v[46:49], v[102:105], v[174:177], v[46:49]
	v_mfma_f32_16x16x32_bf16 v[42:45], v[114:117], v[166:169], 0
	v_mfma_f32_16x16x32_bf16 v[42:45], v[126:129], v[174:177], v[42:45]
	v_mfma_f32_16x16x32_bf16 v[30:33], v[90:93], v[178:181], 0
	v_mfma_f32_16x16x32_bf16 v[30:33], v[102:105], v[204:207], v[30:33]
	v_mfma_f32_16x16x32_bf16 v[26:29], v[114:117], v[178:181], 0
	v_mfma_f32_16x16x32_bf16 v[26:29], v[126:129], v[204:207], v[26:29]
	v_mfma_f32_16x16x32_bf16 v[14:17], v[90:93], v[182:185], 0
	v_mfma_f32_16x16x32_bf16 v[14:17], v[102:105], v[226:229], v[14:17]
	v_mfma_f32_16x16x32_bf16 v[10:13], v[114:117], v[182:185], 0
	v_mfma_f32_16x16x32_bf16 v[10:13], v[126:129], v[226:229], v[10:13]
	s_setprio 0
	s_setprio 1
	v_mfma_f32_16x16x32_bf16 v[54:57], v[138:141], v[162:165], 0
	v_mfma_f32_16x16x32_bf16 v[54:57], v[150:153], v[170:173], v[54:57]
	v_mfma_f32_16x16x32_bf16 v[50:53], v[154:157], v[162:165], 0
	v_mfma_f32_16x16x32_bf16 v[50:53], v[158:161], v[170:173], v[50:53]
	v_mfma_f32_16x16x32_bf16 v[38:41], v[138:141], v[166:169], 0
	v_mfma_f32_16x16x32_bf16 v[38:41], v[150:153], v[174:177], v[38:41]
	v_mfma_f32_16x16x32_bf16 v[34:37], v[154:157], v[166:169], 0
	v_mfma_f32_16x16x32_bf16 v[34:37], v[158:161], v[174:177], v[34:37]
	v_mfma_f32_16x16x32_bf16 v[22:25], v[138:141], v[178:181], 0
	v_mfma_f32_16x16x32_bf16 v[22:25], v[150:153], v[204:207], v[22:25]
	v_mfma_f32_16x16x32_bf16 v[18:21], v[154:157], v[178:181], 0
	v_mfma_f32_16x16x32_bf16 v[18:21], v[158:161], v[204:207], v[18:21]
	v_mfma_f32_16x16x32_bf16 v[6:9], v[138:141], v[182:185], 0
	v_mfma_f32_16x16x32_bf16 v[6:9], v[150:153], v[226:229], v[6:9]
	v_mfma_f32_16x16x32_bf16 v[2:5], v[154:157], v[182:185], 0
	v_mfma_f32_16x16x32_bf16 v[2:5], v[158:161], v[226:229], v[2:5]
	s_setprio 0
	s_barrier
	s_add_i32 s45, 0, 0x18000
	s_add_i32 s48, 0, 0x1c000
	ds_read_b128 v[90:93], v245 offset:32768
	ds_read_b128 v[102:105], v246 offset:32768
	ds_read_b128 v[114:117], v222
	ds_read_b128 v[126:129], v223
	ds_read_b128 v[138:141], v245 offset:49152
	ds_read_b128 v[150:153], v246 offset:49152
	ds_read_b128 v[154:157], v224
	ds_read_b128 v[158:161], v225
	s_add_u32 s46, s54, 0xb0000
	s_addc_u32 s47, s55, 0
	s_mov_b32 m0, s58
	ds_read_b128 v[162:165], v220 offset:32768
	ds_read_b128 v[166:169], v220 offset:34816
	ds_read_b128 v[170:173], v221 offset:32768
	ds_read_b128 v[174:177], v221 offset:34816
	ds_read_b128 v[178:181], v220 offset:36864
	ds_read_b128 v[182:185], v220 offset:38912
	ds_read_b128 v[204:207], v221 offset:36864
	ds_read_b128 v[226:229], v221 offset:38912
	global_load_lds_dwordx4 v186, s[46:47]
	s_mov_b32 m0, s59
	s_nop 0
	global_load_lds_dwordx4 v190, s[46:47]
	s_waitcnt vmcnt(8)
	s_waitcnt lgkmcnt(0)
	s_barrier
	s_setprio 1
	s_waitcnt lgkmcnt(0)
	v_mfma_f32_16x16x32_bf16 v[146:149], v[90:93], v[162:165], v[146:149]
	v_mfma_f32_16x16x32_bf16 v[146:149], v[102:105], v[170:173], v[146:149]
	v_mfma_f32_16x16x32_bf16 v[142:145], v[114:117], v[162:165], v[142:145]
	v_mfma_f32_16x16x32_bf16 v[142:145], v[126:129], v[170:173], v[142:145]
	v_mfma_f32_16x16x32_bf16 v[122:125], v[90:93], v[166:169], v[122:125]
	v_mfma_f32_16x16x32_bf16 v[122:125], v[102:105], v[174:177], v[122:125]
	v_mfma_f32_16x16x32_bf16 v[118:121], v[114:117], v[166:169], v[118:121]
	v_mfma_f32_16x16x32_bf16 v[118:121], v[126:129], v[174:177], v[118:121]
	v_mfma_f32_16x16x32_bf16 v[98:101], v[90:93], v[178:181], v[98:101]
	v_mfma_f32_16x16x32_bf16 v[98:101], v[102:105], v[204:207], v[98:101]
	v_mfma_f32_16x16x32_bf16 v[94:97], v[114:117], v[178:181], v[94:97]
	v_mfma_f32_16x16x32_bf16 v[94:97], v[126:129], v[204:207], v[94:97]
	v_mfma_f32_16x16x32_bf16 v[78:81], v[90:93], v[182:185], v[78:81]
	v_mfma_f32_16x16x32_bf16 v[78:81], v[102:105], v[226:229], v[78:81]
	v_mfma_f32_16x16x32_bf16 v[74:77], v[114:117], v[182:185], v[74:77]
	v_mfma_f32_16x16x32_bf16 v[74:77], v[126:129], v[226:229], v[74:77]
	s_setprio 0
	s_setprio 1
	v_mfma_f32_16x16x32_bf16 v[134:137], v[138:141], v[162:165], v[134:137]
	v_mfma_f32_16x16x32_bf16 v[134:137], v[150:153], v[170:173], v[134:137]
	v_mfma_f32_16x16x32_bf16 v[130:133], v[154:157], v[162:165], v[130:133]
	v_mfma_f32_16x16x32_bf16 v[130:133], v[158:161], v[170:173], v[130:133]
	v_mfma_f32_16x16x32_bf16 v[110:113], v[138:141], v[166:169], v[110:113]
	v_mfma_f32_16x16x32_bf16 v[110:113], v[150:153], v[174:177], v[110:113]
	v_mfma_f32_16x16x32_bf16 v[106:109], v[154:157], v[166:169], v[106:109]
	v_mfma_f32_16x16x32_bf16 v[106:109], v[158:161], v[174:177], v[106:109]
	v_mfma_f32_16x16x32_bf16 v[86:89], v[138:141], v[178:181], v[86:89]
	v_mfma_f32_16x16x32_bf16 v[86:89], v[150:153], v[204:207], v[86:89]
	v_mfma_f32_16x16x32_bf16 v[82:85], v[154:157], v[178:181], v[82:85]
	v_mfma_f32_16x16x32_bf16 v[82:85], v[158:161], v[204:207], v[82:85]
	v_mfma_f32_16x16x32_bf16 v[70:73], v[138:141], v[182:185], v[70:73]
	v_mfma_f32_16x16x32_bf16 v[70:73], v[150:153], v[226:229], v[70:73]
	v_mfma_f32_16x16x32_bf16 v[66:69], v[154:157], v[182:185], v[66:69]
	v_mfma_f32_16x16x32_bf16 v[66:69], v[158:161], v[226:229], v[66:69]
	s_setprio 0
	s_barrier
	s_add_i32 s45, s45, s39
	s_add_i32 m0, s45, 0xffffff80
	ds_read_b128 v[162:165], v220 offset:49152
	ds_read_b128 v[166:169], v220 offset:51200
	ds_read_b128 v[170:173], v221 offset:49152
	ds_read_b128 v[174:177], v221 offset:51200
	ds_read_b128 v[178:181], v220 offset:53248
	ds_read_b128 v[182:185], v220 offset:55296
	ds_read_b128 v[204:207], v221 offset:53248
	ds_read_b128 v[226:229], v221 offset:55296
	global_load_lds_dwordx4 v188, s[52:53] offset:128
	s_add_i32 m0, s45, 0x1f80
	s_add_u32 s46, s52, 0xb0080
	s_addc_u32 s47, s53, 0
	s_add_i32 s45, s48, s39
	global_load_lds_dwordx4 v192, s[52:53] offset:128
	s_mov_b32 m0, s45
	s_nop 0
	global_load_lds_dwordx4 v188, s[46:47]
	s_add_i32 m0, s45, 0x2000
	s_nop 0
	global_load_lds_dwordx4 v192, s[46:47]
	s_add_i32 m0, s63, 0xffffff80
	s_nop 0
	global_load_lds_dwordx4 v186, s[54:55] offset:128
	s_add_i32 m0, s64, 0xffffff80
	s_nop 0
	global_load_lds_dwordx4 v190, s[54:55] offset:128
	s_waitcnt vmcnt(8)
	s_waitcnt lgkmcnt(0)
	s_barrier
	s_setprio 1
	s_waitcnt lgkmcnt(0)
	v_mfma_f32_16x16x32_bf16 v[62:65], v[90:93], v[162:165], v[62:65]
	v_mfma_f32_16x16x32_bf16 v[62:65], v[102:105], v[170:173], v[62:65]
	v_mfma_f32_16x16x32_bf16 v[58:61], v[114:117], v[162:165], v[58:61]
	v_mfma_f32_16x16x32_bf16 v[58:61], v[126:129], v[170:173], v[58:61]
	v_mfma_f32_16x16x32_bf16 v[46:49], v[90:93], v[166:169], v[46:49]
	v_mfma_f32_16x16x32_bf16 v[46:49], v[102:105], v[174:177], v[46:49]
	v_mfma_f32_16x16x32_bf16 v[42:45], v[114:117], v[166:169], v[42:45]
	v_mfma_f32_16x16x32_bf16 v[42:45], v[126:129], v[174:177], v[42:45]
	v_mfma_f32_16x16x32_bf16 v[30:33], v[90:93], v[178:181], v[30:33]
	v_mfma_f32_16x16x32_bf16 v[30:33], v[102:105], v[204:207], v[30:33]
	v_mfma_f32_16x16x32_bf16 v[26:29], v[114:117], v[178:181], v[26:29]
	v_mfma_f32_16x16x32_bf16 v[26:29], v[126:129], v[204:207], v[26:29]
	v_mfma_f32_16x16x32_bf16 v[14:17], v[90:93], v[182:185], v[14:17]
	v_mfma_f32_16x16x32_bf16 v[14:17], v[102:105], v[226:229], v[14:17]
	v_mfma_f32_16x16x32_bf16 v[10:13], v[114:117], v[182:185], v[10:13]
	v_mfma_f32_16x16x32_bf16 v[10:13], v[126:129], v[226:229], v[10:13]
	s_setprio 0
	s_setprio 1
	v_mfma_f32_16x16x32_bf16 v[54:57], v[138:141], v[162:165], v[54:57]
	v_mfma_f32_16x16x32_bf16 v[54:57], v[150:153], v[170:173], v[54:57]
	v_mfma_f32_16x16x32_bf16 v[50:53], v[154:157], v[162:165], v[50:53]
	v_mfma_f32_16x16x32_bf16 v[50:53], v[158:161], v[170:173], v[50:53]
	v_mfma_f32_16x16x32_bf16 v[38:41], v[138:141], v[166:169], v[38:41]
	v_mfma_f32_16x16x32_bf16 v[38:41], v[150:153], v[174:177], v[38:41]
	v_mfma_f32_16x16x32_bf16 v[34:37], v[154:157], v[166:169], v[34:37]
	v_mfma_f32_16x16x32_bf16 v[34:37], v[158:161], v[174:177], v[34:37]
	v_mfma_f32_16x16x32_bf16 v[22:25], v[138:141], v[178:181], v[22:25]
	v_mfma_f32_16x16x32_bf16 v[22:25], v[150:153], v[204:207], v[22:25]
	v_mfma_f32_16x16x32_bf16 v[18:21], v[154:157], v[178:181], v[18:21]
	v_mfma_f32_16x16x32_bf16 v[18:21], v[158:161], v[204:207], v[18:21]
	v_mfma_f32_16x16x32_bf16 v[6:9], v[138:141], v[182:185], v[6:9]
	v_mfma_f32_16x16x32_bf16 v[6:9], v[150:153], v[226:229], v[6:9]
	v_mfma_f32_16x16x32_bf16 v[2:5], v[154:157], v[182:185], v[2:5]
	v_mfma_f32_16x16x32_bf16 v[2:5], v[158:161], v[226:229], v[2:5]
	s_setprio 0
	s_barrier
	s_add_i32 s44, s44, 2
	s_add_u32 s40, s40, 0x100
	s_addc_u32 s41, s41, 0
	s_add_u32 s42, s42, 0x100
	s_addc_u32 s43, s43, 0
	s_cmp_gt_u32 s44, 41
	s_cbranch_scc0 .LBB0_589

.LBB0_684:
	s_cmp_lg_u32 s100, 0
	s_cbranch_scc1 .Lpeel_2
	ds_read_b128 v[132:135], v245
	ds_read_b128 v[136:139], v246
	ds_read_b128 v[140:143], v245 offset:2048
	ds_read_b128 v[144:147], v246 offset:2048
	ds_read_b128 v[148:151], v245 offset:16384
	ds_read_b128 v[152:155], v246 offset:16384
	ds_read_b128 v[156:159], v245 offset:18432
	ds_read_b128 v[160:163], v246 offset:18432
	s_add_u32 s43, s10, 0xfffc0080
	s_addc_u32 s46, s11, -1
	s_and_b64 s[44:45], s[86:87], exec
	s_cselect_b32 vcc_hi, s5, s46
	s_cselect_b32 vcc_lo, s38, s43
	s_cselect_b32 s87, s13, s69
	s_cselect_b32 s86, s39, s68
	s_add_i32 m0, s88, 0xc000
	ds_read_b128 v[164:167], v215
	s_waitcnt lgkmcnt(0)
	ds_read_b128 v[190:193], v215 offset:2048
	ds_read_b128 v[194:197], v216
	ds_read_b128 v[198:201], v216 offset:2048
	ds_read_b128 v[202:205], v215 offset:4096
	ds_read_b128 v[206:209], v215 offset:6144
	ds_read_b128 v[218:221], v216 offset:4096
	ds_read_b128 v[222:225], v216 offset:6144
	global_load_lds_dwordx4 v180, s[10:11]
	s_add_i32 m0, s88, 0xe000
	s_nop 0
	global_load_lds_dwordx4 v184, s[10:11]
	s_waitcnt vmcnt(8)
	s_waitcnt lgkmcnt(0)
	s_barrier
	s_setprio 1
	s_waitcnt lgkmcnt(0)
	v_mfma_f32_16x16x32_bf16 v[126:129], v[132:135], v[164:167], v[126:129]
	v_mfma_f32_16x16x32_bf16 v[126:129], v[136:139], v[194:197], v[126:129]
	v_mfma_f32_16x16x32_bf16 v[122:125], v[140:143], v[164:167], v[122:125]
	v_mfma_f32_16x16x32_bf16 v[122:125], v[144:147], v[194:197], v[122:125]
	v_mfma_f32_16x16x32_bf16 v[110:113], v[132:135], v[190:193], v[110:113]
	v_mfma_f32_16x16x32_bf16 v[110:113], v[136:139], v[198:201], v[110:113]
	v_mfma_f32_16x16x32_bf16 v[106:109], v[140:143], v[190:193], v[106:109]
	v_mfma_f32_16x16x32_bf16 v[106:109], v[144:147], v[198:201], v[106:109]
	v_mfma_f32_16x16x32_bf16 v[94:97], v[132:135], v[202:205], v[94:97]
	v_mfma_f32_16x16x32_bf16 v[94:97], v[136:139], v[218:221], v[94:97]
	v_mfma_f32_16x16x32_bf16 v[90:93], v[140:143], v[202:205], v[90:93]
	v_mfma_f32_16x16x32_bf16 v[90:93], v[144:147], v[218:221], v[90:93]
	v_mfma_f32_16x16x32_bf16 v[78:81], v[132:135], v[206:209], v[78:81]
	v_mfma_f32_16x16x32_bf16 v[78:81], v[136:139], v[222:225], v[78:81]
	v_mfma_f32_16x16x32_bf16 v[74:77], v[140:143], v[206:209], v[74:77]
	v_mfma_f32_16x16x32_bf16 v[74:77], v[144:147], v[222:225], v[74:77]
	s_setprio 0
	s_setprio 1
	v_mfma_f32_16x16x32_bf16 v[118:121], v[148:151], v[164:167], v[118:121]
	v_mfma_f32_16x16x32_bf16 v[118:121], v[152:155], v[194:197], v[118:121]
	v_mfma_f32_16x16x32_bf16 v[114:117], v[156:159], v[164:167], v[114:117]
	v_mfma_f32_16x16x32_bf16 v[114:117], v[160:163], v[194:197], v[114:117]
	v_mfma_f32_16x16x32_bf16 v[102:105], v[148:151], v[190:193], v[102:105]
	v_mfma_f32_16x16x32_bf16 v[102:105], v[152:155], v[198:201], v[102:105]
	v_mfma_f32_16x16x32_bf16 v[98:101], v[156:159], v[190:193], v[98:101]
	v_mfma_f32_16x16x32_bf16 v[98:101], v[160:163], v[198:201], v[98:101]
	v_mfma_f32_16x16x32_bf16 v[86:89], v[148:151], v[202:205], v[86:89]
	v_mfma_f32_16x16x32_bf16 v[86:89], v[152:155], v[218:221], v[86:89]
	v_mfma_f32_16x16x32_bf16 v[82:85], v[156:159], v[202:205], v[82:85]
	v_mfma_f32_16x16x32_bf16 v[82:85], v[160:163], v[218:221], v[82:85]
	v_mfma_f32_16x16x32_bf16 v[70:73], v[148:151], v[206:209], v[70:73]
	v_mfma_f32_16x16x32_bf16 v[70:73], v[152:155], v[222:225], v[70:73]
	v_mfma_f32_16x16x32_bf16 v[66:69], v[156:159], v[206:209], v[66:69]
	v_mfma_f32_16x16x32_bf16 v[66:69], v[160:163], v[222:225], v[66:69]
	s_setprio 0
	s_barrier
	s_add_i32 s43, s78, s15
	s_mov_b32 m0, s43
	ds_read_b128 v[164:167], v215 offset:16384
	ds_read_b128 v[190:193], v215 offset:18432
	ds_read_b128 v[194:197], v216 offset:16384
	ds_read_b128 v[198:201], v216 offset:18432
	ds_read_b128 v[202:205], v215 offset:20480
	ds_read_b128 v[206:209], v215 offset:22528
	ds_read_b128 v[218:221], v216 offset:20480
	ds_read_b128 v[222:225], v216 offset:22528
	global_load_lds_dwordx4 v170, s[86:87]
	s_add_i32 m0, s43, 0x2000
	s_add_u32 s44, s86, 0x40000
	s_addc_u32 s45, s87, 0
	s_add_i32 s43, s82, s15
	global_load_lds_dwordx4 v178, s[86:87]
	s_mov_b32 m0, s43
	s_nop 0
	global_load_lds_dwordx4 v170, s[44:45]
	s_add_i32 m0, s43, 0x2000
	s_nop 0
	global_load_lds_dwordx4 v178, s[44:45]
	s_mov_b32 m0, s88
	s_nop 0
	global_load_lds_dwordx4 v174, vcc
	s_mov_b32 m0, s89
	s_nop 0
	global_load_lds_dwordx4 v176, vcc
	s_waitcnt vmcnt(8)
	s_waitcnt lgkmcnt(0)
	s_barrier
	s_setprio 1
	s_waitcnt lgkmcnt(0)
	v_mfma_f32_16x16x32_bf16 v[62:65], v[132:135], v[164:167], v[62:65]
	v_mfma_f32_16x16x32_bf16 v[62:65], v[136:139], v[194:197], v[62:65]
	v_mfma_f32_16x16x32_bf16 v[58:61], v[140:143], v[164:167], v[58:61]
	v_mfma_f32_16x16x32_bf16 v[58:61], v[144:147], v[194:197], v[58:61]
	v_mfma_f32_16x16x32_bf16 v[46:49], v[132:135], v[190:193], v[46:49]
	v_mfma_f32_16x16x32_bf16 v[46:49], v[136:139], v[198:201], v[46:49]
	v_mfma_f32_16x16x32_bf16 v[42:45], v[140:143], v[190:193], v[42:45]
	v_mfma_f32_16x16x32_bf16 v[42:45], v[144:147], v[198:201], v[42:45]
	v_mfma_f32_16x16x32_bf16 v[30:33], v[132:135], v[202:205], v[30:33]
	v_mfma_f32_16x16x32_bf16 v[30:33], v[136:139], v[218:221], v[30:33]
	v_mfma_f32_16x16x32_bf16 v[26:29], v[140:143], v[202:205], v[26:29]
	v_mfma_f32_16x16x32_bf16 v[26:29], v[144:147], v[218:221], v[26:29]
	v_mfma_f32_16x16x32_bf16 v[14:17], v[132:135], v[206:209], v[14:17]
	v_mfma_f32_16x16x32_bf16 v[14:17], v[136:139], v[222:225], v[14:17]
	v_mfma_f32_16x16x32_bf16 v[10:13], v[140:143], v[206:209], v[10:13]
	v_mfma_f32_16x16x32_bf16 v[10:13], v[144:147], v[222:225], v[10:13]
	s_setprio 0
	s_setprio 1
	v_mfma_f32_16x16x32_bf16 v[54:57], v[148:151], v[164:167], v[54:57]
	v_mfma_f32_16x16x32_bf16 v[54:57], v[152:155], v[194:197], v[54:57]
	v_mfma_f32_16x16x32_bf16 v[50:53], v[156:159], v[164:167], v[50:53]
	v_mfma_f32_16x16x32_bf16 v[50:53], v[160:163], v[194:197], v[50:53]
	v_mfma_f32_16x16x32_bf16 v[38:41], v[148:151], v[190:193], v[38:41]
	v_mfma_f32_16x16x32_bf16 v[38:41], v[152:155], v[198:201], v[38:41]
	v_mfma_f32_16x16x32_bf16 v[34:37], v[156:159], v[190:193], v[34:37]
	v_mfma_f32_16x16x32_bf16 v[34:37], v[160:163], v[198:201], v[34:37]
	v_mfma_f32_16x16x32_bf16 v[22:25], v[148:151], v[202:205], v[22:25]
	v_mfma_f32_16x16x32_bf16 v[22:25], v[152:155], v[218:221], v[22:25]
	v_mfma_f32_16x16x32_bf16 v[18:21], v[156:159], v[202:205], v[18:21]
	v_mfma_f32_16x16x32_bf16 v[18:21], v[160:163], v[218:221], v[18:21]
	v_mfma_f32_16x16x32_bf16 v[6:9], v[148:151], v[206:209], v[6:9]
	v_mfma_f32_16x16x32_bf16 v[6:9], v[152:155], v[222:225], v[6:9]
	v_mfma_f32_16x16x32_bf16 v[2:5], v[156:159], v[206:209], v[2:5]
	v_mfma_f32_16x16x32_bf16 v[2:5], v[160:163], v[222:225], v[2:5]
	s_setprio 0
	s_barrier
	s_add_i32 s43, 0, 0x18000
	s_add_i32 s46, 0, 0x1c000
	ds_read_b128 v[132:135], v245 offset:32768
	ds_read_b128 v[136:139], v246 offset:32768
	ds_read_b128 v[140:143], v245 offset:34816
	ds_read_b128 v[144:147], v246 offset:34816
	ds_read_b128 v[148:151], v245 offset:49152
	ds_read_b128 v[152:155], v246 offset:49152
	ds_read_b128 v[156:159], v245 offset:51200
	ds_read_b128 v[160:163], v246 offset:51200
	s_add_u32 s44, vcc_lo, 0x40000
	s_addc_u32 s45, vcc_hi, 0
	s_mov_b32 m0, s94
	ds_read_b128 v[164:167], v215 offset:32768
	ds_read_b128 v[190:193], v215 offset:34816
	ds_read_b128 v[194:197], v216 offset:32768
	ds_read_b128 v[198:201], v216 offset:34816
	ds_read_b128 v[202:205], v215 offset:36864
	ds_read_b128 v[206:209], v215 offset:38912
	ds_read_b128 v[218:221], v216 offset:36864
	ds_read_b128 v[222:225], v216 offset:38912
	global_load_lds_dwordx4 v174, s[44:45]
	s_mov_b32 m0, s95
	s_nop 0
	global_load_lds_dwordx4 v176, s[44:45]
	s_waitcnt vmcnt(8)
	s_waitcnt lgkmcnt(0)
	s_barrier
	s_setprio 1
	s_waitcnt lgkmcnt(0)
	v_mfma_f32_16x16x32_bf16 v[126:129], v[132:135], v[164:167], v[126:129]
	v_mfma_f32_16x16x32_bf16 v[126:129], v[136:139], v[194:197], v[126:129]
	v_mfma_f32_16x16x32_bf16 v[122:125], v[140:143], v[164:167], v[122:125]
	v_mfma_f32_16x16x32_bf16 v[122:125], v[144:147], v[194:197], v[122:125]
	v_mfma_f32_16x16x32_bf16 v[110:113], v[132:135], v[190:193], v[110:113]
	v_mfma_f32_16x16x32_bf16 v[110:113], v[136:139], v[198:201], v[110:113]
	v_mfma_f32_16x16x32_bf16 v[106:109], v[140:143], v[190:193], v[106:109]
	v_mfma_f32_16x16x32_bf16 v[106:109], v[144:147], v[198:201], v[106:109]
	v_mfma_f32_16x16x32_bf16 v[94:97], v[132:135], v[202:205], v[94:97]
	v_mfma_f32_16x16x32_bf16 v[94:97], v[136:139], v[218:221], v[94:97]
	v_mfma_f32_16x16x32_bf16 v[90:93], v[140:143], v[202:205], v[90:93]
	v_mfma_f32_16x16x32_bf16 v[90:93], v[144:147], v[218:221], v[90:93]
	v_mfma_f32_16x16x32_bf16 v[78:81], v[132:135], v[206:209], v[78:81]
	v_mfma_f32_16x16x32_bf16 v[78:81], v[136:139], v[222:225], v[78:81]
	v_mfma_f32_16x16x32_bf16 v[74:77], v[140:143], v[206:209], v[74:77]
	v_mfma_f32_16x16x32_bf16 v[74:77], v[144:147], v[222:225], v[74:77]
	s_setprio 0
	s_setprio 1
	v_mfma_f32_16x16x32_bf16 v[118:121], v[148:151], v[164:167], v[118:121]
	v_mfma_f32_16x16x32_bf16 v[118:121], v[152:155], v[194:197], v[118:121]
	v_mfma_f32_16x16x32_bf16 v[114:117], v[156:159], v[164:167], v[114:117]
	v_mfma_f32_16x16x32_bf16 v[114:117], v[160:163], v[194:197], v[114:117]
	v_mfma_f32_16x16x32_bf16 v[102:105], v[148:151], v[190:193], v[102:105]
	v_mfma_f32_16x16x32_bf16 v[102:105], v[152:155], v[198:201], v[102:105]
	v_mfma_f32_16x16x32_bf16 v[98:101], v[156:159], v[190:193], v[98:101]
	v_mfma_f32_16x16x32_bf16 v[98:101], v[160:163], v[198:201], v[98:101]
	v_mfma_f32_16x16x32_bf16 v[86:89], v[148:151], v[202:205], v[86:89]
	v_mfma_f32_16x16x32_bf16 v[86:89], v[152:155], v[218:221], v[86:89]
	v_mfma_f32_16x16x32_bf16 v[82:85], v[156:159], v[202:205], v[82:85]
	v_mfma_f32_16x16x32_bf16 v[82:85], v[160:163], v[218:221], v[82:85]
	v_mfma_f32_16x16x32_bf16 v[70:73], v[148:151], v[206:209], v[70:73]
	v_mfma_f32_16x16x32_bf16 v[70:73], v[152:155], v[222:225], v[70:73]
	v_mfma_f32_16x16x32_bf16 v[66:69], v[156:159], v[206:209], v[66:69]
	v_mfma_f32_16x16x32_bf16 v[66:69], v[160:163], v[222:225], v[66:69]
	s_setprio 0
	s_barrier
	s_add_i32 s43, s43, s15
	s_add_i32 m0, s43, 0xffffff80
	ds_read_b128 v[164:167], v215 offset:49152
	ds_read_b128 v[190:193], v215 offset:51200
	ds_read_b128 v[194:197], v216 offset:49152
	ds_read_b128 v[198:201], v216 offset:51200
	ds_read_b128 v[202:205], v215 offset:53248
	ds_read_b128 v[206:209], v215 offset:55296
	ds_read_b128 v[218:221], v216 offset:53248
	ds_read_b128 v[222:225], v216 offset:55296
	global_load_lds_dwordx4 v170, s[86:87] offset:128
	s_add_i32 m0, s43, 0x1f80
	s_add_u32 s44, s86, 0x40080
	s_addc_u32 s45, s87, 0
	s_add_i32 s43, s46, s15
	global_load_lds_dwordx4 v178, s[86:87] offset:128
	s_mov_b32 m0, s43
	s_nop 0
	global_load_lds_dwordx4 v170, s[44:45]
	s_add_i32 m0, s43, 0x2000
	s_nop 0
	global_load_lds_dwordx4 v178, s[44:45]
	s_add_i32 m0, s80, 0xffffff80
	s_nop 0
	global_load_lds_dwordx4 v174, vcc offset:128
	s_add_i32 m0, s81, 0xffffff80
	s_nop 0
	global_load_lds_dwordx4 v176, vcc offset:128
	s_waitcnt vmcnt(8)
	s_waitcnt lgkmcnt(0)
	s_barrier
	s_setprio 1
	s_waitcnt lgkmcnt(0)
	v_mfma_f32_16x16x32_bf16 v[62:65], v[132:135], v[164:167], v[62:65]
	v_mfma_f32_16x16x32_bf16 v[62:65], v[136:139], v[194:197], v[62:65]
	v_mfma_f32_16x16x32_bf16 v[58:61], v[140:143], v[164:167], v[58:61]
	v_mfma_f32_16x16x32_bf16 v[58:61], v[144:147], v[194:197], v[58:61]
	v_mfma_f32_16x16x32_bf16 v[46:49], v[132:135], v[190:193], v[46:49]
	v_mfma_f32_16x16x32_bf16 v[46:49], v[136:139], v[198:201], v[46:49]
	v_mfma_f32_16x16x32_bf16 v[42:45], v[140:143], v[190:193], v[42:45]
	v_mfma_f32_16x16x32_bf16 v[42:45], v[144:147], v[198:201], v[42:45]
	v_mfma_f32_16x16x32_bf16 v[30:33], v[132:135], v[202:205], v[30:33]
	v_mfma_f32_16x16x32_bf16 v[30:33], v[136:139], v[218:221], v[30:33]
	v_mfma_f32_16x16x32_bf16 v[26:29], v[140:143], v[202:205], v[26:29]
	v_mfma_f32_16x16x32_bf16 v[26:29], v[144:147], v[218:221], v[26:29]
	v_mfma_f32_16x16x32_bf16 v[14:17], v[132:135], v[206:209], v[14:17]
	v_mfma_f32_16x16x32_bf16 v[14:17], v[136:139], v[222:225], v[14:17]
	v_mfma_f32_16x16x32_bf16 v[10:13], v[140:143], v[206:209], v[10:13]
	v_mfma_f32_16x16x32_bf16 v[10:13], v[144:147], v[222:225], v[10:13]
	s_setprio 0
	s_setprio 1
	v_mfma_f32_16x16x32_bf16 v[54:57], v[148:151], v[164:167], v[54:57]
	v_mfma_f32_16x16x32_bf16 v[54:57], v[152:155], v[194:197], v[54:57]
	v_mfma_f32_16x16x32_bf16 v[50:53], v[156:159], v[164:167], v[50:53]
	v_mfma_f32_16x16x32_bf16 v[50:53], v[160:163], v[194:197], v[50:53]
	v_mfma_f32_16x16x32_bf16 v[38:41], v[148:151], v[190:193], v[38:41]
	v_mfma_f32_16x16x32_bf16 v[38:41], v[152:155], v[198:201], v[38:41]
	v_mfma_f32_16x16x32_bf16 v[34:37], v[156:159], v[190:193], v[34:37]
	v_mfma_f32_16x16x32_bf16 v[34:37], v[160:163], v[198:201], v[34:37]
	v_mfma_f32_16x16x32_bf16 v[22:25], v[148:151], v[202:205], v[22:25]
	v_mfma_f32_16x16x32_bf16 v[22:25], v[152:155], v[218:221], v[22:25]
	v_mfma_f32_16x16x32_bf16 v[18:21], v[156:159], v[202:205], v[18:21]
	v_mfma_f32_16x16x32_bf16 v[18:21], v[160:163], v[218:221], v[18:21]
	v_mfma_f32_16x16x32_bf16 v[6:9], v[148:151], v[206:209], v[6:9]
	v_mfma_f32_16x16x32_bf16 v[6:9], v[152:155], v[222:225], v[6:9]
	v_mfma_f32_16x16x32_bf16 v[2:5], v[156:159], v[206:209], v[2:5]
	v_mfma_f32_16x16x32_bf16 v[2:5], v[160:163], v[222:225], v[2:5]
	s_setprio 0
	s_barrier
	s_add_i32 s42, s42, 2
	s_add_u32 s10, s10, 0x100
	s_addc_u32 s11, s11, 0
	s_add_u32 s68, s68, 0x100
	s_addc_u32 s69, s69, 0
	s_cmp_gt_u32 s42, 13
	s_cbranch_scc1 .LBB0_688

.Lpeel_2:
	s_mov_b32 s100, 0
	ds_read_b128 v[132:135], v245
	ds_read_b128 v[136:139], v246
	ds_read_b128 v[140:143], v245 offset:2048
	ds_read_b128 v[144:147], v246 offset:2048
	ds_read_b128 v[148:151], v245 offset:16384
	ds_read_b128 v[152:155], v246 offset:16384
	ds_read_b128 v[156:159], v245 offset:18432
	ds_read_b128 v[160:163], v246 offset:18432
	s_add_u32 s43, s10, 0xfffc0080
	s_addc_u32 s46, s11, -1
	s_and_b64 s[44:45], s[86:87], exec
	s_cselect_b32 vcc_hi, s5, s46
	s_cselect_b32 vcc_lo, s38, s43
	s_cselect_b32 s87, s13, s69
	s_cselect_b32 s86, s39, s68
	s_add_i32 m0, s88, 0xc000
	ds_read_b128 v[164:167], v215
	s_waitcnt lgkmcnt(0)
	ds_read_b128 v[190:193], v215 offset:2048
	ds_read_b128 v[194:197], v216
	ds_read_b128 v[198:201], v216 offset:2048
	ds_read_b128 v[202:205], v215 offset:4096
	ds_read_b128 v[206:209], v215 offset:6144
	ds_read_b128 v[218:221], v216 offset:4096
	ds_read_b128 v[222:225], v216 offset:6144
	global_load_lds_dwordx4 v180, s[10:11]
	s_add_i32 m0, s88, 0xe000
	s_nop 0
	global_load_lds_dwordx4 v184, s[10:11]
	s_waitcnt vmcnt(8)
	s_waitcnt lgkmcnt(0)
	s_barrier
	s_setprio 1
	s_waitcnt lgkmcnt(0)
	v_mfma_f32_16x16x32_bf16 v[126:129], v[132:135], v[164:167], 0
	v_mfma_f32_16x16x32_bf16 v[126:129], v[136:139], v[194:197], v[126:129]
	v_mfma_f32_16x16x32_bf16 v[122:125], v[140:143], v[164:167], 0
	v_mfma_f32_16x16x32_bf16 v[122:125], v[144:147], v[194:197], v[122:125]
	v_mfma_f32_16x16x32_bf16 v[110:113], v[132:135], v[190:193], 0
	v_mfma_f32_16x16x32_bf16 v[110:113], v[136:139], v[198:201], v[110:113]
	v_mfma_f32_16x16x32_bf16 v[106:109], v[140:143], v[190:193], 0
	v_mfma_f32_16x16x32_bf16 v[106:109], v[144:147], v[198:201], v[106:109]
	v_mfma_f32_16x16x32_bf16 v[94:97], v[132:135], v[202:205], 0
	v_mfma_f32_16x16x32_bf16 v[94:97], v[136:139], v[218:221], v[94:97]
	v_mfma_f32_16x16x32_bf16 v[90:93], v[140:143], v[202:205], 0
	v_mfma_f32_16x16x32_bf16 v[90:93], v[144:147], v[218:221], v[90:93]
	v_mfma_f32_16x16x32_bf16 v[78:81], v[132:135], v[206:209], 0
	v_mfma_f32_16x16x32_bf16 v[78:81], v[136:139], v[222:225], v[78:81]
	v_mfma_f32_16x16x32_bf16 v[74:77], v[140:143], v[206:209], 0
	v_mfma_f32_16x16x32_bf16 v[74:77], v[144:147], v[222:225], v[74:77]
	s_setprio 0
	s_setprio 1
	v_mfma_f32_16x16x32_bf16 v[118:121], v[148:151], v[164:167], 0
	v_mfma_f32_16x16x32_bf16 v[118:121], v[152:155], v[194:197], v[118:121]
	v_mfma_f32_16x16x32_bf16 v[114:117], v[156:159], v[164:167], 0
	v_mfma_f32_16x16x32_bf16 v[114:117], v[160:163], v[194:197], v[114:117]
	v_mfma_f32_16x16x32_bf16 v[102:105], v[148:151], v[190:193], 0
	v_mfma_f32_16x16x32_bf16 v[102:105], v[152:155], v[198:201], v[102:105]
	v_mfma_f32_16x16x32_bf16 v[98:101], v[156:159], v[190:193], 0
	v_mfma_f32_16x16x32_bf16 v[98:101], v[160:163], v[198:201], v[98:101]
	v_mfma_f32_16x16x32_bf16 v[86:89], v[148:151], v[202:205], 0
	v_mfma_f32_16x16x32_bf16 v[86:89], v[152:155], v[218:221], v[86:89]
	v_mfma_f32_16x16x32_bf16 v[82:85], v[156:159], v[202:205], 0
	v_mfma_f32_16x16x32_bf16 v[82:85], v[160:163], v[218:221], v[82:85]
	v_mfma_f32_16x16x32_bf16 v[70:73], v[148:151], v[206:209], 0
	v_mfma_f32_16x16x32_bf16 v[70:73], v[152:155], v[222:225], v[70:73]
	v_mfma_f32_16x16x32_bf16 v[66:69], v[156:159], v[206:209], 0
	v_mfma_f32_16x16x32_bf16 v[66:69], v[160:163], v[222:225], v[66:69]
	s_setprio 0
	s_barrier
	s_add_i32 s43, s78, s15
	s_mov_b32 m0, s43
	ds_read_b128 v[164:167], v215 offset:16384
	ds_read_b128 v[190:193], v215 offset:18432
	ds_read_b128 v[194:197], v216 offset:16384
	ds_read_b128 v[198:201], v216 offset:18432
	ds_read_b128 v[202:205], v215 offset:20480
	ds_read_b128 v[206:209], v215 offset:22528
	ds_read_b128 v[218:221], v216 offset:20480
	ds_read_b128 v[222:225], v216 offset:22528
	global_load_lds_dwordx4 v170, s[86:87]
	s_add_i32 m0, s43, 0x2000
	s_add_u32 s44, s86, 0x40000
	s_addc_u32 s45, s87, 0
	s_add_i32 s43, s82, s15
	global_load_lds_dwordx4 v178, s[86:87]
	s_mov_b32 m0, s43
	s_nop 0
	global_load_lds_dwordx4 v170, s[44:45]
	s_add_i32 m0, s43, 0x2000
	s_nop 0
	global_load_lds_dwordx4 v178, s[44:45]
	s_mov_b32 m0, s88
	s_nop 0
	global_load_lds_dwordx4 v174, vcc
	s_mov_b32 m0, s89
	s_nop 0
	global_load_lds_dwordx4 v176, vcc
	s_waitcnt vmcnt(8)
	s_waitcnt lgkmcnt(0)
	s_barrier
	s_setprio 1
	s_waitcnt lgkmcnt(0)
	v_mfma_f32_16x16x32_bf16 v[62:65], v[132:135], v[164:167], 0
	v_mfma_f32_16x16x32_bf16 v[62:65], v[136:139], v[194:197], v[62:65]
	v_mfma_f32_16x16x32_bf16 v[58:61], v[140:143], v[164:167], 0
	v_mfma_f32_16x16x32_bf16 v[58:61], v[144:147], v[194:197], v[58:61]
	v_mfma_f32_16x16x32_bf16 v[46:49], v[132:135], v[190:193], 0
	v_mfma_f32_16x16x32_bf16 v[46:49], v[136:139], v[198:201], v[46:49]
	v_mfma_f32_16x16x32_bf16 v[42:45], v[140:143], v[190:193], 0
	v_mfma_f32_16x16x32_bf16 v[42:45], v[144:147], v[198:201], v[42:45]
	v_mfma_f32_16x16x32_bf16 v[30:33], v[132:135], v[202:205], 0
	v_mfma_f32_16x16x32_bf16 v[30:33], v[136:139], v[218:221], v[30:33]
	v_mfma_f32_16x16x32_bf16 v[26:29], v[140:143], v[202:205], 0
	v_mfma_f32_16x16x32_bf16 v[26:29], v[144:147], v[218:221], v[26:29]
	v_mfma_f32_16x16x32_bf16 v[14:17], v[132:135], v[206:209], 0
	v_mfma_f32_16x16x32_bf16 v[14:17], v[136:139], v[222:225], v[14:17]
	v_mfma_f32_16x16x32_bf16 v[10:13], v[140:143], v[206:209], 0
	v_mfma_f32_16x16x32_bf16 v[10:13], v[144:147], v[222:225], v[10:13]
	s_setprio 0
	s_setprio 1
	v_mfma_f32_16x16x32_bf16 v[54:57], v[148:151], v[164:167], 0
	v_mfma_f32_16x16x32_bf16 v[54:57], v[152:155], v[194:197], v[54:57]
	v_mfma_f32_16x16x32_bf16 v[50:53], v[156:159], v[164:167], 0
	v_mfma_f32_16x16x32_bf16 v[50:53], v[160:163], v[194:197], v[50:53]
	v_mfma_f32_16x16x32_bf16 v[38:41], v[148:151], v[190:193], 0
	v_mfma_f32_16x16x32_bf16 v[38:41], v[152:155], v[198:201], v[38:41]
	v_mfma_f32_16x16x32_bf16 v[34:37], v[156:159], v[190:193], 0
	v_mfma_f32_16x16x32_bf16 v[34:37], v[160:163], v[198:201], v[34:37]
	v_mfma_f32_16x16x32_bf16 v[22:25], v[148:151], v[202:205], 0
	v_mfma_f32_16x16x32_bf16 v[22:25], v[152:155], v[218:221], v[22:25]
	v_mfma_f32_16x16x32_bf16 v[18:21], v[156:159], v[202:205], 0
	v_mfma_f32_16x16x32_bf16 v[18:21], v[160:163], v[218:221], v[18:21]
	v_mfma_f32_16x16x32_bf16 v[6:9], v[148:151], v[206:209], 0
	v_mfma_f32_16x16x32_bf16 v[6:9], v[152:155], v[222:225], v[6:9]
	v_mfma_f32_16x16x32_bf16 v[2:5], v[156:159], v[206:209], 0
	v_mfma_f32_16x16x32_bf16 v[2:5], v[160:163], v[222:225], v[2:5]
	s_setprio 0
	s_barrier
	s_add_i32 s43, 0, 0x18000
	s_add_i32 s46, 0, 0x1c000
	ds_read_b128 v[132:135], v245 offset:32768
	ds_read_b128 v[136:139], v246 offset:32768
	ds_read_b128 v[140:143], v245 offset:34816
	ds_read_b128 v[144:147], v246 offset:34816
	ds_read_b128 v[148:151], v245 offset:49152
	ds_read_b128 v[152:155], v246 offset:49152
	ds_read_b128 v[156:159], v245 offset:51200
	ds_read_b128 v[160:163], v246 offset:51200
	s_add_u32 s44, vcc_lo, 0x40000
	s_addc_u32 s45, vcc_hi, 0
	s_mov_b32 m0, s94
	ds_read_b128 v[164:167], v215 offset:32768
	ds_read_b128 v[190:193], v215 offset:34816
	ds_read_b128 v[194:197], v216 offset:32768
	ds_read_b128 v[198:201], v216 offset:34816
	ds_read_b128 v[202:205], v215 offset:36864
	ds_read_b128 v[206:209], v215 offset:38912
	ds_read_b128 v[218:221], v216 offset:36864
	ds_read_b128 v[222:225], v216 offset:38912
	global_load_lds_dwordx4 v174, s[44:45]
	s_mov_b32 m0, s95
	s_nop 0
	global_load_lds_dwordx4 v176, s[44:45]
	s_waitcnt vmcnt(8)
	s_waitcnt lgkmcnt(0)
	s_barrier
	s_setprio 1
	s_waitcnt lgkmcnt(0)
	v_mfma_f32_16x16x32_bf16 v[126:129], v[132:135], v[164:167], v[126:129]
	v_mfma_f32_16x16x32_bf16 v[126:129], v[136:139], v[194:197], v[126:129]
	v_mfma_f32_16x16x32_bf16 v[122:125], v[140:143], v[164:167], v[122:125]
	v_mfma_f32_16x16x32_bf16 v[122:125], v[144:147], v[194:197], v[122:125]
	v_mfma_f32_16x16x32_bf16 v[110:113], v[132:135], v[190:193], v[110:113]
	v_mfma_f32_16x16x32_bf16 v[110:113], v[136:139], v[198:201], v[110:113]
	v_mfma_f32_16x16x32_bf16 v[106:109], v[140:143], v[190:193], v[106:109]
	v_mfma_f32_16x16x32_bf16 v[106:109], v[144:147], v[198:201], v[106:109]
	v_mfma_f32_16x16x32_bf16 v[94:97], v[132:135], v[202:205], v[94:97]
	v_mfma_f32_16x16x32_bf16 v[94:97], v[136:139], v[218:221], v[94:97]
	v_mfma_f32_16x16x32_bf16 v[90:93], v[140:143], v[202:205], v[90:93]
	v_mfma_f32_16x16x32_bf16 v[90:93], v[144:147], v[218:221], v[90:93]
	v_mfma_f32_16x16x32_bf16 v[78:81], v[132:135], v[206:209], v[78:81]
	v_mfma_f32_16x16x32_bf16 v[78:81], v[136:139], v[222:225], v[78:81]
	v_mfma_f32_16x16x32_bf16 v[74:77], v[140:143], v[206:209], v[74:77]
	v_mfma_f32_16x16x32_bf16 v[74:77], v[144:147], v[222:225], v[74:77]
	s_setprio 0
	s_setprio 1
	v_mfma_f32_16x16x32_bf16 v[118:121], v[148:151], v[164:167], v[118:121]
	v_mfma_f32_16x16x32_bf16 v[118:121], v[152:155], v[194:197], v[118:121]
	v_mfma_f32_16x16x32_bf16 v[114:117], v[156:159], v[164:167], v[114:117]
	v_mfma_f32_16x16x32_bf16 v[114:117], v[160:163], v[194:197], v[114:117]
	v_mfma_f32_16x16x32_bf16 v[102:105], v[148:151], v[190:193], v[102:105]
	v_mfma_f32_16x16x32_bf16 v[102:105], v[152:155], v[198:201], v[102:105]
	v_mfma_f32_16x16x32_bf16 v[98:101], v[156:159], v[190:193], v[98:101]
	v_mfma_f32_16x16x32_bf16 v[98:101], v[160:163], v[198:201], v[98:101]
	v_mfma_f32_16x16x32_bf16 v[86:89], v[148:151], v[202:205], v[86:89]
	v_mfma_f32_16x16x32_bf16 v[86:89], v[152:155], v[218:221], v[86:89]
	v_mfma_f32_16x16x32_bf16 v[82:85], v[156:159], v[202:205], v[82:85]
	v_mfma_f32_16x16x32_bf16 v[82:85], v[160:163], v[218:221], v[82:85]
	v_mfma_f32_16x16x32_bf16 v[70:73], v[148:151], v[206:209], v[70:73]
	v_mfma_f32_16x16x32_bf16 v[70:73], v[152:155], v[222:225], v[70:73]
	v_mfma_f32_16x16x32_bf16 v[66:69], v[156:159], v[206:209], v[66:69]
	v_mfma_f32_16x16x32_bf16 v[66:69], v[160:163], v[222:225], v[66:69]
	s_setprio 0
	s_barrier
	s_add_i32 s43, s43, s15
	s_add_i32 m0, s43, 0xffffff80
	ds_read_b128 v[164:167], v215 offset:49152
	ds_read_b128 v[190:193], v215 offset:51200
	ds_read_b128 v[194:197], v216 offset:49152
	ds_read_b128 v[198:201], v216 offset:51200
	ds_read_b128 v[202:205], v215 offset:53248
	ds_read_b128 v[206:209], v215 offset:55296
	ds_read_b128 v[218:221], v216 offset:53248
	ds_read_b128 v[222:225], v216 offset:55296
	global_load_lds_dwordx4 v170, s[86:87] offset:128
	s_add_i32 m0, s43, 0x1f80
	s_add_u32 s44, s86, 0x40080
	s_addc_u32 s45, s87, 0
	s_add_i32 s43, s46, s15
	global_load_lds_dwordx4 v178, s[86:87] offset:128
	s_mov_b32 m0, s43
	s_nop 0
	global_load_lds_dwordx4 v170, s[44:45]
	s_add_i32 m0, s43, 0x2000
	s_nop 0
	global_load_lds_dwordx4 v178, s[44:45]
	s_add_i32 m0, s80, 0xffffff80
	s_nop 0
	global_load_lds_dwordx4 v174, vcc offset:128
	s_add_i32 m0, s81, 0xffffff80
	s_nop 0
	global_load_lds_dwordx4 v176, vcc offset:128
	s_waitcnt vmcnt(8)
	s_waitcnt lgkmcnt(0)
	s_barrier
	s_setprio 1
	s_waitcnt lgkmcnt(0)
	v_mfma_f32_16x16x32_bf16 v[62:65], v[132:135], v[164:167], v[62:65]
	v_mfma_f32_16x16x32_bf16 v[62:65], v[136:139], v[194:197], v[62:65]
	v_mfma_f32_16x16x32_bf16 v[58:61], v[140:143], v[164:167], v[58:61]
	v_mfma_f32_16x16x32_bf16 v[58:61], v[144:147], v[194:197], v[58:61]
	v_mfma_f32_16x16x32_bf16 v[46:49], v[132:135], v[190:193], v[46:49]
	v_mfma_f32_16x16x32_bf16 v[46:49], v[136:139], v[198:201], v[46:49]
	v_mfma_f32_16x16x32_bf16 v[42:45], v[140:143], v[190:193], v[42:45]
	v_mfma_f32_16x16x32_bf16 v[42:45], v[144:147], v[198:201], v[42:45]
	v_mfma_f32_16x16x32_bf16 v[30:33], v[132:135], v[202:205], v[30:33]
	v_mfma_f32_16x16x32_bf16 v[30:33], v[136:139], v[218:221], v[30:33]
	v_mfma_f32_16x16x32_bf16 v[26:29], v[140:143], v[202:205], v[26:29]
	v_mfma_f32_16x16x32_bf16 v[26:29], v[144:147], v[218:221], v[26:29]
	v_mfma_f32_16x16x32_bf16 v[14:17], v[132:135], v[206:209], v[14:17]
	v_mfma_f32_16x16x32_bf16 v[14:17], v[136:139], v[222:225], v[14:17]
	v_mfma_f32_16x16x32_bf16 v[10:13], v[140:143], v[206:209], v[10:13]
	v_mfma_f32_16x16x32_bf16 v[10:13], v[144:147], v[222:225], v[10:13]
	s_setprio 0
	s_setprio 1
	v_mfma_f32_16x16x32_bf16 v[54:57], v[148:151], v[164:167], v[54:57]
	v_mfma_f32_16x16x32_bf16 v[54:57], v[152:155], v[194:197], v[54:57]
	v_mfma_f32_16x16x32_bf16 v[50:53], v[156:159], v[164:167], v[50:53]
	v_mfma_f32_16x16x32_bf16 v[50:53], v[160:163], v[194:197], v[50:53]
	v_mfma_f32_16x16x32_bf16 v[38:41], v[148:151], v[190:193], v[38:41]
	v_mfma_f32_16x16x32_bf16 v[38:41], v[152:155], v[198:201], v[38:41]
	v_mfma_f32_16x16x32_bf16 v[34:37], v[156:159], v[190:193], v[34:37]
	v_mfma_f32_16x16x32_bf16 v[34:37], v[160:163], v[198:201], v[34:37]
	v_mfma_f32_16x16x32_bf16 v[22:25], v[148:151], v[202:205], v[22:25]
	v_mfma_f32_16x16x32_bf16 v[22:25], v[152:155], v[218:221], v[22:25]
	v_mfma_f32_16x16x32_bf16 v[18:21], v[156:159], v[202:205], v[18:21]
	v_mfma_f32_16x16x32_bf16 v[18:21], v[160:163], v[218:221], v[18:21]
	v_mfma_f32_16x16x32_bf16 v[6:9], v[148:151], v[206:209], v[6:9]
	v_mfma_f32_16x16x32_bf16 v[6:9], v[152:155], v[222:225], v[6:9]
	v_mfma_f32_16x16x32_bf16 v[2:5], v[156:159], v[206:209], v[2:5]
	v_mfma_f32_16x16x32_bf16 v[2:5], v[160:163], v[222:225], v[2:5]
	s_setprio 0
	s_barrier
	s_add_i32 s42, s42, 2
	s_add_u32 s10, s10, 0x100
	s_addc_u32 s11, s11, 0
	s_add_u32 s68, s68, 0x100
	s_addc_u32 s69, s69, 0
	s_cmp_gt_u32 s42, 13
	s_cbranch_scc1 .LBB0_688
	s_branch .LBB0_685

.LBB0_1316:
	s_cmp_lg_u32 s100, 0
	s_cbranch_scc1 .Lpeel_3
	ds_read_b128 v[132:135], v245
	ds_read_b128 v[136:139], v246
	ds_read_b128 v[140:143], v245 offset:2048
	ds_read_b128 v[144:147], v246 offset:2048
	ds_read_b128 v[148:151], v245 offset:16384
	ds_read_b128 v[152:155], v246 offset:16384
	ds_read_b128 v[156:159], v245 offset:18432
	ds_read_b128 v[160:163], v246 offset:18432
	s_add_i32 s42, s42, 2
	s_add_u32 s43, s12, 0xfffe8080
	s_addc_u32 s46, s13, -1
	s_and_b64 s[44:45], s[78:79], exec
	s_cselect_b32 s81, s75, s46
	s_cselect_b32 s80, s74, s43
	s_cselect_b32 s79, s77, s72
	s_cselect_b32 s78, s76, s48
	s_add_i32 m0, s63, 0xc000
	ds_read_b128 v[164:167], v211
	ds_read_b128 v[190:193], v211 offset:2048
	s_waitcnt lgkmcnt(0)
	ds_read_b128 v[194:197], v212
	ds_read_b128 v[198:201], v212 offset:2048
	ds_read_b128 v[202:205], v211 offset:4096
	ds_read_b128 v[214:217], v211 offset:6144
	ds_read_b128 v[218:221], v212 offset:4096
	ds_read_b128 v[222:225], v212 offset:6144
	global_load_lds_dwordx4 v178, s[12:13]
	s_add_i32 m0, s63, 0xe000
	s_nop 0
	global_load_lds_dwordx4 v182, s[12:13]
	s_waitcnt vmcnt(8)
	s_waitcnt lgkmcnt(0)
	s_barrier
	s_setprio 1
	s_waitcnt lgkmcnt(0)
	v_mfma_f32_16x16x32_bf16 v[126:129], v[132:135], v[164:167], v[126:129]
	v_mfma_f32_16x16x32_bf16 v[126:129], v[136:139], v[194:197], v[126:129]
	v_mfma_f32_16x16x32_bf16 v[122:125], v[140:143], v[164:167], v[122:125]
	v_mfma_f32_16x16x32_bf16 v[122:125], v[144:147], v[194:197], v[122:125]
	v_mfma_f32_16x16x32_bf16 v[110:113], v[132:135], v[190:193], v[110:113]
	v_mfma_f32_16x16x32_bf16 v[110:113], v[136:139], v[198:201], v[110:113]
	v_mfma_f32_16x16x32_bf16 v[106:109], v[140:143], v[190:193], v[106:109]
	v_mfma_f32_16x16x32_bf16 v[106:109], v[144:147], v[198:201], v[106:109]
	v_mfma_f32_16x16x32_bf16 v[94:97], v[132:135], v[202:205], v[94:97]
	v_mfma_f32_16x16x32_bf16 v[94:97], v[136:139], v[218:221], v[94:97]
	v_mfma_f32_16x16x32_bf16 v[90:93], v[140:143], v[202:205], v[90:93]
	v_mfma_f32_16x16x32_bf16 v[90:93], v[144:147], v[218:221], v[90:93]
	v_mfma_f32_16x16x32_bf16 v[78:81], v[132:135], v[214:217], v[78:81]
	v_mfma_f32_16x16x32_bf16 v[78:81], v[136:139], v[222:225], v[78:81]
	v_mfma_f32_16x16x32_bf16 v[74:77], v[140:143], v[214:217], v[74:77]
	v_mfma_f32_16x16x32_bf16 v[74:77], v[144:147], v[222:225], v[74:77]
	s_setprio 0
	s_setprio 1
	v_mfma_f32_16x16x32_bf16 v[118:121], v[148:151], v[164:167], v[118:121]
	v_mfma_f32_16x16x32_bf16 v[118:121], v[152:155], v[194:197], v[118:121]
	v_mfma_f32_16x16x32_bf16 v[114:117], v[156:159], v[164:167], v[114:117]
	v_mfma_f32_16x16x32_bf16 v[114:117], v[160:163], v[194:197], v[114:117]
	v_mfma_f32_16x16x32_bf16 v[102:105], v[148:151], v[190:193], v[102:105]
	v_mfma_f32_16x16x32_bf16 v[102:105], v[152:155], v[198:201], v[102:105]
	v_mfma_f32_16x16x32_bf16 v[98:101], v[156:159], v[190:193], v[98:101]
	v_mfma_f32_16x16x32_bf16 v[98:101], v[160:163], v[198:201], v[98:101]
	v_mfma_f32_16x16x32_bf16 v[86:89], v[148:151], v[202:205], v[86:89]
	v_mfma_f32_16x16x32_bf16 v[86:89], v[152:155], v[218:221], v[86:89]
	v_mfma_f32_16x16x32_bf16 v[82:85], v[156:159], v[202:205], v[82:85]
	v_mfma_f32_16x16x32_bf16 v[82:85], v[160:163], v[218:221], v[82:85]
	v_mfma_f32_16x16x32_bf16 v[70:73], v[148:151], v[214:217], v[70:73]
	v_mfma_f32_16x16x32_bf16 v[70:73], v[152:155], v[222:225], v[70:73]
	v_mfma_f32_16x16x32_bf16 v[66:69], v[156:159], v[214:217], v[66:69]
	v_mfma_f32_16x16x32_bf16 v[66:69], v[160:163], v[222:225], v[66:69]
	s_setprio 0
	s_barrier
	s_add_i32 s43, s96, s62
	s_mov_b32 m0, s43
	ds_read_b128 v[164:167], v211 offset:16384
	ds_read_b128 v[190:193], v211 offset:18432
	ds_read_b128 v[194:197], v212 offset:16384
	ds_read_b128 v[198:201], v212 offset:18432
	ds_read_b128 v[202:205], v211 offset:20480
	ds_read_b128 v[214:217], v211 offset:22528
	ds_read_b128 v[218:221], v212 offset:20480
	ds_read_b128 v[222:225], v212 offset:22528
	global_load_lds_dwordx4 v170, s[78:79]
	s_add_i32 m0, s43, 0x2000
	s_add_u32 s44, s78, 0x18000
	s_addc_u32 s45, s79, 0
	s_add_i32 s43, s83, s62
	global_load_lds_dwordx4 v176, s[78:79]
	s_mov_b32 m0, s43
	s_nop 0
	global_load_lds_dwordx4 v170, s[44:45]
	s_add_i32 m0, s43, 0x2000
	s_nop 0
	global_load_lds_dwordx4 v176, s[44:45]
	s_mov_b32 m0, s63
	s_nop 0
	global_load_lds_dwordx4 v172, s[80:81]
	s_mov_b32 m0, s64
	s_nop 0
	global_load_lds_dwordx4 v174, s[80:81]
	s_waitcnt vmcnt(8)
	s_waitcnt lgkmcnt(0)
	s_barrier
	s_setprio 1
	s_waitcnt lgkmcnt(0)
	v_mfma_f32_16x16x32_bf16 v[62:65], v[132:135], v[164:167], v[62:65]
	v_mfma_f32_16x16x32_bf16 v[62:65], v[136:139], v[194:197], v[62:65]
	v_mfma_f32_16x16x32_bf16 v[58:61], v[140:143], v[164:167], v[58:61]
	v_mfma_f32_16x16x32_bf16 v[58:61], v[144:147], v[194:197], v[58:61]
	v_mfma_f32_16x16x32_bf16 v[46:49], v[132:135], v[190:193], v[46:49]
	v_mfma_f32_16x16x32_bf16 v[46:49], v[136:139], v[198:201], v[46:49]
	v_mfma_f32_16x16x32_bf16 v[42:45], v[140:143], v[190:193], v[42:45]
	v_mfma_f32_16x16x32_bf16 v[42:45], v[144:147], v[198:201], v[42:45]
	v_mfma_f32_16x16x32_bf16 v[30:33], v[132:135], v[202:205], v[30:33]
	v_mfma_f32_16x16x32_bf16 v[30:33], v[136:139], v[218:221], v[30:33]
	v_mfma_f32_16x16x32_bf16 v[26:29], v[140:143], v[202:205], v[26:29]
	v_mfma_f32_16x16x32_bf16 v[26:29], v[144:147], v[218:221], v[26:29]
	v_mfma_f32_16x16x32_bf16 v[14:17], v[132:135], v[214:217], v[14:17]
	v_mfma_f32_16x16x32_bf16 v[14:17], v[136:139], v[222:225], v[14:17]
	v_mfma_f32_16x16x32_bf16 v[10:13], v[140:143], v[214:217], v[10:13]
	v_mfma_f32_16x16x32_bf16 v[10:13], v[144:147], v[222:225], v[10:13]
	s_setprio 0
	s_setprio 1
	v_mfma_f32_16x16x32_bf16 v[54:57], v[148:151], v[164:167], v[54:57]
	v_mfma_f32_16x16x32_bf16 v[54:57], v[152:155], v[194:197], v[54:57]
	v_mfma_f32_16x16x32_bf16 v[50:53], v[156:159], v[164:167], v[50:53]
	v_mfma_f32_16x16x32_bf16 v[50:53], v[160:163], v[194:197], v[50:53]
	v_mfma_f32_16x16x32_bf16 v[38:41], v[148:151], v[190:193], v[38:41]
	v_mfma_f32_16x16x32_bf16 v[38:41], v[152:155], v[198:201], v[38:41]
	v_mfma_f32_16x16x32_bf16 v[34:37], v[156:159], v[190:193], v[34:37]
	v_mfma_f32_16x16x32_bf16 v[34:37], v[160:163], v[198:201], v[34:37]
	v_mfma_f32_16x16x32_bf16 v[22:25], v[148:151], v[202:205], v[22:25]
	v_mfma_f32_16x16x32_bf16 v[22:25], v[152:155], v[218:221], v[22:25]
	v_mfma_f32_16x16x32_bf16 v[18:21], v[156:159], v[202:205], v[18:21]
	v_mfma_f32_16x16x32_bf16 v[18:21], v[160:163], v[218:221], v[18:21]
	v_mfma_f32_16x16x32_bf16 v[6:9], v[148:151], v[214:217], v[6:9]
	v_mfma_f32_16x16x32_bf16 v[6:9], v[152:155], v[222:225], v[6:9]
	v_mfma_f32_16x16x32_bf16 v[2:5], v[156:159], v[214:217], v[2:5]
	v_mfma_f32_16x16x32_bf16 v[2:5], v[160:163], v[222:225], v[2:5]
	s_setprio 0
	s_barrier
	s_add_i32 s43, 0, 0x18000
	s_add_i32 s46, 0, 0x1c000
	ds_read_b128 v[132:135], v245 offset:32768
	ds_read_b128 v[136:139], v246 offset:32768
	ds_read_b128 v[140:143], v245 offset:34816
	ds_read_b128 v[144:147], v246 offset:34816
	ds_read_b128 v[148:151], v245 offset:49152
	ds_read_b128 v[152:155], v246 offset:49152
	ds_read_b128 v[156:159], v245 offset:51200
	ds_read_b128 v[160:163], v246 offset:51200
	s_add_u32 s44, s80, 0x18000
	s_addc_u32 s45, s81, 0
	s_mov_b32 m0, s65
	ds_read_b128 v[164:167], v211 offset:32768
	ds_read_b128 v[190:193], v211 offset:34816
	ds_read_b128 v[194:197], v212 offset:32768
	ds_read_b128 v[198:201], v212 offset:34816
	ds_read_b128 v[202:205], v211 offset:36864
	ds_read_b128 v[214:217], v211 offset:38912
	ds_read_b128 v[218:221], v212 offset:36864
	ds_read_b128 v[222:225], v212 offset:38912
	global_load_lds_dwordx4 v172, s[44:45]
	s_mov_b32 m0, s82
	s_nop 0
	global_load_lds_dwordx4 v174, s[44:45]
	s_waitcnt vmcnt(8)
	s_waitcnt lgkmcnt(0)
	s_barrier
	s_setprio 1
	s_waitcnt lgkmcnt(0)
	v_mfma_f32_16x16x32_bf16 v[126:129], v[132:135], v[164:167], v[126:129]
	v_mfma_f32_16x16x32_bf16 v[126:129], v[136:139], v[194:197], v[126:129]
	v_mfma_f32_16x16x32_bf16 v[122:125], v[140:143], v[164:167], v[122:125]
	v_mfma_f32_16x16x32_bf16 v[122:125], v[144:147], v[194:197], v[122:125]
	v_mfma_f32_16x16x32_bf16 v[110:113], v[132:135], v[190:193], v[110:113]
	v_mfma_f32_16x16x32_bf16 v[110:113], v[136:139], v[198:201], v[110:113]
	v_mfma_f32_16x16x32_bf16 v[106:109], v[140:143], v[190:193], v[106:109]
	v_mfma_f32_16x16x32_bf16 v[106:109], v[144:147], v[198:201], v[106:109]
	v_mfma_f32_16x16x32_bf16 v[94:97], v[132:135], v[202:205], v[94:97]
	v_mfma_f32_16x16x32_bf16 v[94:97], v[136:139], v[218:221], v[94:97]
	v_mfma_f32_16x16x32_bf16 v[90:93], v[140:143], v[202:205], v[90:93]
	v_mfma_f32_16x16x32_bf16 v[90:93], v[144:147], v[218:221], v[90:93]
	v_mfma_f32_16x16x32_bf16 v[78:81], v[132:135], v[214:217], v[78:81]
	v_mfma_f32_16x16x32_bf16 v[78:81], v[136:139], v[222:225], v[78:81]
	v_mfma_f32_16x16x32_bf16 v[74:77], v[140:143], v[214:217], v[74:77]
	v_mfma_f32_16x16x32_bf16 v[74:77], v[144:147], v[222:225], v[74:77]
	s_setprio 0
	s_setprio 1
	v_mfma_f32_16x16x32_bf16 v[118:121], v[148:151], v[164:167], v[118:121]
	v_mfma_f32_16x16x32_bf16 v[118:121], v[152:155], v[194:197], v[118:121]
	v_mfma_f32_16x16x32_bf16 v[114:117], v[156:159], v[164:167], v[114:117]
	v_mfma_f32_16x16x32_bf16 v[114:117], v[160:163], v[194:197], v[114:117]
	v_mfma_f32_16x16x32_bf16 v[102:105], v[148:151], v[190:193], v[102:105]
	v_mfma_f32_16x16x32_bf16 v[102:105], v[152:155], v[198:201], v[102:105]
	v_mfma_f32_16x16x32_bf16 v[98:101], v[156:159], v[190:193], v[98:101]
	v_mfma_f32_16x16x32_bf16 v[98:101], v[160:163], v[198:201], v[98:101]
	v_mfma_f32_16x16x32_bf16 v[86:89], v[148:151], v[202:205], v[86:89]
	v_mfma_f32_16x16x32_bf16 v[86:89], v[152:155], v[218:221], v[86:89]
	v_mfma_f32_16x16x32_bf16 v[82:85], v[156:159], v[202:205], v[82:85]
	v_mfma_f32_16x16x32_bf16 v[82:85], v[160:163], v[218:221], v[82:85]
	v_mfma_f32_16x16x32_bf16 v[70:73], v[148:151], v[214:217], v[70:73]
	v_mfma_f32_16x16x32_bf16 v[70:73], v[152:155], v[222:225], v[70:73]
	v_mfma_f32_16x16x32_bf16 v[66:69], v[156:159], v[214:217], v[66:69]
	v_mfma_f32_16x16x32_bf16 v[66:69], v[160:163], v[222:225], v[66:69]
	s_setprio 0
	s_barrier
	s_add_i32 s43, s43, s62
	s_add_i32 m0, s43, 0xffffff80
	ds_read_b128 v[164:167], v211 offset:49152
	ds_read_b128 v[190:193], v211 offset:51200
	ds_read_b128 v[194:197], v212 offset:49152
	ds_read_b128 v[198:201], v212 offset:51200
	ds_read_b128 v[202:205], v211 offset:53248
	ds_read_b128 v[214:217], v211 offset:55296
	ds_read_b128 v[218:221], v212 offset:53248
	ds_read_b128 v[222:225], v212 offset:55296
	global_load_lds_dwordx4 v170, s[78:79] offset:128
	s_add_i32 m0, s43, 0x1f80
	s_add_u32 s44, s78, 0x18080
	s_addc_u32 s45, s79, 0
	s_add_i32 s43, s46, s62
	global_load_lds_dwordx4 v176, s[78:79] offset:128
	s_mov_b32 m0, s43
	s_nop 0
	global_load_lds_dwordx4 v170, s[44:45]
	s_add_i32 m0, s43, 0x2000
	s_nop 0
	global_load_lds_dwordx4 v176, s[44:45]
	s_add_i32 m0, s89, 0xffffff80
	s_nop 0
	global_load_lds_dwordx4 v172, s[80:81] offset:128
	s_add_i32 m0, s91, 0xffffff80
	s_nop 0
	global_load_lds_dwordx4 v174, s[80:81] offset:128
	s_waitcnt vmcnt(8)
	s_waitcnt lgkmcnt(0)
	s_barrier
	s_setprio 1
	s_waitcnt lgkmcnt(0)
	v_mfma_f32_16x16x32_bf16 v[62:65], v[132:135], v[164:167], v[62:65]
	v_mfma_f32_16x16x32_bf16 v[62:65], v[136:139], v[194:197], v[62:65]
	v_mfma_f32_16x16x32_bf16 v[58:61], v[140:143], v[164:167], v[58:61]
	v_mfma_f32_16x16x32_bf16 v[58:61], v[144:147], v[194:197], v[58:61]
	v_mfma_f32_16x16x32_bf16 v[46:49], v[132:135], v[190:193], v[46:49]
	v_mfma_f32_16x16x32_bf16 v[46:49], v[136:139], v[198:201], v[46:49]
	v_mfma_f32_16x16x32_bf16 v[42:45], v[140:143], v[190:193], v[42:45]
	v_mfma_f32_16x16x32_bf16 v[42:45], v[144:147], v[198:201], v[42:45]
	v_mfma_f32_16x16x32_bf16 v[30:33], v[132:135], v[202:205], v[30:33]
	v_mfma_f32_16x16x32_bf16 v[30:33], v[136:139], v[218:221], v[30:33]
	v_mfma_f32_16x16x32_bf16 v[26:29], v[140:143], v[202:205], v[26:29]
	v_mfma_f32_16x16x32_bf16 v[26:29], v[144:147], v[218:221], v[26:29]
	v_mfma_f32_16x16x32_bf16 v[14:17], v[132:135], v[214:217], v[14:17]
	v_mfma_f32_16x16x32_bf16 v[14:17], v[136:139], v[222:225], v[14:17]
	v_mfma_f32_16x16x32_bf16 v[10:13], v[140:143], v[214:217], v[10:13]
	v_mfma_f32_16x16x32_bf16 v[10:13], v[144:147], v[222:225], v[10:13]
	s_setprio 0
	s_setprio 1
	v_mfma_f32_16x16x32_bf16 v[54:57], v[148:151], v[164:167], v[54:57]
	v_mfma_f32_16x16x32_bf16 v[54:57], v[152:155], v[194:197], v[54:57]
	v_mfma_f32_16x16x32_bf16 v[50:53], v[156:159], v[164:167], v[50:53]
	v_mfma_f32_16x16x32_bf16 v[50:53], v[160:163], v[194:197], v[50:53]
	v_mfma_f32_16x16x32_bf16 v[38:41], v[148:151], v[190:193], v[38:41]
	v_mfma_f32_16x16x32_bf16 v[38:41], v[152:155], v[198:201], v[38:41]
	v_mfma_f32_16x16x32_bf16 v[34:37], v[156:159], v[190:193], v[34:37]
	v_mfma_f32_16x16x32_bf16 v[34:37], v[160:163], v[198:201], v[34:37]
	v_mfma_f32_16x16x32_bf16 v[22:25], v[148:151], v[202:205], v[22:25]
	v_mfma_f32_16x16x32_bf16 v[22:25], v[152:155], v[218:221], v[22:25]
	v_mfma_f32_16x16x32_bf16 v[18:21], v[156:159], v[202:205], v[18:21]
	v_mfma_f32_16x16x32_bf16 v[18:21], v[160:163], v[218:221], v[18:21]
	v_mfma_f32_16x16x32_bf16 v[6:9], v[148:151], v[214:217], v[6:9]
	v_mfma_f32_16x16x32_bf16 v[6:9], v[152:155], v[222:225], v[6:9]
	v_mfma_f32_16x16x32_bf16 v[2:5], v[156:159], v[214:217], v[2:5]
	v_mfma_f32_16x16x32_bf16 v[2:5], v[160:163], v[222:225], v[2:5]
	s_setprio 0
	s_barrier
	s_add_u32 s12, s12, 0x100
	s_addc_u32 s13, s13, 0
	s_add_u32 s48, s48, 0x100
	s_addc_u32 s72, s72, 0
	s_cmp_ge_i32 s42, s39
	s_cbranch_scc1 .LBB0_1320

.Lpeel_3:
	s_mov_b32 s100, 0
	ds_read_b128 v[132:135], v245
	ds_read_b128 v[136:139], v246
	ds_read_b128 v[140:143], v245 offset:2048
	ds_read_b128 v[144:147], v246 offset:2048
	ds_read_b128 v[148:151], v245 offset:16384
	ds_read_b128 v[152:155], v246 offset:16384
	ds_read_b128 v[156:159], v245 offset:18432
	ds_read_b128 v[160:163], v246 offset:18432
	s_add_i32 s42, s42, 2
	s_add_u32 s43, s12, 0xfffe8080
	s_addc_u32 s46, s13, -1
	s_and_b64 s[44:45], s[78:79], exec
	s_cselect_b32 s81, s75, s46
	s_cselect_b32 s80, s74, s43
	s_cselect_b32 s79, s77, s72
	s_cselect_b32 s78, s76, s48
	s_add_i32 m0, s63, 0xc000
	ds_read_b128 v[164:167], v211
	ds_read_b128 v[190:193], v211 offset:2048
	s_waitcnt lgkmcnt(0)
	ds_read_b128 v[194:197], v212
	ds_read_b128 v[198:201], v212 offset:2048
	ds_read_b128 v[202:205], v211 offset:4096
	ds_read_b128 v[214:217], v211 offset:6144
	ds_read_b128 v[218:221], v212 offset:4096
	ds_read_b128 v[222:225], v212 offset:6144
	global_load_lds_dwordx4 v178, s[12:13]
	s_add_i32 m0, s63, 0xe000
	s_nop 0
	global_load_lds_dwordx4 v182, s[12:13]
	s_waitcnt vmcnt(8)
	s_waitcnt lgkmcnt(0)
	s_barrier
	s_setprio 1
	s_waitcnt lgkmcnt(0)
	v_mfma_f32_16x16x32_bf16 v[126:129], v[132:135], v[164:167], 0
	v_mfma_f32_16x16x32_bf16 v[126:129], v[136:139], v[194:197], v[126:129]
	v_mfma_f32_16x16x32_bf16 v[122:125], v[140:143], v[164:167], 0
	v_mfma_f32_16x16x32_bf16 v[122:125], v[144:147], v[194:197], v[122:125]
	v_mfma_f32_16x16x32_bf16 v[110:113], v[132:135], v[190:193], 0
	v_mfma_f32_16x16x32_bf16 v[110:113], v[136:139], v[198:201], v[110:113]
	v_mfma_f32_16x16x32_bf16 v[106:109], v[140:143], v[190:193], 0
	v_mfma_f32_16x16x32_bf16 v[106:109], v[144:147], v[198:201], v[106:109]
	v_mfma_f32_16x16x32_bf16 v[94:97], v[132:135], v[202:205], 0
	v_mfma_f32_16x16x32_bf16 v[94:97], v[136:139], v[218:221], v[94:97]
	v_mfma_f32_16x16x32_bf16 v[90:93], v[140:143], v[202:205], 0
	v_mfma_f32_16x16x32_bf16 v[90:93], v[144:147], v[218:221], v[90:93]
	v_mfma_f32_16x16x32_bf16 v[78:81], v[132:135], v[214:217], 0
	v_mfma_f32_16x16x32_bf16 v[78:81], v[136:139], v[222:225], v[78:81]
	v_mfma_f32_16x16x32_bf16 v[74:77], v[140:143], v[214:217], 0
	v_mfma_f32_16x16x32_bf16 v[74:77], v[144:147], v[222:225], v[74:77]
	s_setprio 0
	s_setprio 1
	v_mfma_f32_16x16x32_bf16 v[118:121], v[148:151], v[164:167], 0
	v_mfma_f32_16x16x32_bf16 v[118:121], v[152:155], v[194:197], v[118:121]
	v_mfma_f32_16x16x32_bf16 v[114:117], v[156:159], v[164:167], 0
	v_mfma_f32_16x16x32_bf16 v[114:117], v[160:163], v[194:197], v[114:117]
	v_mfma_f32_16x16x32_bf16 v[102:105], v[148:151], v[190:193], 0
	v_mfma_f32_16x16x32_bf16 v[102:105], v[152:155], v[198:201], v[102:105]
	v_mfma_f32_16x16x32_bf16 v[98:101], v[156:159], v[190:193], 0
	v_mfma_f32_16x16x32_bf16 v[98:101], v[160:163], v[198:201], v[98:101]
	v_mfma_f32_16x16x32_bf16 v[86:89], v[148:151], v[202:205], 0
	v_mfma_f32_16x16x32_bf16 v[86:89], v[152:155], v[218:221], v[86:89]
	v_mfma_f32_16x16x32_bf16 v[82:85], v[156:159], v[202:205], 0
	v_mfma_f32_16x16x32_bf16 v[82:85], v[160:163], v[218:221], v[82:85]
	v_mfma_f32_16x16x32_bf16 v[70:73], v[148:151], v[214:217], 0
	v_mfma_f32_16x16x32_bf16 v[70:73], v[152:155], v[222:225], v[70:73]
	v_mfma_f32_16x16x32_bf16 v[66:69], v[156:159], v[214:217], 0
	v_mfma_f32_16x16x32_bf16 v[66:69], v[160:163], v[222:225], v[66:69]
	s_setprio 0
	s_barrier
	s_add_i32 s43, s96, s62
	s_mov_b32 m0, s43
	ds_read_b128 v[164:167], v211 offset:16384
	ds_read_b128 v[190:193], v211 offset:18432
	ds_read_b128 v[194:197], v212 offset:16384
	ds_read_b128 v[198:201], v212 offset:18432
	ds_read_b128 v[202:205], v211 offset:20480
	ds_read_b128 v[214:217], v211 offset:22528
	ds_read_b128 v[218:221], v212 offset:20480
	ds_read_b128 v[222:225], v212 offset:22528
	global_load_lds_dwordx4 v170, s[78:79]
	s_add_i32 m0, s43, 0x2000
	s_add_u32 s44, s78, 0x18000
	s_addc_u32 s45, s79, 0
	s_add_i32 s43, s83, s62
	global_load_lds_dwordx4 v176, s[78:79]
	s_mov_b32 m0, s43
	s_nop 0
	global_load_lds_dwordx4 v170, s[44:45]
	s_add_i32 m0, s43, 0x2000
	s_nop 0
	global_load_lds_dwordx4 v176, s[44:45]
	s_mov_b32 m0, s63
	s_nop 0
	global_load_lds_dwordx4 v172, s[80:81]
	s_mov_b32 m0, s64
	s_nop 0
	global_load_lds_dwordx4 v174, s[80:81]
	s_waitcnt vmcnt(8)
	s_waitcnt lgkmcnt(0)
	s_barrier
	s_setprio 1
	s_waitcnt lgkmcnt(0)
	v_mfma_f32_16x16x32_bf16 v[62:65], v[132:135], v[164:167], 0
	v_mfma_f32_16x16x32_bf16 v[62:65], v[136:139], v[194:197], v[62:65]
	v_mfma_f32_16x16x32_bf16 v[58:61], v[140:143], v[164:167], 0
	v_mfma_f32_16x16x32_bf16 v[58:61], v[144:147], v[194:197], v[58:61]
	v_mfma_f32_16x16x32_bf16 v[46:49], v[132:135], v[190:193], 0
	v_mfma_f32_16x16x32_bf16 v[46:49], v[136:139], v[198:201], v[46:49]
	v_mfma_f32_16x16x32_bf16 v[42:45], v[140:143], v[190:193], 0
	v_mfma_f32_16x16x32_bf16 v[42:45], v[144:147], v[198:201], v[42:45]
	v_mfma_f32_16x16x32_bf16 v[30:33], v[132:135], v[202:205], 0
	v_mfma_f32_16x16x32_bf16 v[30:33], v[136:139], v[218:221], v[30:33]
	v_mfma_f32_16x16x32_bf16 v[26:29], v[140:143], v[202:205], 0
	v_mfma_f32_16x16x32_bf16 v[26:29], v[144:147], v[218:221], v[26:29]
	v_mfma_f32_16x16x32_bf16 v[14:17], v[132:135], v[214:217], 0
	v_mfma_f32_16x16x32_bf16 v[14:17], v[136:139], v[222:225], v[14:17]
	v_mfma_f32_16x16x32_bf16 v[10:13], v[140:143], v[214:217], 0
	v_mfma_f32_16x16x32_bf16 v[10:13], v[144:147], v[222:225], v[10:13]
	s_setprio 0
	s_setprio 1
	v_mfma_f32_16x16x32_bf16 v[54:57], v[148:151], v[164:167], 0
	v_mfma_f32_16x16x32_bf16 v[54:57], v[152:155], v[194:197], v[54:57]
	v_mfma_f32_16x16x32_bf16 v[50:53], v[156:159], v[164:167], 0
	v_mfma_f32_16x16x32_bf16 v[50:53], v[160:163], v[194:197], v[50:53]
	v_mfma_f32_16x16x32_bf16 v[38:41], v[148:151], v[190:193], 0
	v_mfma_f32_16x16x32_bf16 v[38:41], v[152:155], v[198:201], v[38:41]
	v_mfma_f32_16x16x32_bf16 v[34:37], v[156:159], v[190:193], 0
	v_mfma_f32_16x16x32_bf16 v[34:37], v[160:163], v[198:201], v[34:37]
	v_mfma_f32_16x16x32_bf16 v[22:25], v[148:151], v[202:205], 0
	v_mfma_f32_16x16x32_bf16 v[22:25], v[152:155], v[218:221], v[22:25]
	v_mfma_f32_16x16x32_bf16 v[18:21], v[156:159], v[202:205], 0
	v_mfma_f32_16x16x32_bf16 v[18:21], v[160:163], v[218:221], v[18:21]
	v_mfma_f32_16x16x32_bf16 v[6:9], v[148:151], v[214:217], 0
	v_mfma_f32_16x16x32_bf16 v[6:9], v[152:155], v[222:225], v[6:9]
	v_mfma_f32_16x16x32_bf16 v[2:5], v[156:159], v[214:217], 0
	v_mfma_f32_16x16x32_bf16 v[2:5], v[160:163], v[222:225], v[2:5]
	s_setprio 0
	s_barrier
	s_add_i32 s43, 0, 0x18000
	s_add_i32 s46, 0, 0x1c000
	ds_read_b128 v[132:135], v245 offset:32768
	ds_read_b128 v[136:139], v246 offset:32768
	ds_read_b128 v[140:143], v245 offset:34816
	ds_read_b128 v[144:147], v246 offset:34816
	ds_read_b128 v[148:151], v245 offset:49152
	ds_read_b128 v[152:155], v246 offset:49152
	ds_read_b128 v[156:159], v245 offset:51200
	ds_read_b128 v[160:163], v246 offset:51200
	s_add_u32 s44, s80, 0x18000
	s_addc_u32 s45, s81, 0
	s_mov_b32 m0, s65
	ds_read_b128 v[164:167], v211 offset:32768
	ds_read_b128 v[190:193], v211 offset:34816
	ds_read_b128 v[194:197], v212 offset:32768
	ds_read_b128 v[198:201], v212 offset:34816
	ds_read_b128 v[202:205], v211 offset:36864
	ds_read_b128 v[214:217], v211 offset:38912
	ds_read_b128 v[218:221], v212 offset:36864
	ds_read_b128 v[222:225], v212 offset:38912
	global_load_lds_dwordx4 v172, s[44:45]
	s_mov_b32 m0, s82
	s_nop 0
	global_load_lds_dwordx4 v174, s[44:45]
	s_waitcnt vmcnt(8)
	s_waitcnt lgkmcnt(0)
	s_barrier
	s_setprio 1
	s_waitcnt lgkmcnt(0)
	v_mfma_f32_16x16x32_bf16 v[126:129], v[132:135], v[164:167], v[126:129]
	v_mfma_f32_16x16x32_bf16 v[126:129], v[136:139], v[194:197], v[126:129]
	v_mfma_f32_16x16x32_bf16 v[122:125], v[140:143], v[164:167], v[122:125]
	v_mfma_f32_16x16x32_bf16 v[122:125], v[144:147], v[194:197], v[122:125]
	v_mfma_f32_16x16x32_bf16 v[110:113], v[132:135], v[190:193], v[110:113]
	v_mfma_f32_16x16x32_bf16 v[110:113], v[136:139], v[198:201], v[110:113]
	v_mfma_f32_16x16x32_bf16 v[106:109], v[140:143], v[190:193], v[106:109]
	v_mfma_f32_16x16x32_bf16 v[106:109], v[144:147], v[198:201], v[106:109]
	v_mfma_f32_16x16x32_bf16 v[94:97], v[132:135], v[202:205], v[94:97]
	v_mfma_f32_16x16x32_bf16 v[94:97], v[136:139], v[218:221], v[94:97]
	v_mfma_f32_16x16x32_bf16 v[90:93], v[140:143], v[202:205], v[90:93]
	v_mfma_f32_16x16x32_bf16 v[90:93], v[144:147], v[218:221], v[90:93]
	v_mfma_f32_16x16x32_bf16 v[78:81], v[132:135], v[214:217], v[78:81]
	v_mfma_f32_16x16x32_bf16 v[78:81], v[136:139], v[222:225], v[78:81]
	v_mfma_f32_16x16x32_bf16 v[74:77], v[140:143], v[214:217], v[74:77]
	v_mfma_f32_16x16x32_bf16 v[74:77], v[144:147], v[222:225], v[74:77]
	s_setprio 0
	s_setprio 1
	v_mfma_f32_16x16x32_bf16 v[118:121], v[148:151], v[164:167], v[118:121]
	v_mfma_f32_16x16x32_bf16 v[118:121], v[152:155], v[194:197], v[118:121]
	v_mfma_f32_16x16x32_bf16 v[114:117], v[156:159], v[164:167], v[114:117]
	v_mfma_f32_16x16x32_bf16 v[114:117], v[160:163], v[194:197], v[114:117]
	v_mfma_f32_16x16x32_bf16 v[102:105], v[148:151], v[190:193], v[102:105]
	v_mfma_f32_16x16x32_bf16 v[102:105], v[152:155], v[198:201], v[102:105]
	v_mfma_f32_16x16x32_bf16 v[98:101], v[156:159], v[190:193], v[98:101]
	v_mfma_f32_16x16x32_bf16 v[98:101], v[160:163], v[198:201], v[98:101]
	v_mfma_f32_16x16x32_bf16 v[86:89], v[148:151], v[202:205], v[86:89]
	v_mfma_f32_16x16x32_bf16 v[86:89], v[152:155], v[218:221], v[86:89]
	v_mfma_f32_16x16x32_bf16 v[82:85], v[156:159], v[202:205], v[82:85]
	v_mfma_f32_16x16x32_bf16 v[82:85], v[160:163], v[218:221], v[82:85]
	v_mfma_f32_16x16x32_bf16 v[70:73], v[148:151], v[214:217], v[70:73]
	v_mfma_f32_16x16x32_bf16 v[70:73], v[152:155], v[222:225], v[70:73]
	v_mfma_f32_16x16x32_bf16 v[66:69], v[156:159], v[214:217], v[66:69]
	v_mfma_f32_16x16x32_bf16 v[66:69], v[160:163], v[222:225], v[66:69]
	s_setprio 0
	s_barrier
	s_add_i32 s43, s43, s62
	s_add_i32 m0, s43, 0xffffff80
	ds_read_b128 v[164:167], v211 offset:49152
	ds_read_b128 v[190:193], v211 offset:51200
	ds_read_b128 v[194:197], v212 offset:49152
	ds_read_b128 v[198:201], v212 offset:51200
	ds_read_b128 v[202:205], v211 offset:53248
	ds_read_b128 v[214:217], v211 offset:55296
	ds_read_b128 v[218:221], v212 offset:53248
	ds_read_b128 v[222:225], v212 offset:55296
	global_load_lds_dwordx4 v170, s[78:79] offset:128
	s_add_i32 m0, s43, 0x1f80
	s_add_u32 s44, s78, 0x18080
	s_addc_u32 s45, s79, 0
	s_add_i32 s43, s46, s62
	global_load_lds_dwordx4 v176, s[78:79] offset:128
	s_mov_b32 m0, s43
	s_nop 0
	global_load_lds_dwordx4 v170, s[44:45]
	s_add_i32 m0, s43, 0x2000
	s_nop 0
	global_load_lds_dwordx4 v176, s[44:45]
	s_add_i32 m0, s89, 0xffffff80
	s_nop 0
	global_load_lds_dwordx4 v172, s[80:81] offset:128
	s_add_i32 m0, s91, 0xffffff80
	s_nop 0
	global_load_lds_dwordx4 v174, s[80:81] offset:128
	s_waitcnt vmcnt(8)
	s_waitcnt lgkmcnt(0)
	s_barrier
	s_setprio 1
	s_waitcnt lgkmcnt(0)
	v_mfma_f32_16x16x32_bf16 v[62:65], v[132:135], v[164:167], v[62:65]
	v_mfma_f32_16x16x32_bf16 v[62:65], v[136:139], v[194:197], v[62:65]
	v_mfma_f32_16x16x32_bf16 v[58:61], v[140:143], v[164:167], v[58:61]
	v_mfma_f32_16x16x32_bf16 v[58:61], v[144:147], v[194:197], v[58:61]
	v_mfma_f32_16x16x32_bf16 v[46:49], v[132:135], v[190:193], v[46:49]
	v_mfma_f32_16x16x32_bf16 v[46:49], v[136:139], v[198:201], v[46:49]
	v_mfma_f32_16x16x32_bf16 v[42:45], v[140:143], v[190:193], v[42:45]
	v_mfma_f32_16x16x32_bf16 v[42:45], v[144:147], v[198:201], v[42:45]
	v_mfma_f32_16x16x32_bf16 v[30:33], v[132:135], v[202:205], v[30:33]
	v_mfma_f32_16x16x32_bf16 v[30:33], v[136:139], v[218:221], v[30:33]
	v_mfma_f32_16x16x32_bf16 v[26:29], v[140:143], v[202:205], v[26:29]
	v_mfma_f32_16x16x32_bf16 v[26:29], v[144:147], v[218:221], v[26:29]
	v_mfma_f32_16x16x32_bf16 v[14:17], v[132:135], v[214:217], v[14:17]
	v_mfma_f32_16x16x32_bf16 v[14:17], v[136:139], v[222:225], v[14:17]
	v_mfma_f32_16x16x32_bf16 v[10:13], v[140:143], v[214:217], v[10:13]
	v_mfma_f32_16x16x32_bf16 v[10:13], v[144:147], v[222:225], v[10:13]
	s_setprio 0
	s_setprio 1
	v_mfma_f32_16x16x32_bf16 v[54:57], v[148:151], v[164:167], v[54:57]
	v_mfma_f32_16x16x32_bf16 v[54:57], v[152:155], v[194:197], v[54:57]
	v_mfma_f32_16x16x32_bf16 v[50:53], v[156:159], v[164:167], v[50:53]
	v_mfma_f32_16x16x32_bf16 v[50:53], v[160:163], v[194:197], v[50:53]
	v_mfma_f32_16x16x32_bf16 v[38:41], v[148:151], v[190:193], v[38:41]
	v_mfma_f32_16x16x32_bf16 v[38:41], v[152:155], v[198:201], v[38:41]
	v_mfma_f32_16x16x32_bf16 v[34:37], v[156:159], v[190:193], v[34:37]
	v_mfma_f32_16x16x32_bf16 v[34:37], v[160:163], v[198:201], v[34:37]
	v_mfma_f32_16x16x32_bf16 v[22:25], v[148:151], v[202:205], v[22:25]
	v_mfma_f32_16x16x32_bf16 v[22:25], v[152:155], v[218:221], v[22:25]
	v_mfma_f32_16x16x32_bf16 v[18:21], v[156:159], v[202:205], v[18:21]
	v_mfma_f32_16x16x32_bf16 v[18:21], v[160:163], v[218:221], v[18:21]
	v_mfma_f32_16x16x32_bf16 v[6:9], v[148:151], v[214:217], v[6:9]
	v_mfma_f32_16x16x32_bf16 v[6:9], v[152:155], v[222:225], v[6:9]
	v_mfma_f32_16x16x32_bf16 v[2:5], v[156:159], v[214:217], v[2:5]
	v_mfma_f32_16x16x32_bf16 v[2:5], v[160:163], v[222:225], v[2:5]
	s_setprio 0
	s_barrier
	s_add_u32 s12, s12, 0x100
	s_addc_u32 s13, s13, 0
	s_add_u32 s48, s48, 0x100
	s_addc_u32 s72, s72, 0
	s_cmp_ge_i32 s42, s39
	s_cbranch_scc1 .LBB0_1320
	s_branch .LBB0_1317

.LBB0_1629:
	s_cmp_lg_u32 s100, 0
	s_cbranch_scc1 .Lpeel_4
	ds_read_b128 v[90:93], v211
	ds_read_b128 v[102:105], v212
	ds_read_b128 v[114:117], v213
	ds_read_b128 v[126:129], v214
	ds_read_b128 v[138:141], v215
	ds_read_b128 v[150:153], v216
	ds_read_b128 v[154:157], v217
	ds_read_b128 v[158:161], v218
	s_add_u32 s26, s24, 0xfffc0080
	s_addc_u32 s27, s25, -1
	s_cmp_eq_u32 s57, 12
	s_cselect_b32 s29, s15, s27
	s_cselect_b32 s28, s21, s26
	s_cselect_b32 s27, s13, s56
	s_cselect_b32 s26, s23, s55
	s_add_i32 m0, s41, 0xc000
	ds_read_b128 v[162:165], v219
	ds_read_b128 v[166:169], v219 offset:2048
	ds_read_b128 v[170:173], v220
	ds_read_b128 v[174:177], v220 offset:2048
	ds_read_b128 v[178:181], v219 offset:4096
	ds_read_b128 v[182:185], v219 offset:6144
	ds_read_b128 v[204:207], v220 offset:4096
	ds_read_b128 v[226:229], v220 offset:6144
	global_load_lds_dwordx4 v196, s[24:25]
	s_add_i32 m0, s41, 0xe000
	s_nop 0
	global_load_lds_dwordx4 v198, s[24:25]
	s_waitcnt vmcnt(8)
	s_waitcnt lgkmcnt(0)
	s_barrier
	s_setprio 1
	s_waitcnt lgkmcnt(0)
	v_mfma_f32_16x16x32_bf16 v[146:149], v[90:93], v[162:165], v[146:149]
	v_mfma_f32_16x16x32_bf16 v[146:149], v[102:105], v[170:173], v[146:149]
	v_mfma_f32_16x16x32_bf16 v[142:145], v[114:117], v[162:165], v[142:145]
	v_mfma_f32_16x16x32_bf16 v[142:145], v[126:129], v[170:173], v[142:145]
	v_mfma_f32_16x16x32_bf16 v[122:125], v[90:93], v[166:169], v[122:125]
	v_mfma_f32_16x16x32_bf16 v[122:125], v[102:105], v[174:177], v[122:125]
	v_mfma_f32_16x16x32_bf16 v[118:121], v[114:117], v[166:169], v[118:121]
	v_mfma_f32_16x16x32_bf16 v[118:121], v[126:129], v[174:177], v[118:121]
	v_mfma_f32_16x16x32_bf16 v[98:101], v[90:93], v[178:181], v[98:101]
	v_mfma_f32_16x16x32_bf16 v[98:101], v[102:105], v[204:207], v[98:101]
	v_mfma_f32_16x16x32_bf16 v[94:97], v[114:117], v[178:181], v[94:97]
	v_mfma_f32_16x16x32_bf16 v[94:97], v[126:129], v[204:207], v[94:97]
	v_mfma_f32_16x16x32_bf16 v[78:81], v[90:93], v[182:185], v[78:81]
	v_mfma_f32_16x16x32_bf16 v[78:81], v[102:105], v[226:229], v[78:81]
	v_mfma_f32_16x16x32_bf16 v[74:77], v[114:117], v[182:185], v[74:77]
	v_mfma_f32_16x16x32_bf16 v[74:77], v[126:129], v[226:229], v[74:77]
	s_setprio 0
	s_setprio 1
	v_mfma_f32_16x16x32_bf16 v[134:137], v[138:141], v[162:165], v[134:137]
	v_mfma_f32_16x16x32_bf16 v[134:137], v[150:153], v[170:173], v[134:137]
	v_mfma_f32_16x16x32_bf16 v[130:133], v[154:157], v[162:165], v[130:133]
	v_mfma_f32_16x16x32_bf16 v[130:133], v[158:161], v[170:173], v[130:133]
	v_mfma_f32_16x16x32_bf16 v[110:113], v[138:141], v[166:169], v[110:113]
	v_mfma_f32_16x16x32_bf16 v[110:113], v[150:153], v[174:177], v[110:113]
	v_mfma_f32_16x16x32_bf16 v[106:109], v[154:157], v[166:169], v[106:109]
	v_mfma_f32_16x16x32_bf16 v[106:109], v[158:161], v[174:177], v[106:109]
	v_mfma_f32_16x16x32_bf16 v[86:89], v[138:141], v[178:181], v[86:89]
	v_mfma_f32_16x16x32_bf16 v[86:89], v[150:153], v[204:207], v[86:89]
	v_mfma_f32_16x16x32_bf16 v[82:85], v[154:157], v[178:181], v[82:85]
	v_mfma_f32_16x16x32_bf16 v[82:85], v[158:161], v[204:207], v[82:85]
	v_mfma_f32_16x16x32_bf16 v[70:73], v[138:141], v[182:185], v[70:73]
	v_mfma_f32_16x16x32_bf16 v[70:73], v[150:153], v[226:229], v[70:73]
	v_mfma_f32_16x16x32_bf16 v[66:69], v[154:157], v[182:185], v[66:69]
	v_mfma_f32_16x16x32_bf16 v[66:69], v[158:161], v[226:229], v[66:69]
	s_setprio 0
	s_barrier
	s_add_i32 s58, s53, s40
	s_mov_b32 m0, s58
	ds_read_b128 v[162:165], v219 offset:16384
	ds_read_b128 v[166:169], v219 offset:18432
	ds_read_b128 v[170:173], v220 offset:16384
	ds_read_b128 v[174:177], v220 offset:18432
	ds_read_b128 v[178:181], v219 offset:20480
	ds_read_b128 v[182:185], v219 offset:22528
	ds_read_b128 v[204:207], v220 offset:20480
	ds_read_b128 v[226:229], v220 offset:22528
	global_load_lds_dwordx4 v188, s[26:27]
	s_add_i32 m0, s58, 0x2000
	s_add_u32 s58, s26, 0x40000
	s_addc_u32 s59, s27, 0
	s_add_i32 s60, s54, s40
	global_load_lds_dwordx4 v192, s[26:27]
	s_mov_b32 m0, s60
	s_mov_b64 s[98:99], s[28:29]
	global_load_lds_dwordx4 v188, s[58:59]
	s_add_i32 m0, s60, 0x2000
	s_nop 0
	global_load_lds_dwordx4 v192, s[58:59]
	s_mov_b32 m0, s41
	s_nop 0
	global_load_lds_dwordx4 v186, s[28:29]
	s_mov_b32 m0, s42
	s_nop 0
	global_load_lds_dwordx4 v190, s[28:29]
	s_waitcnt vmcnt(8)
	s_waitcnt lgkmcnt(0)
	s_barrier
	s_setprio 1
	s_waitcnt lgkmcnt(0)
	v_mfma_f32_16x16x32_bf16 v[62:65], v[90:93], v[162:165], v[62:65]
	v_mfma_f32_16x16x32_bf16 v[62:65], v[102:105], v[170:173], v[62:65]
	v_mfma_f32_16x16x32_bf16 v[58:61], v[114:117], v[162:165], v[58:61]
	v_mfma_f32_16x16x32_bf16 v[58:61], v[126:129], v[170:173], v[58:61]
	v_mfma_f32_16x16x32_bf16 v[46:49], v[90:93], v[166:169], v[46:49]
	v_mfma_f32_16x16x32_bf16 v[46:49], v[102:105], v[174:177], v[46:49]
	v_mfma_f32_16x16x32_bf16 v[42:45], v[114:117], v[166:169], v[42:45]
	v_mfma_f32_16x16x32_bf16 v[42:45], v[126:129], v[174:177], v[42:45]
	v_mfma_f32_16x16x32_bf16 v[30:33], v[90:93], v[178:181], v[30:33]
	v_mfma_f32_16x16x32_bf16 v[30:33], v[102:105], v[204:207], v[30:33]
	v_mfma_f32_16x16x32_bf16 v[26:29], v[114:117], v[178:181], v[26:29]
	v_mfma_f32_16x16x32_bf16 v[26:29], v[126:129], v[204:207], v[26:29]
	v_mfma_f32_16x16x32_bf16 v[14:17], v[90:93], v[182:185], v[14:17]
	v_mfma_f32_16x16x32_bf16 v[14:17], v[102:105], v[226:229], v[14:17]
	v_mfma_f32_16x16x32_bf16 v[10:13], v[114:117], v[182:185], v[10:13]
	v_mfma_f32_16x16x32_bf16 v[10:13], v[126:129], v[226:229], v[10:13]
	s_setprio 0
	s_setprio 1
	v_mfma_f32_16x16x32_bf16 v[54:57], v[138:141], v[162:165], v[54:57]
	v_mfma_f32_16x16x32_bf16 v[54:57], v[150:153], v[170:173], v[54:57]
	v_mfma_f32_16x16x32_bf16 v[50:53], v[154:157], v[162:165], v[50:53]
	v_mfma_f32_16x16x32_bf16 v[50:53], v[158:161], v[170:173], v[50:53]
	v_mfma_f32_16x16x32_bf16 v[38:41], v[138:141], v[166:169], v[38:41]
	v_mfma_f32_16x16x32_bf16 v[38:41], v[150:153], v[174:177], v[38:41]
	v_mfma_f32_16x16x32_bf16 v[34:37], v[154:157], v[166:169], v[34:37]
	v_mfma_f32_16x16x32_bf16 v[34:37], v[158:161], v[174:177], v[34:37]
	v_mfma_f32_16x16x32_bf16 v[22:25], v[138:141], v[178:181], v[22:25]
	v_mfma_f32_16x16x32_bf16 v[22:25], v[150:153], v[204:207], v[22:25]
	v_mfma_f32_16x16x32_bf16 v[18:21], v[154:157], v[178:181], v[18:21]
	v_mfma_f32_16x16x32_bf16 v[18:21], v[158:161], v[204:207], v[18:21]
	v_mfma_f32_16x16x32_bf16 v[6:9], v[138:141], v[182:185], v[6:9]
	v_mfma_f32_16x16x32_bf16 v[6:9], v[150:153], v[226:229], v[6:9]
	v_mfma_f32_16x16x32_bf16 v[2:5], v[154:157], v[182:185], v[2:5]
	v_mfma_f32_16x16x32_bf16 v[2:5], v[158:161], v[226:229], v[2:5]
	s_setprio 0
	s_barrier
	s_add_i32 s58, 0, 0x18000
	s_add_i32 s59, 0, 0x1c000
	ds_read_b128 v[90:93], v245 offset:32768
	ds_read_b128 v[102:105], v246 offset:32768
	ds_read_b128 v[114:117], v221
	ds_read_b128 v[126:129], v222
	ds_read_b128 v[138:141], v245 offset:49152
	ds_read_b128 v[150:153], v246 offset:49152
	ds_read_b128 v[154:157], v223
	ds_read_b128 v[158:161], v224
	s_add_u32 s28, s28, 0x40000
	s_addc_u32 s29, s29, 0
	s_mov_b32 m0, s43
	ds_read_b128 v[162:165], v219 offset:32768
	ds_read_b128 v[166:169], v219 offset:34816
	ds_read_b128 v[170:173], v220 offset:32768
	ds_read_b128 v[174:177], v220 offset:34816
	ds_read_b128 v[178:181], v219 offset:36864
	ds_read_b128 v[182:185], v219 offset:38912
	ds_read_b128 v[204:207], v220 offset:36864
	ds_read_b128 v[226:229], v220 offset:38912
	global_load_lds_dwordx4 v186, s[28:29]
	s_mov_b32 m0, s44
	s_nop 0
	global_load_lds_dwordx4 v190, s[28:29]
	s_waitcnt vmcnt(8)
	s_waitcnt lgkmcnt(0)
	s_barrier
	s_setprio 1
	s_waitcnt lgkmcnt(0)
	v_mfma_f32_16x16x32_bf16 v[146:149], v[90:93], v[162:165], v[146:149]
	v_mfma_f32_16x16x32_bf16 v[146:149], v[102:105], v[170:173], v[146:149]
	v_mfma_f32_16x16x32_bf16 v[142:145], v[114:117], v[162:165], v[142:145]
	v_mfma_f32_16x16x32_bf16 v[142:145], v[126:129], v[170:173], v[142:145]
	v_mfma_f32_16x16x32_bf16 v[122:125], v[90:93], v[166:169], v[122:125]
	v_mfma_f32_16x16x32_bf16 v[122:125], v[102:105], v[174:177], v[122:125]
	v_mfma_f32_16x16x32_bf16 v[118:121], v[114:117], v[166:169], v[118:121]
	v_mfma_f32_16x16x32_bf16 v[118:121], v[126:129], v[174:177], v[118:121]
	v_mfma_f32_16x16x32_bf16 v[98:101], v[90:93], v[178:181], v[98:101]
	v_mfma_f32_16x16x32_bf16 v[98:101], v[102:105], v[204:207], v[98:101]
	v_mfma_f32_16x16x32_bf16 v[94:97], v[114:117], v[178:181], v[94:97]
	v_mfma_f32_16x16x32_bf16 v[94:97], v[126:129], v[204:207], v[94:97]
	v_mfma_f32_16x16x32_bf16 v[78:81], v[90:93], v[182:185], v[78:81]
	v_mfma_f32_16x16x32_bf16 v[78:81], v[102:105], v[226:229], v[78:81]
	v_mfma_f32_16x16x32_bf16 v[74:77], v[114:117], v[182:185], v[74:77]
	v_mfma_f32_16x16x32_bf16 v[74:77], v[126:129], v[226:229], v[74:77]
	s_setprio 0
	s_setprio 1
	v_mfma_f32_16x16x32_bf16 v[134:137], v[138:141], v[162:165], v[134:137]
	v_mfma_f32_16x16x32_bf16 v[134:137], v[150:153], v[170:173], v[134:137]
	v_mfma_f32_16x16x32_bf16 v[130:133], v[154:157], v[162:165], v[130:133]
	v_mfma_f32_16x16x32_bf16 v[130:133], v[158:161], v[170:173], v[130:133]
	v_mfma_f32_16x16x32_bf16 v[110:113], v[138:141], v[166:169], v[110:113]
	v_mfma_f32_16x16x32_bf16 v[110:113], v[150:153], v[174:177], v[110:113]
	v_mfma_f32_16x16x32_bf16 v[106:109], v[154:157], v[166:169], v[106:109]
	v_mfma_f32_16x16x32_bf16 v[106:109], v[158:161], v[174:177], v[106:109]
	v_mfma_f32_16x16x32_bf16 v[86:89], v[138:141], v[178:181], v[86:89]
	v_mfma_f32_16x16x32_bf16 v[86:89], v[150:153], v[204:207], v[86:89]
	v_mfma_f32_16x16x32_bf16 v[82:85], v[154:157], v[178:181], v[82:85]
	v_mfma_f32_16x16x32_bf16 v[82:85], v[158:161], v[204:207], v[82:85]
	v_mfma_f32_16x16x32_bf16 v[70:73], v[138:141], v[182:185], v[70:73]
	v_mfma_f32_16x16x32_bf16 v[70:73], v[150:153], v[226:229], v[70:73]
	v_mfma_f32_16x16x32_bf16 v[66:69], v[154:157], v[182:185], v[66:69]
	v_mfma_f32_16x16x32_bf16 v[66:69], v[158:161], v[226:229], v[66:69]
	s_setprio 0
	s_barrier
	s_add_i32 s28, s58, s40
	s_add_i32 m0, s28, 0xffffff80
	ds_read_b128 v[162:165], v219 offset:49152
	ds_read_b128 v[166:169], v219 offset:51200
	ds_read_b128 v[170:173], v220 offset:49152
	ds_read_b128 v[174:177], v220 offset:51200
	ds_read_b128 v[178:181], v219 offset:53248
	ds_read_b128 v[182:185], v219 offset:55296
	ds_read_b128 v[204:207], v220 offset:53248
	ds_read_b128 v[226:229], v220 offset:55296
	global_load_lds_dwordx4 v188, s[26:27] offset:128
	s_add_i32 m0, s28, 0x1f80
	s_add_i32 s28, s59, s40
	global_load_lds_dwordx4 v192, s[26:27] offset:128
	s_add_u32 s26, s26, 0x40080
	s_addc_u32 s27, s27, 0
	s_mov_b32 m0, s28
	s_nop 0
	global_load_lds_dwordx4 v188, s[26:27]
	s_add_i32 m0, s28, 0x2000
	s_nop 0
	global_load_lds_dwordx4 v192, s[26:27]
	s_add_i32 m0, s48, 0xffffff80
	s_nop 0
	global_load_lds_dwordx4 v186, s[98:99] offset:128
	s_add_i32 m0, s49, 0xffffff80
	s_nop 0
	global_load_lds_dwordx4 v190, s[98:99] offset:128
	s_waitcnt vmcnt(8)
	s_waitcnt lgkmcnt(0)
	s_barrier
	s_setprio 1
	s_waitcnt lgkmcnt(0)
	v_mfma_f32_16x16x32_bf16 v[62:65], v[90:93], v[162:165], v[62:65]
	v_mfma_f32_16x16x32_bf16 v[62:65], v[102:105], v[170:173], v[62:65]
	v_mfma_f32_16x16x32_bf16 v[58:61], v[114:117], v[162:165], v[58:61]
	v_mfma_f32_16x16x32_bf16 v[58:61], v[126:129], v[170:173], v[58:61]
	v_mfma_f32_16x16x32_bf16 v[46:49], v[90:93], v[166:169], v[46:49]
	v_mfma_f32_16x16x32_bf16 v[46:49], v[102:105], v[174:177], v[46:49]
	v_mfma_f32_16x16x32_bf16 v[42:45], v[114:117], v[166:169], v[42:45]
	v_mfma_f32_16x16x32_bf16 v[42:45], v[126:129], v[174:177], v[42:45]
	v_mfma_f32_16x16x32_bf16 v[30:33], v[90:93], v[178:181], v[30:33]
	v_mfma_f32_16x16x32_bf16 v[30:33], v[102:105], v[204:207], v[30:33]
	v_mfma_f32_16x16x32_bf16 v[26:29], v[114:117], v[178:181], v[26:29]
	v_mfma_f32_16x16x32_bf16 v[26:29], v[126:129], v[204:207], v[26:29]
	v_mfma_f32_16x16x32_bf16 v[14:17], v[90:93], v[182:185], v[14:17]
	v_mfma_f32_16x16x32_bf16 v[14:17], v[102:105], v[226:229], v[14:17]
	v_mfma_f32_16x16x32_bf16 v[10:13], v[114:117], v[182:185], v[10:13]
	v_mfma_f32_16x16x32_bf16 v[10:13], v[126:129], v[226:229], v[10:13]
	s_setprio 0
	s_setprio 1
	v_mfma_f32_16x16x32_bf16 v[54:57], v[138:141], v[162:165], v[54:57]
	v_mfma_f32_16x16x32_bf16 v[54:57], v[150:153], v[170:173], v[54:57]
	v_mfma_f32_16x16x32_bf16 v[50:53], v[154:157], v[162:165], v[50:53]
	v_mfma_f32_16x16x32_bf16 v[50:53], v[158:161], v[170:173], v[50:53]
	v_mfma_f32_16x16x32_bf16 v[38:41], v[138:141], v[166:169], v[38:41]
	v_mfma_f32_16x16x32_bf16 v[38:41], v[150:153], v[174:177], v[38:41]
	v_mfma_f32_16x16x32_bf16 v[34:37], v[154:157], v[166:169], v[34:37]
	v_mfma_f32_16x16x32_bf16 v[34:37], v[158:161], v[174:177], v[34:37]
	v_mfma_f32_16x16x32_bf16 v[22:25], v[138:141], v[178:181], v[22:25]
	v_mfma_f32_16x16x32_bf16 v[22:25], v[150:153], v[204:207], v[22:25]
	v_mfma_f32_16x16x32_bf16 v[18:21], v[154:157], v[178:181], v[18:21]
	v_mfma_f32_16x16x32_bf16 v[18:21], v[158:161], v[204:207], v[18:21]
	v_mfma_f32_16x16x32_bf16 v[6:9], v[138:141], v[182:185], v[6:9]
	v_mfma_f32_16x16x32_bf16 v[6:9], v[150:153], v[226:229], v[6:9]
	v_mfma_f32_16x16x32_bf16 v[2:5], v[154:157], v[182:185], v[2:5]
	v_mfma_f32_16x16x32_bf16 v[2:5], v[158:161], v[226:229], v[2:5]
	s_setprio 0
	s_barrier
	s_add_i32 s57, s57, 2
	s_add_u32 s24, s24, 0x100
	s_addc_u32 s25, s25, 0
	s_add_u32 s55, s55, 0x100
	s_addc_u32 s56, s56, 0
	s_cmp_gt_u32 s57, 13
	s_cbranch_scc0 .LBB0_1629
	s_branch .Lpx_4
.Lpeel_4:
	s_mov_b32 s100, 0
	ds_read_b128 v[90:93], v211
	ds_read_b128 v[102:105], v212
	ds_read_b128 v[114:117], v213
	ds_read_b128 v[126:129], v214
	ds_read_b128 v[138:141], v215
	ds_read_b128 v[150:153], v216
	ds_read_b128 v[154:157], v217
	ds_read_b128 v[158:161], v218
	s_add_u32 s26, s24, 0xfffc0080
	s_addc_u32 s27, s25, -1
	s_cmp_eq_u32 s57, 12
	s_cselect_b32 s29, s15, s27
	s_cselect_b32 s28, s21, s26
	s_cselect_b32 s27, s13, s56
	s_cselect_b32 s26, s23, s55
	s_add_i32 m0, s41, 0xc000
	ds_read_b128 v[162:165], v219
	ds_read_b128 v[166:169], v219 offset:2048
	ds_read_b128 v[170:173], v220
	ds_read_b128 v[174:177], v220 offset:2048
	ds_read_b128 v[178:181], v219 offset:4096
	ds_read_b128 v[182:185], v219 offset:6144
	ds_read_b128 v[204:207], v220 offset:4096
	ds_read_b128 v[226:229], v220 offset:6144
	global_load_lds_dwordx4 v196, s[24:25]
	s_add_i32 m0, s41, 0xe000
	s_nop 0
	global_load_lds_dwordx4 v198, s[24:25]
	s_waitcnt vmcnt(8)
	s_waitcnt lgkmcnt(0)
	s_barrier
	s_setprio 1
	s_waitcnt lgkmcnt(0)
	v_mfma_f32_16x16x32_bf16 v[146:149], v[90:93], v[162:165], 0
	v_mfma_f32_16x16x32_bf16 v[146:149], v[102:105], v[170:173], v[146:149]
	v_mfma_f32_16x16x32_bf16 v[142:145], v[114:117], v[162:165], 0
	v_mfma_f32_16x16x32_bf16 v[142:145], v[126:129], v[170:173], v[142:145]
	v_mfma_f32_16x16x32_bf16 v[122:125], v[90:93], v[166:169], 0
	v_mfma_f32_16x16x32_bf16 v[122:125], v[102:105], v[174:177], v[122:125]
	v_mfma_f32_16x16x32_bf16 v[118:121], v[114:117], v[166:169], 0
	v_mfma_f32_16x16x32_bf16 v[118:121], v[126:129], v[174:177], v[118:121]
	v_mfma_f32_16x16x32_bf16 v[98:101], v[90:93], v[178:181], 0
	v_mfma_f32_16x16x32_bf16 v[98:101], v[102:105], v[204:207], v[98:101]
	v_mfma_f32_16x16x32_bf16 v[94:97], v[114:117], v[178:181], 0
	v_mfma_f32_16x16x32_bf16 v[94:97], v[126:129], v[204:207], v[94:97]
	v_mfma_f32_16x16x32_bf16 v[78:81], v[90:93], v[182:185], 0
	v_mfma_f32_16x16x32_bf16 v[78:81], v[102:105], v[226:229], v[78:81]
	v_mfma_f32_16x16x32_bf16 v[74:77], v[114:117], v[182:185], 0
	v_mfma_f32_16x16x32_bf16 v[74:77], v[126:129], v[226:229], v[74:77]
	s_setprio 0
	s_setprio 1
	v_mfma_f32_16x16x32_bf16 v[134:137], v[138:141], v[162:165], 0
	v_mfma_f32_16x16x32_bf16 v[134:137], v[150:153], v[170:173], v[134:137]
	v_mfma_f32_16x16x32_bf16 v[130:133], v[154:157], v[162:165], 0
	v_mfma_f32_16x16x32_bf16 v[130:133], v[158:161], v[170:173], v[130:133]
	v_mfma_f32_16x16x32_bf16 v[110:113], v[138:141], v[166:169], 0
	v_mfma_f32_16x16x32_bf16 v[110:113], v[150:153], v[174:177], v[110:113]
	v_mfma_f32_16x16x32_bf16 v[106:109], v[154:157], v[166:169], 0
	v_mfma_f32_16x16x32_bf16 v[106:109], v[158:161], v[174:177], v[106:109]
	v_mfma_f32_16x16x32_bf16 v[86:89], v[138:141], v[178:181], 0
	v_mfma_f32_16x16x32_bf16 v[86:89], v[150:153], v[204:207], v[86:89]
	v_mfma_f32_16x16x32_bf16 v[82:85], v[154:157], v[178:181], 0
	v_mfma_f32_16x16x32_bf16 v[82:85], v[158:161], v[204:207], v[82:85]
	v_mfma_f32_16x16x32_bf16 v[70:73], v[138:141], v[182:185], 0
	v_mfma_f32_16x16x32_bf16 v[70:73], v[150:153], v[226:229], v[70:73]
	v_mfma_f32_16x16x32_bf16 v[66:69], v[154:157], v[182:185], 0
	v_mfma_f32_16x16x32_bf16 v[66:69], v[158:161], v[226:229], v[66:69]
	s_setprio 0
	s_barrier
	s_add_i32 s58, s53, s40
	s_mov_b32 m0, s58
	ds_read_b128 v[162:165], v219 offset:16384
	ds_read_b128 v[166:169], v219 offset:18432
	ds_read_b128 v[170:173], v220 offset:16384
	ds_read_b128 v[174:177], v220 offset:18432
	ds_read_b128 v[178:181], v219 offset:20480
	ds_read_b128 v[182:185], v219 offset:22528
	ds_read_b128 v[204:207], v220 offset:20480
	ds_read_b128 v[226:229], v220 offset:22528
	global_load_lds_dwordx4 v188, s[26:27]
	s_add_i32 m0, s58, 0x2000
	s_add_u32 s58, s26, 0x40000
	s_addc_u32 s59, s27, 0
	s_add_i32 s60, s54, s40
	global_load_lds_dwordx4 v192, s[26:27]
	s_mov_b32 m0, s60
	s_mov_b64 s[98:99], s[28:29]
	global_load_lds_dwordx4 v188, s[58:59]
	s_add_i32 m0, s60, 0x2000
	s_nop 0
	global_load_lds_dwordx4 v192, s[58:59]
	s_mov_b32 m0, s41
	s_nop 0
	global_load_lds_dwordx4 v186, s[28:29]
	s_mov_b32 m0, s42
	s_nop 0
	global_load_lds_dwordx4 v190, s[28:29]
	s_waitcnt vmcnt(8)
	s_waitcnt lgkmcnt(0)
	s_barrier
	s_setprio 1
	s_waitcnt lgkmcnt(0)
	v_mfma_f32_16x16x32_bf16 v[62:65], v[90:93], v[162:165], 0
	v_mfma_f32_16x16x32_bf16 v[62:65], v[102:105], v[170:173], v[62:65]
	v_mfma_f32_16x16x32_bf16 v[58:61], v[114:117], v[162:165], 0
	v_mfma_f32_16x16x32_bf16 v[58:61], v[126:129], v[170:173], v[58:61]
	v_mfma_f32_16x16x32_bf16 v[46:49], v[90:93], v[166:169], 0
	v_mfma_f32_16x16x32_bf16 v[46:49], v[102:105], v[174:177], v[46:49]
	v_mfma_f32_16x16x32_bf16 v[42:45], v[114:117], v[166:169], 0
	v_mfma_f32_16x16x32_bf16 v[42:45], v[126:129], v[174:177], v[42:45]
	v_mfma_f32_16x16x32_bf16 v[30:33], v[90:93], v[178:181], 0
	v_mfma_f32_16x16x32_bf16 v[30:33], v[102:105], v[204:207], v[30:33]
	v_mfma_f32_16x16x32_bf16 v[26:29], v[114:117], v[178:181], 0
	v_mfma_f32_16x16x32_bf16 v[26:29], v[126:129], v[204:207], v[26:29]
	v_mfma_f32_16x16x32_bf16 v[14:17], v[90:93], v[182:185], 0
	v_mfma_f32_16x16x32_bf16 v[14:17], v[102:105], v[226:229], v[14:17]
	v_mfma_f32_16x16x32_bf16 v[10:13], v[114:117], v[182:185], 0
	v_mfma_f32_16x16x32_bf16 v[10:13], v[126:129], v[226:229], v[10:13]
	s_setprio 0
	s_setprio 1
	v_mfma_f32_16x16x32_bf16 v[54:57], v[138:141], v[162:165], 0
	v_mfma_f32_16x16x32_bf16 v[54:57], v[150:153], v[170:173], v[54:57]
	v_mfma_f32_16x16x32_bf16 v[50:53], v[154:157], v[162:165], 0
	v_mfma_f32_16x16x32_bf16 v[50:53], v[158:161], v[170:173], v[50:53]
	v_mfma_f32_16x16x32_bf16 v[38:41], v[138:141], v[166:169], 0
	v_mfma_f32_16x16x32_bf16 v[38:41], v[150:153], v[174:177], v[38:41]
	v_mfma_f32_16x16x32_bf16 v[34:37], v[154:157], v[166:169], 0
	v_mfma_f32_16x16x32_bf16 v[34:37], v[158:161], v[174:177], v[34:37]
	v_mfma_f32_16x16x32_bf16 v[22:25], v[138:141], v[178:181], 0
	v_mfma_f32_16x16x32_bf16 v[22:25], v[150:153], v[204:207], v[22:25]
	v_mfma_f32_16x16x32_bf16 v[18:21], v[154:157], v[178:181], 0
	v_mfma_f32_16x16x32_bf16 v[18:21], v[158:161], v[204:207], v[18:21]
	v_mfma_f32_16x16x32_bf16 v[6:9], v[138:141], v[182:185], 0
	v_mfma_f32_16x16x32_bf16 v[6:9], v[150:153], v[226:229], v[6:9]
	v_mfma_f32_16x16x32_bf16 v[2:5], v[154:157], v[182:185], 0
	v_mfma_f32_16x16x32_bf16 v[2:5], v[158:161], v[226:229], v[2:5]
	s_setprio 0
	s_barrier
	s_add_i32 s58, 0, 0x18000
	s_add_i32 s59, 0, 0x1c000
	ds_read_b128 v[90:93], v245 offset:32768
	ds_read_b128 v[102:105], v246 offset:32768
	ds_read_b128 v[114:117], v221
	ds_read_b128 v[126:129], v222
	ds_read_b128 v[138:141], v245 offset:49152
	ds_read_b128 v[150:153], v246 offset:49152
	ds_read_b128 v[154:157], v223
	ds_read_b128 v[158:161], v224
	s_add_u32 s28, s28, 0x40000
	s_addc_u32 s29, s29, 0
	s_mov_b32 m0, s43
	ds_read_b128 v[162:165], v219 offset:32768
	ds_read_b128 v[166:169], v219 offset:34816
	ds_read_b128 v[170:173], v220 offset:32768
	ds_read_b128 v[174:177], v220 offset:34816
	ds_read_b128 v[178:181], v219 offset:36864
	ds_read_b128 v[182:185], v219 offset:38912
	ds_read_b128 v[204:207], v220 offset:36864
	ds_read_b128 v[226:229], v220 offset:38912
	global_load_lds_dwordx4 v186, s[28:29]
	s_mov_b32 m0, s44
	s_nop 0
	global_load_lds_dwordx4 v190, s[28:29]
	s_waitcnt vmcnt(8)
	s_waitcnt lgkmcnt(0)
	s_barrier
	s_setprio 1
	s_waitcnt lgkmcnt(0)
	v_mfma_f32_16x16x32_bf16 v[146:149], v[90:93], v[162:165], v[146:149]
	v_mfma_f32_16x16x32_bf16 v[146:149], v[102:105], v[170:173], v[146:149]
	v_mfma_f32_16x16x32_bf16 v[142:145], v[114:117], v[162:165], v[142:145]
	v_mfma_f32_16x16x32_bf16 v[142:145], v[126:129], v[170:173], v[142:145]
	v_mfma_f32_16x16x32_bf16 v[122:125], v[90:93], v[166:169], v[122:125]
	v_mfma_f32_16x16x32_bf16 v[122:125], v[102:105], v[174:177], v[122:125]
	v_mfma_f32_16x16x32_bf16 v[118:121], v[114:117], v[166:169], v[118:121]
	v_mfma_f32_16x16x32_bf16 v[118:121], v[126:129], v[174:177], v[118:121]
	v_mfma_f32_16x16x32_bf16 v[98:101], v[90:93], v[178:181], v[98:101]
	v_mfma_f32_16x16x32_bf16 v[98:101], v[102:105], v[204:207], v[98:101]
	v_mfma_f32_16x16x32_bf16 v[94:97], v[114:117], v[178:181], v[94:97]
	v_mfma_f32_16x16x32_bf16 v[94:97], v[126:129], v[204:207], v[94:97]
	v_mfma_f32_16x16x32_bf16 v[78:81], v[90:93], v[182:185], v[78:81]
	v_mfma_f32_16x16x32_bf16 v[78:81], v[102:105], v[226:229], v[78:81]
	v_mfma_f32_16x16x32_bf16 v[74:77], v[114:117], v[182:185], v[74:77]
	v_mfma_f32_16x16x32_bf16 v[74:77], v[126:129], v[226:229], v[74:77]
	s_setprio 0
	s_setprio 1
	v_mfma_f32_16x16x32_bf16 v[134:137], v[138:141], v[162:165], v[134:137]
	v_mfma_f32_16x16x32_bf16 v[134:137], v[150:153], v[170:173], v[134:137]
	v_mfma_f32_16x16x32_bf16 v[130:133], v[154:157], v[162:165], v[130:133]
	v_mfma_f32_16x16x32_bf16 v[130:133], v[158:161], v[170:173], v[130:133]
	v_mfma_f32_16x16x32_bf16 v[110:113], v[138:141], v[166:169], v[110:113]
	v_mfma_f32_16x16x32_bf16 v[110:113], v[150:153], v[174:177], v[110:113]
	v_mfma_f32_16x16x32_bf16 v[106:109], v[154:157], v[166:169], v[106:109]
	v_mfma_f32_16x16x32_bf16 v[106:109], v[158:161], v[174:177], v[106:109]
	v_mfma_f32_16x16x32_bf16 v[86:89], v[138:141], v[178:181], v[86:89]
	v_mfma_f32_16x16x32_bf16 v[86:89], v[150:153], v[204:207], v[86:89]
	v_mfma_f32_16x16x32_bf16 v[82:85], v[154:157], v[178:181], v[82:85]
	v_mfma_f32_16x16x32_bf16 v[82:85], v[158:161], v[204:207], v[82:85]
	v_mfma_f32_16x16x32_bf16 v[70:73], v[138:141], v[182:185], v[70:73]
	v_mfma_f32_16x16x32_bf16 v[70:73], v[150:153], v[226:229], v[70:73]
	v_mfma_f32_16x16x32_bf16 v[66:69], v[154:157], v[182:185], v[66:69]
	v_mfma_f32_16x16x32_bf16 v[66:69], v[158:161], v[226:229], v[66:69]
	s_setprio 0
	s_barrier
	s_add_i32 s28, s58, s40
	s_add_i32 m0, s28, 0xffffff80
	ds_read_b128 v[162:165], v219 offset:49152
	ds_read_b128 v[166:169], v219 offset:51200
	ds_read_b128 v[170:173], v220 offset:49152
	ds_read_b128 v[174:177], v220 offset:51200
	ds_read_b128 v[178:181], v219 offset:53248
	ds_read_b128 v[182:185], v219 offset:55296
	ds_read_b128 v[204:207], v220 offset:53248
	ds_read_b128 v[226:229], v220 offset:55296
	global_load_lds_dwordx4 v188, s[26:27] offset:128
	s_add_i32 m0, s28, 0x1f80
	s_add_i32 s28, s59, s40
	global_load_lds_dwordx4 v192, s[26:27] offset:128
	s_add_u32 s26, s26, 0x40080
	s_addc_u32 s27, s27, 0
	s_mov_b32 m0, s28
	s_nop 0
	global_load_lds_dwordx4 v188, s[26:27]
	s_add_i32 m0, s28, 0x2000
	s_nop 0
	global_load_lds_dwordx4 v192, s[26:27]
	s_add_i32 m0, s48, 0xffffff80
	s_nop 0
	global_load_lds_dwordx4 v186, s[98:99] offset:128
	s_add_i32 m0, s49, 0xffffff80
	s_nop 0
	global_load_lds_dwordx4 v190, s[98:99] offset:128
	s_waitcnt vmcnt(8)
	s_waitcnt lgkmcnt(0)
	s_barrier
	s_setprio 1
	s_waitcnt lgkmcnt(0)
	v_mfma_f32_16x16x32_bf16 v[62:65], v[90:93], v[162:165], v[62:65]
	v_mfma_f32_16x16x32_bf16 v[62:65], v[102:105], v[170:173], v[62:65]
	v_mfma_f32_16x16x32_bf16 v[58:61], v[114:117], v[162:165], v[58:61]
	v_mfma_f32_16x16x32_bf16 v[58:61], v[126:129], v[170:173], v[58:61]
	v_mfma_f32_16x16x32_bf16 v[46:49], v[90:93], v[166:169], v[46:49]
	v_mfma_f32_16x16x32_bf16 v[46:49], v[102:105], v[174:177], v[46:49]
	v_mfma_f32_16x16x32_bf16 v[42:45], v[114:117], v[166:169], v[42:45]
	v_mfma_f32_16x16x32_bf16 v[42:45], v[126:129], v[174:177], v[42:45]
	v_mfma_f32_16x16x32_bf16 v[30:33], v[90:93], v[178:181], v[30:33]
	v_mfma_f32_16x16x32_bf16 v[30:33], v[102:105], v[204:207], v[30:33]
	v_mfma_f32_16x16x32_bf16 v[26:29], v[114:117], v[178:181], v[26:29]
	v_mfma_f32_16x16x32_bf16 v[26:29], v[126:129], v[204:207], v[26:29]
	v_mfma_f32_16x16x32_bf16 v[14:17], v[90:93], v[182:185], v[14:17]
	v_mfma_f32_16x16x32_bf16 v[14:17], v[102:105], v[226:229], v[14:17]
	v_mfma_f32_16x16x32_bf16 v[10:13], v[114:117], v[182:185], v[10:13]
	v_mfma_f32_16x16x32_bf16 v[10:13], v[126:129], v[226:229], v[10:13]
	s_setprio 0
	s_setprio 1
	v_mfma_f32_16x16x32_bf16 v[54:57], v[138:141], v[162:165], v[54:57]
	v_mfma_f32_16x16x32_bf16 v[54:57], v[150:153], v[170:173], v[54:57]
	v_mfma_f32_16x16x32_bf16 v[50:53], v[154:157], v[162:165], v[50:53]
	v_mfma_f32_16x16x32_bf16 v[50:53], v[158:161], v[170:173], v[50:53]
	v_mfma_f32_16x16x32_bf16 v[38:41], v[138:141], v[166:169], v[38:41]
	v_mfma_f32_16x16x32_bf16 v[38:41], v[150:153], v[174:177], v[38:41]
	v_mfma_f32_16x16x32_bf16 v[34:37], v[154:157], v[166:169], v[34:37]
	v_mfma_f32_16x16x32_bf16 v[34:37], v[158:161], v[174:177], v[34:37]
	v_mfma_f32_16x16x32_bf16 v[22:25], v[138:141], v[178:181], v[22:25]
	v_mfma_f32_16x16x32_bf16 v[22:25], v[150:153], v[204:207], v[22:25]
	v_mfma_f32_16x16x32_bf16 v[18:21], v[154:157], v[178:181], v[18:21]
	v_mfma_f32_16x16x32_bf16 v[18:21], v[158:161], v[204:207], v[18:21]
	v_mfma_f32_16x16x32_bf16 v[6:9], v[138:141], v[182:185], v[6:9]
	v_mfma_f32_16x16x32_bf16 v[6:9], v[150:153], v[226:229], v[6:9]
	v_mfma_f32_16x16x32_bf16 v[2:5], v[154:157], v[182:185], v[2:5]
	v_mfma_f32_16x16x32_bf16 v[2:5], v[158:161], v[226:229], v[2:5]
	s_setprio 0
	s_barrier
	s_add_i32 s57, s57, 2
	s_add_u32 s24, s24, 0x100
	s_addc_u32 s25, s25, 0
	s_add_u32 s55, s55, 0x100
	s_addc_u32 s56, s56, 0
	s_cmp_gt_u32 s57, 13
	s_cbranch_scc0 .LBB0_1629

.LBB0_1721:
	s_cmp_lg_u32 s100, 0
	s_cbranch_scc1 .Lpeel_5
	ds_read_b128 v[150:153], v245
	ds_read_b128 v[160:163], v246
	ds_read_b128 v[164:167], v245 offset:2048
	ds_read_b128 v[168:171], v246 offset:2048
	ds_read_b128 v[172:175], v245 offset:16384
	ds_read_b128 v[176:179], v246 offset:16384
	ds_read_b128 v[180:183], v245 offset:18432
	ds_read_b128 v[184:187], v246 offset:18432
	s_add_u32 s26, s22, 0xfffc0080
	s_addc_u32 s27, s23, -1
	s_and_b64 s[24:25], s[24:25], exec
	s_cselect_b32 s27, s13, s27
	s_cselect_b32 s26, s58, s26
	s_cselect_b32 s25, s5, s62
	s_cselect_b32 s24, s59, s61
	s_add_i32 m0, s38, 0xc000
	ds_read_b128 v[188:191], v157
	s_waitcnt lgkmcnt(0)
	ds_read_b128 v[192:195], v157 offset:2048
	ds_read_b128 v[196:199], v158
	ds_read_b128 v[200:203], v158 offset:2048
	ds_read_b128 v[204:207], v157 offset:4096
	ds_read_b128 v[208:211], v157 offset:6144
	ds_read_b128 v[212:215], v158 offset:4096
	ds_read_b128 v[216:219], v158 offset:6144
	global_load_lds_dwordx4 v140, s[22:23]
	s_add_i32 m0, s38, 0xe000
	s_nop 0
	global_load_lds_dwordx4 v142, s[22:23]
	s_waitcnt vmcnt(8)
	s_waitcnt lgkmcnt(0)
	s_barrier
	s_setprio 1
	v_mfma_f32_16x16x32_bf16 v[126:129], v[150:153], v[188:191], v[126:129]
	v_mfma_f32_16x16x32_bf16 v[118:121], v[164:167], v[188:191], v[118:121]
	s_waitcnt lgkmcnt(0)
	v_mfma_f32_16x16x32_bf16 v[110:113], v[150:153], v[192:195], v[110:113]
	v_mfma_f32_16x16x32_bf16 v[102:105], v[164:167], v[192:195], v[102:105]
	v_mfma_f32_16x16x32_bf16 v[94:97], v[150:153], v[204:207], v[94:97]
	v_mfma_f32_16x16x32_bf16 v[86:89], v[164:167], v[204:207], v[86:89]
	v_mfma_f32_16x16x32_bf16 v[78:81], v[150:153], v[208:211], v[78:81]
	v_mfma_f32_16x16x32_bf16 v[70:73], v[164:167], v[208:211], v[70:73]
	v_mfma_f32_16x16x32_bf16 v[126:129], v[160:163], v[196:199], v[126:129]
	v_mfma_f32_16x16x32_bf16 v[118:121], v[168:171], v[196:199], v[118:121]
	v_mfma_f32_16x16x32_bf16 v[110:113], v[160:163], v[200:203], v[110:113]
	v_mfma_f32_16x16x32_bf16 v[102:105], v[168:171], v[200:203], v[102:105]
	v_mfma_f32_16x16x32_bf16 v[94:97], v[160:163], v[212:215], v[94:97]
	v_mfma_f32_16x16x32_bf16 v[86:89], v[168:171], v[212:215], v[86:89]
	v_mfma_f32_16x16x32_bf16 v[78:81], v[160:163], v[216:219], v[78:81]
	v_mfma_f32_16x16x32_bf16 v[70:73], v[168:171], v[216:219], v[70:73]
	s_setprio 0
	s_setprio 1
	v_mfma_f32_16x16x32_bf16 v[122:125], v[172:175], v[188:191], v[122:125]
	v_mfma_f32_16x16x32_bf16 v[122:125], v[176:179], v[196:199], v[122:125]
	v_mfma_f32_16x16x32_bf16 v[114:117], v[180:183], v[188:191], v[114:117]
	v_mfma_f32_16x16x32_bf16 v[114:117], v[184:187], v[196:199], v[114:117]
	v_mfma_f32_16x16x32_bf16 v[106:109], v[172:175], v[192:195], v[106:109]
	v_mfma_f32_16x16x32_bf16 v[106:109], v[176:179], v[200:203], v[106:109]
	v_mfma_f32_16x16x32_bf16 v[98:101], v[180:183], v[192:195], v[98:101]
	v_mfma_f32_16x16x32_bf16 v[98:101], v[184:187], v[200:203], v[98:101]
	v_mfma_f32_16x16x32_bf16 v[90:93], v[172:175], v[204:207], v[90:93]
	v_mfma_f32_16x16x32_bf16 v[90:93], v[176:179], v[212:215], v[90:93]
	v_mfma_f32_16x16x32_bf16 v[82:85], v[180:183], v[204:207], v[82:85]
	v_mfma_f32_16x16x32_bf16 v[82:85], v[184:187], v[212:215], v[82:85]
	v_mfma_f32_16x16x32_bf16 v[74:77], v[172:175], v[208:211], v[74:77]
	v_mfma_f32_16x16x32_bf16 v[74:77], v[176:179], v[216:219], v[74:77]
	v_mfma_f32_16x16x32_bf16 v[66:69], v[180:183], v[208:211], v[66:69]
	v_mfma_f32_16x16x32_bf16 v[66:69], v[184:187], v[216:219], v[66:69]
	s_setprio 0
	s_barrier
	s_add_i32 s64, s49, s21
	s_mov_b32 m0, s64
	ds_read_b128 v[188:191], v157 offset:16384
	ds_read_b128 v[192:195], v157 offset:18432
	ds_read_b128 v[196:199], v158 offset:16384
	ds_read_b128 v[200:203], v158 offset:18432
	ds_read_b128 v[204:207], v157 offset:20480
	ds_read_b128 v[208:211], v157 offset:22528
	ds_read_b128 v[212:215], v158 offset:20480
	ds_read_b128 v[216:219], v158 offset:22528
	global_load_lds_dwordx4 v132, s[24:25]
	s_add_i32 m0, s64, 0x2000
	s_add_u32 s64, s24, 0x40000
	s_addc_u32 s65, s25, 0
	s_add_i32 s66, s51, s21
	global_load_lds_dwordx4 v136, s[24:25]
	s_mov_b32 m0, s66
	s_mov_b64 s[98:99], s[26:27]
	global_load_lds_dwordx4 v132, s[64:65]
	s_add_i32 m0, s66, 0x2000
	s_nop 0
	global_load_lds_dwordx4 v136, s[64:65]
	s_mov_b32 m0, s38
	s_nop 0
	global_load_lds_dwordx4 v130, s[26:27]
	s_mov_b32 m0, s39
	s_nop 0
	global_load_lds_dwordx4 v134, s[26:27]
	s_waitcnt vmcnt(8)
	s_waitcnt lgkmcnt(0)
	s_barrier
	s_setprio 1
	s_waitcnt lgkmcnt(0)
	v_mfma_f32_16x16x32_bf16 v[62:65], v[150:153], v[188:191], v[62:65]
	v_mfma_f32_16x16x32_bf16 v[62:65], v[160:163], v[196:199], v[62:65]
	v_mfma_f32_16x16x32_bf16 v[54:57], v[164:167], v[188:191], v[54:57]
	v_mfma_f32_16x16x32_bf16 v[54:57], v[168:171], v[196:199], v[54:57]
	v_mfma_f32_16x16x32_bf16 v[46:49], v[150:153], v[192:195], v[46:49]
	v_mfma_f32_16x16x32_bf16 v[46:49], v[160:163], v[200:203], v[46:49]
	v_mfma_f32_16x16x32_bf16 v[38:41], v[164:167], v[192:195], v[38:41]
	v_mfma_f32_16x16x32_bf16 v[38:41], v[168:171], v[200:203], v[38:41]
	v_mfma_f32_16x16x32_bf16 v[30:33], v[150:153], v[204:207], v[30:33]
	v_mfma_f32_16x16x32_bf16 v[30:33], v[160:163], v[212:215], v[30:33]
	v_mfma_f32_16x16x32_bf16 v[22:25], v[164:167], v[204:207], v[22:25]
	v_mfma_f32_16x16x32_bf16 v[22:25], v[168:171], v[212:215], v[22:25]
	v_mfma_f32_16x16x32_bf16 v[14:17], v[150:153], v[208:211], v[14:17]
	v_mfma_f32_16x16x32_bf16 v[14:17], v[160:163], v[216:219], v[14:17]
	v_mfma_f32_16x16x32_bf16 v[6:9], v[164:167], v[208:211], v[6:9]
	v_mfma_f32_16x16x32_bf16 v[6:9], v[168:171], v[216:219], v[6:9]
	s_setprio 0
	s_setprio 1
	v_mfma_f32_16x16x32_bf16 v[58:61], v[172:175], v[188:191], v[58:61]
	v_mfma_f32_16x16x32_bf16 v[58:61], v[176:179], v[196:199], v[58:61]
	v_mfma_f32_16x16x32_bf16 v[50:53], v[180:183], v[188:191], v[50:53]
	v_mfma_f32_16x16x32_bf16 v[50:53], v[184:187], v[196:199], v[50:53]
	v_mfma_f32_16x16x32_bf16 v[42:45], v[172:175], v[192:195], v[42:45]
	v_mfma_f32_16x16x32_bf16 v[42:45], v[176:179], v[200:203], v[42:45]
	v_mfma_f32_16x16x32_bf16 v[34:37], v[180:183], v[192:195], v[34:37]
	v_mfma_f32_16x16x32_bf16 v[34:37], v[184:187], v[200:203], v[34:37]
	v_mfma_f32_16x16x32_bf16 v[26:29], v[172:175], v[204:207], v[26:29]
	v_mfma_f32_16x16x32_bf16 v[26:29], v[176:179], v[212:215], v[26:29]
	v_mfma_f32_16x16x32_bf16 v[18:21], v[180:183], v[204:207], v[18:21]
	v_mfma_f32_16x16x32_bf16 v[18:21], v[184:187], v[212:215], v[18:21]
	v_mfma_f32_16x16x32_bf16 v[10:13], v[172:175], v[208:211], v[10:13]
	v_mfma_f32_16x16x32_bf16 v[10:13], v[176:179], v[216:219], v[10:13]
	v_mfma_f32_16x16x32_bf16 v[2:5], v[180:183], v[208:211], v[2:5]
	v_mfma_f32_16x16x32_bf16 v[2:5], v[184:187], v[216:219], v[2:5]
	s_setprio 0
	s_barrier
	s_add_i32 s64, 0, 0x18000
	s_add_i32 s65, 0, 0x1c000
	ds_read_b128 v[150:153], v245 offset:32768
	ds_read_b128 v[160:163], v246 offset:32768
	ds_read_b128 v[164:167], v245 offset:34816
	ds_read_b128 v[168:171], v246 offset:34816
	ds_read_b128 v[172:175], v245 offset:49152
	ds_read_b128 v[176:179], v246 offset:49152
	ds_read_b128 v[180:183], v245 offset:51200
	ds_read_b128 v[184:187], v246 offset:51200
	s_add_u32 s26, s26, 0x40000
	s_addc_u32 s27, s27, 0
	s_mov_b32 m0, s40
	ds_read_b128 v[188:191], v157 offset:32768
	ds_read_b128 v[192:195], v157 offset:34816
	ds_read_b128 v[196:199], v158 offset:32768
	ds_read_b128 v[200:203], v158 offset:34816
	ds_read_b128 v[204:207], v157 offset:36864
	ds_read_b128 v[208:211], v157 offset:38912
	ds_read_b128 v[212:215], v158 offset:36864
	ds_read_b128 v[216:219], v158 offset:38912
	global_load_lds_dwordx4 v130, s[26:27]
	s_mov_b32 m0, s41
	s_nop 0
	global_load_lds_dwordx4 v134, s[26:27]
	s_waitcnt vmcnt(8)
	s_waitcnt lgkmcnt(0)
	s_barrier
	s_setprio 1
	s_waitcnt lgkmcnt(0)
	v_mfma_f32_16x16x32_bf16 v[126:129], v[150:153], v[188:191], v[126:129]
	v_mfma_f32_16x16x32_bf16 v[126:129], v[160:163], v[196:199], v[126:129]
	v_mfma_f32_16x16x32_bf16 v[118:121], v[164:167], v[188:191], v[118:121]
	v_mfma_f32_16x16x32_bf16 v[118:121], v[168:171], v[196:199], v[118:121]
	v_mfma_f32_16x16x32_bf16 v[110:113], v[150:153], v[192:195], v[110:113]
	v_mfma_f32_16x16x32_bf16 v[110:113], v[160:163], v[200:203], v[110:113]
	v_mfma_f32_16x16x32_bf16 v[102:105], v[164:167], v[192:195], v[102:105]
	v_mfma_f32_16x16x32_bf16 v[102:105], v[168:171], v[200:203], v[102:105]
	v_mfma_f32_16x16x32_bf16 v[94:97], v[150:153], v[204:207], v[94:97]
	v_mfma_f32_16x16x32_bf16 v[94:97], v[160:163], v[212:215], v[94:97]
	v_mfma_f32_16x16x32_bf16 v[86:89], v[164:167], v[204:207], v[86:89]
	v_mfma_f32_16x16x32_bf16 v[86:89], v[168:171], v[212:215], v[86:89]
	v_mfma_f32_16x16x32_bf16 v[78:81], v[150:153], v[208:211], v[78:81]
	v_mfma_f32_16x16x32_bf16 v[78:81], v[160:163], v[216:219], v[78:81]
	v_mfma_f32_16x16x32_bf16 v[70:73], v[164:167], v[208:211], v[70:73]
	v_mfma_f32_16x16x32_bf16 v[70:73], v[168:171], v[216:219], v[70:73]
	s_setprio 0
	s_setprio 1
	v_mfma_f32_16x16x32_bf16 v[122:125], v[172:175], v[188:191], v[122:125]
	v_mfma_f32_16x16x32_bf16 v[122:125], v[176:179], v[196:199], v[122:125]
	v_mfma_f32_16x16x32_bf16 v[114:117], v[180:183], v[188:191], v[114:117]
	v_mfma_f32_16x16x32_bf16 v[114:117], v[184:187], v[196:199], v[114:117]
	v_mfma_f32_16x16x32_bf16 v[106:109], v[172:175], v[192:195], v[106:109]
	v_mfma_f32_16x16x32_bf16 v[106:109], v[176:179], v[200:203], v[106:109]
	v_mfma_f32_16x16x32_bf16 v[98:101], v[180:183], v[192:195], v[98:101]
	v_mfma_f32_16x16x32_bf16 v[98:101], v[184:187], v[200:203], v[98:101]
	v_mfma_f32_16x16x32_bf16 v[90:93], v[172:175], v[204:207], v[90:93]
	v_mfma_f32_16x16x32_bf16 v[90:93], v[176:179], v[212:215], v[90:93]
	v_mfma_f32_16x16x32_bf16 v[82:85], v[180:183], v[204:207], v[82:85]
	v_mfma_f32_16x16x32_bf16 v[82:85], v[184:187], v[212:215], v[82:85]
	v_mfma_f32_16x16x32_bf16 v[74:77], v[172:175], v[208:211], v[74:77]
	v_mfma_f32_16x16x32_bf16 v[74:77], v[176:179], v[216:219], v[74:77]
	v_mfma_f32_16x16x32_bf16 v[66:69], v[180:183], v[208:211], v[66:69]
	v_mfma_f32_16x16x32_bf16 v[66:69], v[184:187], v[216:219], v[66:69]
	s_setprio 0
	s_barrier
	s_add_i32 s26, s64, s21
	s_add_i32 m0, s26, 0xffffff80
	ds_read_b128 v[188:191], v157 offset:49152
	ds_read_b128 v[192:195], v157 offset:51200
	ds_read_b128 v[196:199], v158 offset:49152
	ds_read_b128 v[200:203], v158 offset:51200
	ds_read_b128 v[204:207], v157 offset:53248
	ds_read_b128 v[208:211], v157 offset:55296
	ds_read_b128 v[212:215], v158 offset:53248
	ds_read_b128 v[216:219], v158 offset:55296
	global_load_lds_dwordx4 v132, s[24:25] offset:128
	s_add_i32 m0, s26, 0x1f80
	s_add_i32 s26, s65, s21
	global_load_lds_dwordx4 v136, s[24:25] offset:128
	s_add_u32 s24, s24, 0x40080
	s_addc_u32 s25, s25, 0
	s_mov_b32 m0, s26
	s_nop 0
	global_load_lds_dwordx4 v132, s[24:25]
	s_add_i32 m0, s26, 0x2000
	s_nop 0
	global_load_lds_dwordx4 v136, s[24:25]
	s_add_i32 m0, s44, 0xffffff80
	s_nop 0
	global_load_lds_dwordx4 v130, s[98:99] offset:128
	s_add_i32 m0, s45, 0xffffff80
	s_nop 0
	global_load_lds_dwordx4 v134, s[98:99] offset:128
	s_waitcnt vmcnt(8)
	s_waitcnt lgkmcnt(0)
	s_barrier
	s_setprio 1
	s_waitcnt lgkmcnt(0)
	v_mfma_f32_16x16x32_bf16 v[62:65], v[150:153], v[188:191], v[62:65]
	v_mfma_f32_16x16x32_bf16 v[62:65], v[160:163], v[196:199], v[62:65]
	v_mfma_f32_16x16x32_bf16 v[54:57], v[164:167], v[188:191], v[54:57]
	v_mfma_f32_16x16x32_bf16 v[54:57], v[168:171], v[196:199], v[54:57]
	v_mfma_f32_16x16x32_bf16 v[46:49], v[150:153], v[192:195], v[46:49]
	v_mfma_f32_16x16x32_bf16 v[46:49], v[160:163], v[200:203], v[46:49]
	v_mfma_f32_16x16x32_bf16 v[38:41], v[164:167], v[192:195], v[38:41]
	v_mfma_f32_16x16x32_bf16 v[38:41], v[168:171], v[200:203], v[38:41]
	v_mfma_f32_16x16x32_bf16 v[30:33], v[150:153], v[204:207], v[30:33]
	v_mfma_f32_16x16x32_bf16 v[30:33], v[160:163], v[212:215], v[30:33]
	v_mfma_f32_16x16x32_bf16 v[22:25], v[164:167], v[204:207], v[22:25]
	v_mfma_f32_16x16x32_bf16 v[22:25], v[168:171], v[212:215], v[22:25]
	v_mfma_f32_16x16x32_bf16 v[14:17], v[150:153], v[208:211], v[14:17]
	v_mfma_f32_16x16x32_bf16 v[14:17], v[160:163], v[216:219], v[14:17]
	v_mfma_f32_16x16x32_bf16 v[6:9], v[164:167], v[208:211], v[6:9]
	v_mfma_f32_16x16x32_bf16 v[6:9], v[168:171], v[216:219], v[6:9]
	s_setprio 0
	s_setprio 1
	v_mfma_f32_16x16x32_bf16 v[58:61], v[172:175], v[188:191], v[58:61]
	v_mfma_f32_16x16x32_bf16 v[58:61], v[176:179], v[196:199], v[58:61]
	v_mfma_f32_16x16x32_bf16 v[50:53], v[180:183], v[188:191], v[50:53]
	v_mfma_f32_16x16x32_bf16 v[50:53], v[184:187], v[196:199], v[50:53]
	v_mfma_f32_16x16x32_bf16 v[42:45], v[172:175], v[192:195], v[42:45]
	v_mfma_f32_16x16x32_bf16 v[42:45], v[176:179], v[200:203], v[42:45]
	v_mfma_f32_16x16x32_bf16 v[34:37], v[180:183], v[192:195], v[34:37]
	v_mfma_f32_16x16x32_bf16 v[34:37], v[184:187], v[200:203], v[34:37]
	v_mfma_f32_16x16x32_bf16 v[26:29], v[172:175], v[204:207], v[26:29]
	v_mfma_f32_16x16x32_bf16 v[26:29], v[176:179], v[212:215], v[26:29]
	v_mfma_f32_16x16x32_bf16 v[18:21], v[180:183], v[204:207], v[18:21]
	v_mfma_f32_16x16x32_bf16 v[18:21], v[184:187], v[212:215], v[18:21]
	v_mfma_f32_16x16x32_bf16 v[10:13], v[172:175], v[208:211], v[10:13]
	v_mfma_f32_16x16x32_bf16 v[10:13], v[176:179], v[216:219], v[10:13]
	v_mfma_f32_16x16x32_bf16 v[2:5], v[180:183], v[208:211], v[2:5]
	v_mfma_f32_16x16x32_bf16 v[2:5], v[184:187], v[216:219], v[2:5]
	s_setprio 0
	s_barrier
	s_add_i32 s63, s63, 2
	s_add_u32 s22, s22, 0x100
	s_addc_u32 s23, s23, 0
	s_add_u32 s61, s61, 0x100
	s_addc_u32 s62, s62, 0
	s_cmp_gt_u32 s63, 13
	s_cbranch_scc1 .LBB0_1725

.Lpeel_5:
	s_mov_b32 s100, 0
	ds_read_b128 v[150:153], v245
	ds_read_b128 v[160:163], v246
	ds_read_b128 v[164:167], v245 offset:2048
	ds_read_b128 v[168:171], v246 offset:2048
	ds_read_b128 v[172:175], v245 offset:16384
	ds_read_b128 v[176:179], v246 offset:16384
	ds_read_b128 v[180:183], v245 offset:18432
	ds_read_b128 v[184:187], v246 offset:18432
	s_add_u32 s26, s22, 0xfffc0080
	s_addc_u32 s27, s23, -1
	s_and_b64 s[24:25], s[24:25], exec
	s_cselect_b32 s27, s13, s27
	s_cselect_b32 s26, s58, s26
	s_cselect_b32 s25, s5, s62
	s_cselect_b32 s24, s59, s61
	s_add_i32 m0, s38, 0xc000
	ds_read_b128 v[188:191], v157
	s_waitcnt lgkmcnt(0)
	ds_read_b128 v[192:195], v157 offset:2048
	ds_read_b128 v[196:199], v158
	ds_read_b128 v[200:203], v158 offset:2048
	ds_read_b128 v[204:207], v157 offset:4096
	ds_read_b128 v[208:211], v157 offset:6144
	ds_read_b128 v[212:215], v158 offset:4096
	ds_read_b128 v[216:219], v158 offset:6144
	global_load_lds_dwordx4 v140, s[22:23]
	s_add_i32 m0, s38, 0xe000
	s_nop 0
	global_load_lds_dwordx4 v142, s[22:23]
	s_waitcnt vmcnt(8)
	s_waitcnt lgkmcnt(0)
	s_barrier
	s_setprio 1
	v_mfma_f32_16x16x32_bf16 v[126:129], v[150:153], v[188:191], 0
	v_mfma_f32_16x16x32_bf16 v[118:121], v[164:167], v[188:191], 0
	s_waitcnt lgkmcnt(0)
	v_mfma_f32_16x16x32_bf16 v[110:113], v[150:153], v[192:195], 0
	v_mfma_f32_16x16x32_bf16 v[102:105], v[164:167], v[192:195], 0
	v_mfma_f32_16x16x32_bf16 v[94:97], v[150:153], v[204:207], 0
	v_mfma_f32_16x16x32_bf16 v[86:89], v[164:167], v[204:207], 0
	v_mfma_f32_16x16x32_bf16 v[78:81], v[150:153], v[208:211], 0
	v_mfma_f32_16x16x32_bf16 v[70:73], v[164:167], v[208:211], 0
	v_mfma_f32_16x16x32_bf16 v[126:129], v[160:163], v[196:199], v[126:129]
	v_mfma_f32_16x16x32_bf16 v[118:121], v[168:171], v[196:199], v[118:121]
	v_mfma_f32_16x16x32_bf16 v[110:113], v[160:163], v[200:203], v[110:113]
	v_mfma_f32_16x16x32_bf16 v[102:105], v[168:171], v[200:203], v[102:105]
	v_mfma_f32_16x16x32_bf16 v[94:97], v[160:163], v[212:215], v[94:97]
	v_mfma_f32_16x16x32_bf16 v[86:89], v[168:171], v[212:215], v[86:89]
	v_mfma_f32_16x16x32_bf16 v[78:81], v[160:163], v[216:219], v[78:81]
	v_mfma_f32_16x16x32_bf16 v[70:73], v[168:171], v[216:219], v[70:73]
	s_setprio 0
	s_setprio 1
	v_mfma_f32_16x16x32_bf16 v[122:125], v[172:175], v[188:191], 0
	v_mfma_f32_16x16x32_bf16 v[122:125], v[176:179], v[196:199], v[122:125]
	v_mfma_f32_16x16x32_bf16 v[114:117], v[180:183], v[188:191], 0
	v_mfma_f32_16x16x32_bf16 v[114:117], v[184:187], v[196:199], v[114:117]
	v_mfma_f32_16x16x32_bf16 v[106:109], v[172:175], v[192:195], 0
	v_mfma_f32_16x16x32_bf16 v[106:109], v[176:179], v[200:203], v[106:109]
	v_mfma_f32_16x16x32_bf16 v[98:101], v[180:183], v[192:195], 0
	v_mfma_f32_16x16x32_bf16 v[98:101], v[184:187], v[200:203], v[98:101]
	v_mfma_f32_16x16x32_bf16 v[90:93], v[172:175], v[204:207], 0
	v_mfma_f32_16x16x32_bf16 v[90:93], v[176:179], v[212:215], v[90:93]
	v_mfma_f32_16x16x32_bf16 v[82:85], v[180:183], v[204:207], 0
	v_mfma_f32_16x16x32_bf16 v[82:85], v[184:187], v[212:215], v[82:85]
	v_mfma_f32_16x16x32_bf16 v[74:77], v[172:175], v[208:211], 0
	v_mfma_f32_16x16x32_bf16 v[74:77], v[176:179], v[216:219], v[74:77]
	v_mfma_f32_16x16x32_bf16 v[66:69], v[180:183], v[208:211], 0
	v_mfma_f32_16x16x32_bf16 v[66:69], v[184:187], v[216:219], v[66:69]
	s_setprio 0
	s_barrier
	s_add_i32 s64, s49, s21
	s_mov_b32 m0, s64
	ds_read_b128 v[188:191], v157 offset:16384
	ds_read_b128 v[192:195], v157 offset:18432
	ds_read_b128 v[196:199], v158 offset:16384
	ds_read_b128 v[200:203], v158 offset:18432
	ds_read_b128 v[204:207], v157 offset:20480
	ds_read_b128 v[208:211], v157 offset:22528
	ds_read_b128 v[212:215], v158 offset:20480
	ds_read_b128 v[216:219], v158 offset:22528
	global_load_lds_dwordx4 v132, s[24:25]
	s_add_i32 m0, s64, 0x2000
	s_add_u32 s64, s24, 0x40000
	s_addc_u32 s65, s25, 0
	s_add_i32 s66, s51, s21
	global_load_lds_dwordx4 v136, s[24:25]
	s_mov_b32 m0, s66
	s_mov_b64 s[98:99], s[26:27]
	global_load_lds_dwordx4 v132, s[64:65]
	s_add_i32 m0, s66, 0x2000
	s_nop 0
	global_load_lds_dwordx4 v136, s[64:65]
	s_mov_b32 m0, s38
	s_nop 0
	global_load_lds_dwordx4 v130, s[26:27]
	s_mov_b32 m0, s39
	s_nop 0
	global_load_lds_dwordx4 v134, s[26:27]
	s_waitcnt vmcnt(8)
	s_waitcnt lgkmcnt(0)
	s_barrier
	s_setprio 1
	s_waitcnt lgkmcnt(0)
	v_mfma_f32_16x16x32_bf16 v[62:65], v[150:153], v[188:191], 0
	v_mfma_f32_16x16x32_bf16 v[62:65], v[160:163], v[196:199], v[62:65]
	v_mfma_f32_16x16x32_bf16 v[54:57], v[164:167], v[188:191], 0
	v_mfma_f32_16x16x32_bf16 v[54:57], v[168:171], v[196:199], v[54:57]
	v_mfma_f32_16x16x32_bf16 v[46:49], v[150:153], v[192:195], 0
	v_mfma_f32_16x16x32_bf16 v[46:49], v[160:163], v[200:203], v[46:49]
	v_mfma_f32_16x16x32_bf16 v[38:41], v[164:167], v[192:195], 0
	v_mfma_f32_16x16x32_bf16 v[38:41], v[168:171], v[200:203], v[38:41]
	v_mfma_f32_16x16x32_bf16 v[30:33], v[150:153], v[204:207], 0
	v_mfma_f32_16x16x32_bf16 v[30:33], v[160:163], v[212:215], v[30:33]
	v_mfma_f32_16x16x32_bf16 v[22:25], v[164:167], v[204:207], 0
	v_mfma_f32_16x16x32_bf16 v[22:25], v[168:171], v[212:215], v[22:25]
	v_mfma_f32_16x16x32_bf16 v[14:17], v[150:153], v[208:211], 0
	v_mfma_f32_16x16x32_bf16 v[14:17], v[160:163], v[216:219], v[14:17]
	v_mfma_f32_16x16x32_bf16 v[6:9], v[164:167], v[208:211], 0
	v_mfma_f32_16x16x32_bf16 v[6:9], v[168:171], v[216:219], v[6:9]
	s_setprio 0
	s_setprio 1
	v_mfma_f32_16x16x32_bf16 v[58:61], v[172:175], v[188:191], 0
	v_mfma_f32_16x16x32_bf16 v[58:61], v[176:179], v[196:199], v[58:61]
	v_mfma_f32_16x16x32_bf16 v[50:53], v[180:183], v[188:191], 0
	v_mfma_f32_16x16x32_bf16 v[50:53], v[184:187], v[196:199], v[50:53]
	v_mfma_f32_16x16x32_bf16 v[42:45], v[172:175], v[192:195], 0
	v_mfma_f32_16x16x32_bf16 v[42:45], v[176:179], v[200:203], v[42:45]
	v_mfma_f32_16x16x32_bf16 v[34:37], v[180:183], v[192:195], 0
	v_mfma_f32_16x16x32_bf16 v[34:37], v[184:187], v[200:203], v[34:37]
	v_mfma_f32_16x16x32_bf16 v[26:29], v[172:175], v[204:207], 0
	v_mfma_f32_16x16x32_bf16 v[26:29], v[176:179], v[212:215], v[26:29]
	v_mfma_f32_16x16x32_bf16 v[18:21], v[180:183], v[204:207], 0
	v_mfma_f32_16x16x32_bf16 v[18:21], v[184:187], v[212:215], v[18:21]
	v_mfma_f32_16x16x32_bf16 v[10:13], v[172:175], v[208:211], 0
	v_mfma_f32_16x16x32_bf16 v[10:13], v[176:179], v[216:219], v[10:13]
	v_mfma_f32_16x16x32_bf16 v[2:5], v[180:183], v[208:211], 0
	v_mfma_f32_16x16x32_bf16 v[2:5], v[184:187], v[216:219], v[2:5]
	s_setprio 0
	s_barrier
	s_add_i32 s64, 0, 0x18000
	s_add_i32 s65, 0, 0x1c000
	ds_read_b128 v[150:153], v245 offset:32768
	ds_read_b128 v[160:163], v246 offset:32768
	ds_read_b128 v[164:167], v245 offset:34816
	ds_read_b128 v[168:171], v246 offset:34816
	ds_read_b128 v[172:175], v245 offset:49152
	ds_read_b128 v[176:179], v246 offset:49152
	ds_read_b128 v[180:183], v245 offset:51200
	ds_read_b128 v[184:187], v246 offset:51200
	s_add_u32 s26, s26, 0x40000
	s_addc_u32 s27, s27, 0
	s_mov_b32 m0, s40
	ds_read_b128 v[188:191], v157 offset:32768
	ds_read_b128 v[192:195], v157 offset:34816
	ds_read_b128 v[196:199], v158 offset:32768
	ds_read_b128 v[200:203], v158 offset:34816
	ds_read_b128 v[204:207], v157 offset:36864
	ds_read_b128 v[208:211], v157 offset:38912
	ds_read_b128 v[212:215], v158 offset:36864
	ds_read_b128 v[216:219], v158 offset:38912
	global_load_lds_dwordx4 v130, s[26:27]
	s_mov_b32 m0, s41
	s_nop 0
	global_load_lds_dwordx4 v134, s[26:27]
	s_waitcnt vmcnt(8)
	s_waitcnt lgkmcnt(0)
	s_barrier
	s_setprio 1
	s_waitcnt lgkmcnt(0)
	v_mfma_f32_16x16x32_bf16 v[126:129], v[150:153], v[188:191], v[126:129]
	v_mfma_f32_16x16x32_bf16 v[126:129], v[160:163], v[196:199], v[126:129]
	v_mfma_f32_16x16x32_bf16 v[118:121], v[164:167], v[188:191], v[118:121]
	v_mfma_f32_16x16x32_bf16 v[118:121], v[168:171], v[196:199], v[118:121]
	v_mfma_f32_16x16x32_bf16 v[110:113], v[150:153], v[192:195], v[110:113]
	v_mfma_f32_16x16x32_bf16 v[110:113], v[160:163], v[200:203], v[110:113]
	v_mfma_f32_16x16x32_bf16 v[102:105], v[164:167], v[192:195], v[102:105]
	v_mfma_f32_16x16x32_bf16 v[102:105], v[168:171], v[200:203], v[102:105]
	v_mfma_f32_16x16x32_bf16 v[94:97], v[150:153], v[204:207], v[94:97]
	v_mfma_f32_16x16x32_bf16 v[94:97], v[160:163], v[212:215], v[94:97]
	v_mfma_f32_16x16x32_bf16 v[86:89], v[164:167], v[204:207], v[86:89]
	v_mfma_f32_16x16x32_bf16 v[86:89], v[168:171], v[212:215], v[86:89]
	v_mfma_f32_16x16x32_bf16 v[78:81], v[150:153], v[208:211], v[78:81]
	v_mfma_f32_16x16x32_bf16 v[78:81], v[160:163], v[216:219], v[78:81]
	v_mfma_f32_16x16x32_bf16 v[70:73], v[164:167], v[208:211], v[70:73]
	v_mfma_f32_16x16x32_bf16 v[70:73], v[168:171], v[216:219], v[70:73]
	s_setprio 0
	s_setprio 1
	v_mfma_f32_16x16x32_bf16 v[122:125], v[172:175], v[188:191], v[122:125]
	v_mfma_f32_16x16x32_bf16 v[122:125], v[176:179], v[196:199], v[122:125]
	v_mfma_f32_16x16x32_bf16 v[114:117], v[180:183], v[188:191], v[114:117]
	v_mfma_f32_16x16x32_bf16 v[114:117], v[184:187], v[196:199], v[114:117]
	v_mfma_f32_16x16x32_bf16 v[106:109], v[172:175], v[192:195], v[106:109]
	v_mfma_f32_16x16x32_bf16 v[106:109], v[176:179], v[200:203], v[106:109]
	v_mfma_f32_16x16x32_bf16 v[98:101], v[180:183], v[192:195], v[98:101]
	v_mfma_f32_16x16x32_bf16 v[98:101], v[184:187], v[200:203], v[98:101]
	v_mfma_f32_16x16x32_bf16 v[90:93], v[172:175], v[204:207], v[90:93]
	v_mfma_f32_16x16x32_bf16 v[90:93], v[176:179], v[212:215], v[90:93]
	v_mfma_f32_16x16x32_bf16 v[82:85], v[180:183], v[204:207], v[82:85]
	v_mfma_f32_16x16x32_bf16 v[82:85], v[184:187], v[212:215], v[82:85]
	v_mfma_f32_16x16x32_bf16 v[74:77], v[172:175], v[208:211], v[74:77]
	v_mfma_f32_16x16x32_bf16 v[74:77], v[176:179], v[216:219], v[74:77]
	v_mfma_f32_16x16x32_bf16 v[66:69], v[180:183], v[208:211], v[66:69]
	v_mfma_f32_16x16x32_bf16 v[66:69], v[184:187], v[216:219], v[66:69]
	s_setprio 0
	s_barrier
	s_add_i32 s26, s64, s21
	s_add_i32 m0, s26, 0xffffff80
	ds_read_b128 v[188:191], v157 offset:49152
	ds_read_b128 v[192:195], v157 offset:51200
	ds_read_b128 v[196:199], v158 offset:49152
	ds_read_b128 v[200:203], v158 offset:51200
	ds_read_b128 v[204:207], v157 offset:53248
	ds_read_b128 v[208:211], v157 offset:55296
	ds_read_b128 v[212:215], v158 offset:53248
	ds_read_b128 v[216:219], v158 offset:55296
	global_load_lds_dwordx4 v132, s[24:25] offset:128
	s_add_i32 m0, s26, 0x1f80
	s_add_i32 s26, s65, s21
	global_load_lds_dwordx4 v136, s[24:25] offset:128
	s_add_u32 s24, s24, 0x40080
	s_addc_u32 s25, s25, 0
	s_mov_b32 m0, s26
	s_nop 0
	global_load_lds_dwordx4 v132, s[24:25]
	s_add_i32 m0, s26, 0x2000
	s_nop 0
	global_load_lds_dwordx4 v136, s[24:25]
	s_add_i32 m0, s44, 0xffffff80
	s_nop 0
	global_load_lds_dwordx4 v130, s[98:99] offset:128
	s_add_i32 m0, s45, 0xffffff80
	s_nop 0
	global_load_lds_dwordx4 v134, s[98:99] offset:128
	s_waitcnt vmcnt(8)
	s_waitcnt lgkmcnt(0)
	s_barrier
	s_setprio 1
	s_waitcnt lgkmcnt(0)
	v_mfma_f32_16x16x32_bf16 v[62:65], v[150:153], v[188:191], v[62:65]
	v_mfma_f32_16x16x32_bf16 v[62:65], v[160:163], v[196:199], v[62:65]
	v_mfma_f32_16x16x32_bf16 v[54:57], v[164:167], v[188:191], v[54:57]
	v_mfma_f32_16x16x32_bf16 v[54:57], v[168:171], v[196:199], v[54:57]
	v_mfma_f32_16x16x32_bf16 v[46:49], v[150:153], v[192:195], v[46:49]
	v_mfma_f32_16x16x32_bf16 v[46:49], v[160:163], v[200:203], v[46:49]
	v_mfma_f32_16x16x32_bf16 v[38:41], v[164:167], v[192:195], v[38:41]
	v_mfma_f32_16x16x32_bf16 v[38:41], v[168:171], v[200:203], v[38:41]
	v_mfma_f32_16x16x32_bf16 v[30:33], v[150:153], v[204:207], v[30:33]
	v_mfma_f32_16x16x32_bf16 v[30:33], v[160:163], v[212:215], v[30:33]
	v_mfma_f32_16x16x32_bf16 v[22:25], v[164:167], v[204:207], v[22:25]
	v_mfma_f32_16x16x32_bf16 v[22:25], v[168:171], v[212:215], v[22:25]
	v_mfma_f32_16x16x32_bf16 v[14:17], v[150:153], v[208:211], v[14:17]
	v_mfma_f32_16x16x32_bf16 v[14:17], v[160:163], v[216:219], v[14:17]
	v_mfma_f32_16x16x32_bf16 v[6:9], v[164:167], v[208:211], v[6:9]
	v_mfma_f32_16x16x32_bf16 v[6:9], v[168:171], v[216:219], v[6:9]
	s_setprio 0
	s_setprio 1
	v_mfma_f32_16x16x32_bf16 v[58:61], v[172:175], v[188:191], v[58:61]
	v_mfma_f32_16x16x32_bf16 v[58:61], v[176:179], v[196:199], v[58:61]
	v_mfma_f32_16x16x32_bf16 v[50:53], v[180:183], v[188:191], v[50:53]
	v_mfma_f32_16x16x32_bf16 v[50:53], v[184:187], v[196:199], v[50:53]
	v_mfma_f32_16x16x32_bf16 v[42:45], v[172:175], v[192:195], v[42:45]
	v_mfma_f32_16x16x32_bf16 v[42:45], v[176:179], v[200:203], v[42:45]
	v_mfma_f32_16x16x32_bf16 v[34:37], v[180:183], v[192:195], v[34:37]
	v_mfma_f32_16x16x32_bf16 v[34:37], v[184:187], v[200:203], v[34:37]
	v_mfma_f32_16x16x32_bf16 v[26:29], v[172:175], v[204:207], v[26:29]
	v_mfma_f32_16x16x32_bf16 v[26:29], v[176:179], v[212:215], v[26:29]
	v_mfma_f32_16x16x32_bf16 v[18:21], v[180:183], v[204:207], v[18:21]
	v_mfma_f32_16x16x32_bf16 v[18:21], v[184:187], v[212:215], v[18:21]
	v_mfma_f32_16x16x32_bf16 v[10:13], v[172:175], v[208:211], v[10:13]
	v_mfma_f32_16x16x32_bf16 v[10:13], v[176:179], v[216:219], v[10:13]
	v_mfma_f32_16x16x32_bf16 v[2:5], v[180:183], v[208:211], v[2:5]
	v_mfma_f32_16x16x32_bf16 v[2:5], v[184:187], v[216:219], v[2:5]
	s_setprio 0
	s_barrier
	s_add_i32 s63, s63, 2
	s_add_u32 s22, s22, 0x100
	s_addc_u32 s23, s23, 0
	s_add_u32 s61, s61, 0x100
	s_addc_u32 s62, s62, 0
	s_cmp_gt_u32 s63, 13
	s_cbranch_scc1 .LBB0_1725
	s_branch .LBB0_1722

.LBB0_1827:
	s_cmp_lg_u32 s100, 0
	s_cbranch_scc1 .Lpeel_6
	ds_read_b128 v[120:123], v220
	ds_read_b128 v[128:131], v221
	ds_read_b128 v[136:139], v222
	ds_read_b128 v[140:143], v223
	ds_read_b128 v[144:147], v224
	ds_read_b128 v[148:151], v225
	ds_read_b128 v[152:155], v226
	ds_read_b128 v[156:159], v227
	s_add_u32 s40, s4, 0xfff50080
	s_addc_u32 s41, s5, -1
	s_cmp_eq_u32 s66, 40
	s_cselect_b32 s43, s29, s41
	s_cselect_b32 s42, s28, s40
	s_cselect_b32 s41, s35, s65
	s_cselect_b32 s40, s34, s64
	s_add_i32 m0, s44, 0xc000
	ds_read_b128 v[160:163], v228
	ds_read_b128 v[164:167], v228 offset:2048
	ds_read_b128 v[168:171], v229
	ds_read_b128 v[172:175], v229 offset:2048
	ds_read_b128 v[176:179], v228 offset:4096
	ds_read_b128 v[180:183], v228 offset:6144
	ds_read_b128 v[184:187], v229 offset:4096
	ds_read_b128 v[188:191], v229 offset:6144
	global_load_lds_dwordx4 v202, s[4:5]
	s_add_i32 m0, s44, 0xe000
	s_nop 0
	global_load_lds_dwordx4 v204, s[4:5]
	s_waitcnt vmcnt(8)
	s_waitcnt lgkmcnt(0)
	s_barrier
	s_setprio 1
	s_waitcnt lgkmcnt(0)
	v_mfma_f32_16x16x32_bf16 v[132:135], v[120:123], v[160:163], v[132:135]
	v_mfma_f32_16x16x32_bf16 v[132:135], v[128:131], v[168:171], v[132:135]
	v_mfma_f32_16x16x32_bf16 v[124:127], v[136:139], v[160:163], v[124:127]
	v_mfma_f32_16x16x32_bf16 v[124:127], v[140:143], v[168:171], v[124:127]
	v_mfma_f32_16x16x32_bf16 v[108:111], v[120:123], v[164:167], v[108:111]
	v_mfma_f32_16x16x32_bf16 v[108:111], v[128:131], v[172:175], v[108:111]
	v_mfma_f32_16x16x32_bf16 v[104:107], v[136:139], v[164:167], v[104:107]
	v_mfma_f32_16x16x32_bf16 v[104:107], v[140:143], v[172:175], v[104:107]
	v_mfma_f32_16x16x32_bf16 v[92:95], v[120:123], v[176:179], v[92:95]
	v_mfma_f32_16x16x32_bf16 v[92:95], v[128:131], v[184:187], v[92:95]
	v_mfma_f32_16x16x32_bf16 v[88:91], v[136:139], v[176:179], v[88:91]
	v_mfma_f32_16x16x32_bf16 v[88:91], v[140:143], v[184:187], v[88:91]
	v_mfma_f32_16x16x32_bf16 v[76:79], v[120:123], v[180:183], v[76:79]
	v_mfma_f32_16x16x32_bf16 v[76:79], v[128:131], v[188:191], v[76:79]
	v_mfma_f32_16x16x32_bf16 v[72:75], v[136:139], v[180:183], v[72:75]
	v_mfma_f32_16x16x32_bf16 v[72:75], v[140:143], v[188:191], v[72:75]
	s_setprio 0
	s_setprio 1
	v_mfma_f32_16x16x32_bf16 v[116:119], v[144:147], v[160:163], v[116:119]
	v_mfma_f32_16x16x32_bf16 v[116:119], v[148:151], v[168:171], v[116:119]
	v_mfma_f32_16x16x32_bf16 v[112:115], v[152:155], v[160:163], v[112:115]
	v_mfma_f32_16x16x32_bf16 v[112:115], v[156:159], v[168:171], v[112:115]
	v_mfma_f32_16x16x32_bf16 v[100:103], v[144:147], v[164:167], v[100:103]
	v_mfma_f32_16x16x32_bf16 v[100:103], v[148:151], v[172:175], v[100:103]
	v_mfma_f32_16x16x32_bf16 v[96:99], v[152:155], v[164:167], v[96:99]
	v_mfma_f32_16x16x32_bf16 v[96:99], v[156:159], v[172:175], v[96:99]
	v_mfma_f32_16x16x32_bf16 v[84:87], v[144:147], v[176:179], v[84:87]
	v_mfma_f32_16x16x32_bf16 v[84:87], v[148:151], v[184:187], v[84:87]
	v_mfma_f32_16x16x32_bf16 v[80:83], v[152:155], v[176:179], v[80:83]
	v_mfma_f32_16x16x32_bf16 v[80:83], v[156:159], v[184:187], v[80:83]
	v_mfma_f32_16x16x32_bf16 v[68:71], v[144:147], v[180:183], v[68:71]
	v_mfma_f32_16x16x32_bf16 v[68:71], v[148:151], v[188:191], v[68:71]
	v_mfma_f32_16x16x32_bf16 v[64:67], v[152:155], v[180:183], v[64:67]
	v_mfma_f32_16x16x32_bf16 v[64:67], v[156:159], v[188:191], v[64:67]
	s_setprio 0
	s_barrier
	s_add_i32 s67, s58, s39
	s_mov_b32 m0, s67
	ds_read_b128 v[160:163], v228 offset:16384
	ds_read_b128 v[164:167], v228 offset:18432
	ds_read_b128 v[168:171], v229 offset:16384
	ds_read_b128 v[172:175], v229 offset:18432
	ds_read_b128 v[176:179], v228 offset:20480
	ds_read_b128 v[180:183], v228 offset:22528
	ds_read_b128 v[184:187], v229 offset:20480
	ds_read_b128 v[188:191], v229 offset:22528
	global_load_lds_dwordx4 v194, s[40:41]
	s_add_i32 m0, s67, 0x2000
	s_add_u32 s68, s40, 0xb0000
	s_addc_u32 s69, s41, 0
	s_add_i32 s67, s59, s39
	global_load_lds_dwordx4 v198, s[40:41]
	s_mov_b32 m0, s67
	s_mov_b64 s[98:99], s[42:43]
	global_load_lds_dwordx4 v194, s[68:69]
	s_add_i32 m0, s67, 0x2000
	s_nop 0
	global_load_lds_dwordx4 v198, s[68:69]
	s_mov_b32 m0, s44
	s_nop 0
	global_load_lds_dwordx4 v192, s[42:43]
	s_mov_b32 m0, s45
	s_nop 0
	global_load_lds_dwordx4 v196, s[42:43]
	s_waitcnt vmcnt(8)
	s_waitcnt lgkmcnt(0)
	s_barrier
	s_setprio 1
	s_waitcnt lgkmcnt(0)
	v_mfma_f32_16x16x32_bf16 v[60:63], v[120:123], v[160:163], v[60:63]
	v_mfma_f32_16x16x32_bf16 v[60:63], v[128:131], v[168:171], v[60:63]
	v_mfma_f32_16x16x32_bf16 v[56:59], v[136:139], v[160:163], v[56:59]
	v_mfma_f32_16x16x32_bf16 v[56:59], v[140:143], v[168:171], v[56:59]
	v_mfma_f32_16x16x32_bf16 v[44:47], v[120:123], v[164:167], v[44:47]
	v_mfma_f32_16x16x32_bf16 v[44:47], v[128:131], v[172:175], v[44:47]
	v_mfma_f32_16x16x32_bf16 v[40:43], v[136:139], v[164:167], v[40:43]
	v_mfma_f32_16x16x32_bf16 v[40:43], v[140:143], v[172:175], v[40:43]
	v_mfma_f32_16x16x32_bf16 v[28:31], v[120:123], v[176:179], v[28:31]
	v_mfma_f32_16x16x32_bf16 v[28:31], v[128:131], v[184:187], v[28:31]
	v_mfma_f32_16x16x32_bf16 v[24:27], v[136:139], v[176:179], v[24:27]
	v_mfma_f32_16x16x32_bf16 v[24:27], v[140:143], v[184:187], v[24:27]
	v_mfma_f32_16x16x32_bf16 v[12:15], v[120:123], v[180:183], v[12:15]
	v_mfma_f32_16x16x32_bf16 v[12:15], v[128:131], v[188:191], v[12:15]
	v_mfma_f32_16x16x32_bf16 v[8:11], v[136:139], v[180:183], v[8:11]
	v_mfma_f32_16x16x32_bf16 v[8:11], v[140:143], v[188:191], v[8:11]
	s_setprio 0
	s_setprio 1
	v_mfma_f32_16x16x32_bf16 v[52:55], v[144:147], v[160:163], v[52:55]
	v_mfma_f32_16x16x32_bf16 v[52:55], v[148:151], v[168:171], v[52:55]
	v_mfma_f32_16x16x32_bf16 v[48:51], v[152:155], v[160:163], v[48:51]
	v_mfma_f32_16x16x32_bf16 v[48:51], v[156:159], v[168:171], v[48:51]
	v_mfma_f32_16x16x32_bf16 v[36:39], v[144:147], v[164:167], v[36:39]
	v_mfma_f32_16x16x32_bf16 v[36:39], v[148:151], v[172:175], v[36:39]
	v_mfma_f32_16x16x32_bf16 v[32:35], v[152:155], v[164:167], v[32:35]
	v_mfma_f32_16x16x32_bf16 v[32:35], v[156:159], v[172:175], v[32:35]
	v_mfma_f32_16x16x32_bf16 v[20:23], v[144:147], v[176:179], v[20:23]
	v_mfma_f32_16x16x32_bf16 v[20:23], v[148:151], v[184:187], v[20:23]
	v_mfma_f32_16x16x32_bf16 v[16:19], v[152:155], v[176:179], v[16:19]
	v_mfma_f32_16x16x32_bf16 v[16:19], v[156:159], v[184:187], v[16:19]
	v_mfma_f32_16x16x32_bf16 v[4:7], v[144:147], v[180:183], v[4:7]
	v_mfma_f32_16x16x32_bf16 v[4:7], v[148:151], v[188:191], v[4:7]
	v_mfma_f32_16x16x32_bf16 v[0:3], v[152:155], v[180:183], v[0:3]
	v_mfma_f32_16x16x32_bf16 v[0:3], v[156:159], v[188:191], v[0:3]
	s_setprio 0
	s_barrier
	s_add_i32 s67, 0, 0x18000
	s_add_i32 s68, 0, 0x1c000
	ds_read_b128 v[120:123], v245 offset:32768
	ds_read_b128 v[128:131], v246 offset:32768
	ds_read_b128 v[136:139], v230
	ds_read_b128 v[140:143], v231
	ds_read_b128 v[144:147], v245 offset:49152
	ds_read_b128 v[148:151], v246 offset:49152
	ds_read_b128 v[152:155], v232
	ds_read_b128 v[156:159], v233
	s_add_u32 s42, s42, 0xb0000
	s_addc_u32 s43, s43, 0
	s_mov_b32 m0, s46
	ds_read_b128 v[160:163], v228 offset:32768
	ds_read_b128 v[164:167], v228 offset:34816
	ds_read_b128 v[168:171], v229 offset:32768
	ds_read_b128 v[172:175], v229 offset:34816
	ds_read_b128 v[176:179], v228 offset:36864
	ds_read_b128 v[180:183], v228 offset:38912
	ds_read_b128 v[184:187], v229 offset:36864
	ds_read_b128 v[188:191], v229 offset:38912
	global_load_lds_dwordx4 v192, s[42:43]
	s_mov_b32 m0, s47
	s_nop 0
	global_load_lds_dwordx4 v196, s[42:43]
	s_waitcnt vmcnt(8)
	s_waitcnt lgkmcnt(0)
	s_barrier
	s_setprio 1
	s_waitcnt lgkmcnt(0)
	v_mfma_f32_16x16x32_bf16 v[132:135], v[120:123], v[160:163], v[132:135]
	v_mfma_f32_16x16x32_bf16 v[132:135], v[128:131], v[168:171], v[132:135]
	v_mfma_f32_16x16x32_bf16 v[124:127], v[136:139], v[160:163], v[124:127]
	v_mfma_f32_16x16x32_bf16 v[124:127], v[140:143], v[168:171], v[124:127]
	v_mfma_f32_16x16x32_bf16 v[108:111], v[120:123], v[164:167], v[108:111]
	v_mfma_f32_16x16x32_bf16 v[108:111], v[128:131], v[172:175], v[108:111]
	v_mfma_f32_16x16x32_bf16 v[104:107], v[136:139], v[164:167], v[104:107]
	v_mfma_f32_16x16x32_bf16 v[104:107], v[140:143], v[172:175], v[104:107]
	v_mfma_f32_16x16x32_bf16 v[92:95], v[120:123], v[176:179], v[92:95]
	v_mfma_f32_16x16x32_bf16 v[92:95], v[128:131], v[184:187], v[92:95]
	v_mfma_f32_16x16x32_bf16 v[88:91], v[136:139], v[176:179], v[88:91]
	v_mfma_f32_16x16x32_bf16 v[88:91], v[140:143], v[184:187], v[88:91]
	v_mfma_f32_16x16x32_bf16 v[76:79], v[120:123], v[180:183], v[76:79]
	v_mfma_f32_16x16x32_bf16 v[76:79], v[128:131], v[188:191], v[76:79]
	v_mfma_f32_16x16x32_bf16 v[72:75], v[136:139], v[180:183], v[72:75]
	v_mfma_f32_16x16x32_bf16 v[72:75], v[140:143], v[188:191], v[72:75]
	s_setprio 0
	s_setprio 1
	v_mfma_f32_16x16x32_bf16 v[116:119], v[144:147], v[160:163], v[116:119]
	v_mfma_f32_16x16x32_bf16 v[116:119], v[148:151], v[168:171], v[116:119]
	v_mfma_f32_16x16x32_bf16 v[112:115], v[152:155], v[160:163], v[112:115]
	v_mfma_f32_16x16x32_bf16 v[112:115], v[156:159], v[168:171], v[112:115]
	v_mfma_f32_16x16x32_bf16 v[100:103], v[144:147], v[164:167], v[100:103]
	v_mfma_f32_16x16x32_bf16 v[100:103], v[148:151], v[172:175], v[100:103]
	v_mfma_f32_16x16x32_bf16 v[96:99], v[152:155], v[164:167], v[96:99]
	v_mfma_f32_16x16x32_bf16 v[96:99], v[156:159], v[172:175], v[96:99]
	v_mfma_f32_16x16x32_bf16 v[84:87], v[144:147], v[176:179], v[84:87]
	v_mfma_f32_16x16x32_bf16 v[84:87], v[148:151], v[184:187], v[84:87]
	v_mfma_f32_16x16x32_bf16 v[80:83], v[152:155], v[176:179], v[80:83]
	v_mfma_f32_16x16x32_bf16 v[80:83], v[156:159], v[184:187], v[80:83]
	v_mfma_f32_16x16x32_bf16 v[68:71], v[144:147], v[180:183], v[68:71]
	v_mfma_f32_16x16x32_bf16 v[68:71], v[148:151], v[188:191], v[68:71]
	v_mfma_f32_16x16x32_bf16 v[64:67], v[152:155], v[180:183], v[64:67]
	v_mfma_f32_16x16x32_bf16 v[64:67], v[156:159], v[188:191], v[64:67]
	s_setprio 0
	s_barrier
	s_add_i32 s42, s67, s39
	s_add_i32 m0, s42, 0xffffff80
	ds_read_b128 v[160:163], v228 offset:49152
	ds_read_b128 v[164:167], v228 offset:51200
	ds_read_b128 v[168:171], v229 offset:49152
	ds_read_b128 v[172:175], v229 offset:51200
	ds_read_b128 v[176:179], v228 offset:53248
	ds_read_b128 v[180:183], v228 offset:55296
	ds_read_b128 v[184:187], v229 offset:53248
	ds_read_b128 v[188:191], v229 offset:55296
	global_load_lds_dwordx4 v194, s[40:41] offset:128
	s_add_i32 m0, s42, 0x1f80
	s_add_i32 s42, s68, s39
	global_load_lds_dwordx4 v198, s[40:41] offset:128
	s_add_u32 s40, s40, 0xb0080
	s_addc_u32 s41, s41, 0
	s_mov_b32 m0, s42
	s_nop 0
	global_load_lds_dwordx4 v194, s[40:41]
	s_add_i32 m0, s42, 0x2000
	s_nop 0
	global_load_lds_dwordx4 v198, s[40:41]
	s_add_i32 m0, s51, 0xffffff80
	s_nop 0
	global_load_lds_dwordx4 v192, s[98:99] offset:128
	s_add_i32 m0, s52, 0xffffff80
	s_nop 0
	global_load_lds_dwordx4 v196, s[98:99] offset:128
	s_waitcnt vmcnt(8)
	s_waitcnt lgkmcnt(0)
	s_barrier
	s_setprio 1
	s_waitcnt lgkmcnt(0)
	v_mfma_f32_16x16x32_bf16 v[60:63], v[120:123], v[160:163], v[60:63]
	v_mfma_f32_16x16x32_bf16 v[60:63], v[128:131], v[168:171], v[60:63]
	v_mfma_f32_16x16x32_bf16 v[56:59], v[136:139], v[160:163], v[56:59]
	v_mfma_f32_16x16x32_bf16 v[56:59], v[140:143], v[168:171], v[56:59]
	v_mfma_f32_16x16x32_bf16 v[44:47], v[120:123], v[164:167], v[44:47]
	v_mfma_f32_16x16x32_bf16 v[44:47], v[128:131], v[172:175], v[44:47]
	v_mfma_f32_16x16x32_bf16 v[40:43], v[136:139], v[164:167], v[40:43]
	v_mfma_f32_16x16x32_bf16 v[40:43], v[140:143], v[172:175], v[40:43]
	v_mfma_f32_16x16x32_bf16 v[28:31], v[120:123], v[176:179], v[28:31]
	v_mfma_f32_16x16x32_bf16 v[28:31], v[128:131], v[184:187], v[28:31]
	v_mfma_f32_16x16x32_bf16 v[24:27], v[136:139], v[176:179], v[24:27]
	v_mfma_f32_16x16x32_bf16 v[24:27], v[140:143], v[184:187], v[24:27]
	v_mfma_f32_16x16x32_bf16 v[12:15], v[120:123], v[180:183], v[12:15]
	v_mfma_f32_16x16x32_bf16 v[12:15], v[128:131], v[188:191], v[12:15]
	v_mfma_f32_16x16x32_bf16 v[8:11], v[136:139], v[180:183], v[8:11]
	v_mfma_f32_16x16x32_bf16 v[8:11], v[140:143], v[188:191], v[8:11]
	s_setprio 0
	s_setprio 1
	v_mfma_f32_16x16x32_bf16 v[52:55], v[144:147], v[160:163], v[52:55]
	v_mfma_f32_16x16x32_bf16 v[52:55], v[148:151], v[168:171], v[52:55]
	v_mfma_f32_16x16x32_bf16 v[48:51], v[152:155], v[160:163], v[48:51]
	v_mfma_f32_16x16x32_bf16 v[48:51], v[156:159], v[168:171], v[48:51]
	v_mfma_f32_16x16x32_bf16 v[36:39], v[144:147], v[164:167], v[36:39]
	v_mfma_f32_16x16x32_bf16 v[36:39], v[148:151], v[172:175], v[36:39]
	v_mfma_f32_16x16x32_bf16 v[32:35], v[152:155], v[164:167], v[32:35]
	v_mfma_f32_16x16x32_bf16 v[32:35], v[156:159], v[172:175], v[32:35]
	v_mfma_f32_16x16x32_bf16 v[20:23], v[144:147], v[176:179], v[20:23]
	v_mfma_f32_16x16x32_bf16 v[20:23], v[148:151], v[184:187], v[20:23]
	v_mfma_f32_16x16x32_bf16 v[16:19], v[152:155], v[176:179], v[16:19]
	v_mfma_f32_16x16x32_bf16 v[16:19], v[156:159], v[184:187], v[16:19]
	v_mfma_f32_16x16x32_bf16 v[4:7], v[144:147], v[180:183], v[4:7]
	v_mfma_f32_16x16x32_bf16 v[4:7], v[148:151], v[188:191], v[4:7]
	v_mfma_f32_16x16x32_bf16 v[0:3], v[152:155], v[180:183], v[0:3]
	v_mfma_f32_16x16x32_bf16 v[0:3], v[156:159], v[188:191], v[0:3]
	s_setprio 0
	s_barrier
	s_add_i32 s66, s66, 2
	s_add_u32 s4, s4, 0x100
	s_addc_u32 s5, s5, 0
	s_add_u32 s64, s64, 0x100
	s_addc_u32 s65, s65, 0
	s_cmp_gt_u32 s66, 41
	s_cbranch_scc0 .LBB0_1827
	s_branch .Lpx_6
.Lpeel_6:
	s_mov_b32 s100, 0
	ds_read_b128 v[120:123], v220
	ds_read_b128 v[128:131], v221
	ds_read_b128 v[136:139], v222
	ds_read_b128 v[140:143], v223
	ds_read_b128 v[144:147], v224
	ds_read_b128 v[148:151], v225
	ds_read_b128 v[152:155], v226
	ds_read_b128 v[156:159], v227
	s_add_u32 s40, s4, 0xfff50080
	s_addc_u32 s41, s5, -1
	s_cmp_eq_u32 s66, 40
	s_cselect_b32 s43, s29, s41
	s_cselect_b32 s42, s28, s40
	s_cselect_b32 s41, s35, s65
	s_cselect_b32 s40, s34, s64
	s_add_i32 m0, s44, 0xc000
	ds_read_b128 v[160:163], v228
	ds_read_b128 v[164:167], v228 offset:2048
	ds_read_b128 v[168:171], v229
	ds_read_b128 v[172:175], v229 offset:2048
	ds_read_b128 v[176:179], v228 offset:4096
	ds_read_b128 v[180:183], v228 offset:6144
	ds_read_b128 v[184:187], v229 offset:4096
	ds_read_b128 v[188:191], v229 offset:6144
	global_load_lds_dwordx4 v202, s[4:5]
	s_add_i32 m0, s44, 0xe000
	s_nop 0
	global_load_lds_dwordx4 v204, s[4:5]
	s_waitcnt vmcnt(8)
	s_waitcnt lgkmcnt(0)
	s_barrier
	s_setprio 1
	s_waitcnt lgkmcnt(0)
	v_mfma_f32_16x16x32_bf16 v[132:135], v[120:123], v[160:163], 0
	v_mfma_f32_16x16x32_bf16 v[132:135], v[128:131], v[168:171], v[132:135]
	v_mfma_f32_16x16x32_bf16 v[124:127], v[136:139], v[160:163], 0
	v_mfma_f32_16x16x32_bf16 v[124:127], v[140:143], v[168:171], v[124:127]
	v_mfma_f32_16x16x32_bf16 v[108:111], v[120:123], v[164:167], 0
	v_mfma_f32_16x16x32_bf16 v[108:111], v[128:131], v[172:175], v[108:111]
	v_mfma_f32_16x16x32_bf16 v[104:107], v[136:139], v[164:167], 0
	v_mfma_f32_16x16x32_bf16 v[104:107], v[140:143], v[172:175], v[104:107]
	v_mfma_f32_16x16x32_bf16 v[92:95], v[120:123], v[176:179], 0
	v_mfma_f32_16x16x32_bf16 v[92:95], v[128:131], v[184:187], v[92:95]
	v_mfma_f32_16x16x32_bf16 v[88:91], v[136:139], v[176:179], 0
	v_mfma_f32_16x16x32_bf16 v[88:91], v[140:143], v[184:187], v[88:91]
	v_mfma_f32_16x16x32_bf16 v[76:79], v[120:123], v[180:183], 0
	v_mfma_f32_16x16x32_bf16 v[76:79], v[128:131], v[188:191], v[76:79]
	v_mfma_f32_16x16x32_bf16 v[72:75], v[136:139], v[180:183], 0
	v_mfma_f32_16x16x32_bf16 v[72:75], v[140:143], v[188:191], v[72:75]
	s_setprio 0
	s_setprio 1
	v_mfma_f32_16x16x32_bf16 v[116:119], v[144:147], v[160:163], 0
	v_mfma_f32_16x16x32_bf16 v[116:119], v[148:151], v[168:171], v[116:119]
	v_mfma_f32_16x16x32_bf16 v[112:115], v[152:155], v[160:163], 0
	v_mfma_f32_16x16x32_bf16 v[112:115], v[156:159], v[168:171], v[112:115]
	v_mfma_f32_16x16x32_bf16 v[100:103], v[144:147], v[164:167], 0
	v_mfma_f32_16x16x32_bf16 v[100:103], v[148:151], v[172:175], v[100:103]
	v_mfma_f32_16x16x32_bf16 v[96:99], v[152:155], v[164:167], 0
	v_mfma_f32_16x16x32_bf16 v[96:99], v[156:159], v[172:175], v[96:99]
	v_mfma_f32_16x16x32_bf16 v[84:87], v[144:147], v[176:179], 0
	v_mfma_f32_16x16x32_bf16 v[84:87], v[148:151], v[184:187], v[84:87]
	v_mfma_f32_16x16x32_bf16 v[80:83], v[152:155], v[176:179], 0
	v_mfma_f32_16x16x32_bf16 v[80:83], v[156:159], v[184:187], v[80:83]
	v_mfma_f32_16x16x32_bf16 v[68:71], v[144:147], v[180:183], 0
	v_mfma_f32_16x16x32_bf16 v[68:71], v[148:151], v[188:191], v[68:71]
	v_mfma_f32_16x16x32_bf16 v[64:67], v[152:155], v[180:183], 0
	v_mfma_f32_16x16x32_bf16 v[64:67], v[156:159], v[188:191], v[64:67]
	s_setprio 0
	s_barrier
	s_add_i32 s67, s58, s39
	s_mov_b32 m0, s67
	ds_read_b128 v[160:163], v228 offset:16384
	ds_read_b128 v[164:167], v228 offset:18432
	ds_read_b128 v[168:171], v229 offset:16384
	ds_read_b128 v[172:175], v229 offset:18432
	ds_read_b128 v[176:179], v228 offset:20480
	ds_read_b128 v[180:183], v228 offset:22528
	ds_read_b128 v[184:187], v229 offset:20480
	ds_read_b128 v[188:191], v229 offset:22528
	global_load_lds_dwordx4 v194, s[40:41]
	s_add_i32 m0, s67, 0x2000
	s_add_u32 s68, s40, 0xb0000
	s_addc_u32 s69, s41, 0
	s_add_i32 s67, s59, s39
	global_load_lds_dwordx4 v198, s[40:41]
	s_mov_b32 m0, s67
	s_mov_b64 s[98:99], s[42:43]
	global_load_lds_dwordx4 v194, s[68:69]
	s_add_i32 m0, s67, 0x2000
	s_nop 0
	global_load_lds_dwordx4 v198, s[68:69]
	s_mov_b32 m0, s44
	s_nop 0
	global_load_lds_dwordx4 v192, s[42:43]
	s_mov_b32 m0, s45
	s_nop 0
	global_load_lds_dwordx4 v196, s[42:43]
	s_waitcnt vmcnt(8)
	s_waitcnt lgkmcnt(0)
	s_barrier
	s_setprio 1
	s_waitcnt lgkmcnt(0)
	v_mfma_f32_16x16x32_bf16 v[60:63], v[120:123], v[160:163], 0
	v_mfma_f32_16x16x32_bf16 v[60:63], v[128:131], v[168:171], v[60:63]
	v_mfma_f32_16x16x32_bf16 v[56:59], v[136:139], v[160:163], 0
	v_mfma_f32_16x16x32_bf16 v[56:59], v[140:143], v[168:171], v[56:59]
	v_mfma_f32_16x16x32_bf16 v[44:47], v[120:123], v[164:167], 0
	v_mfma_f32_16x16x32_bf16 v[44:47], v[128:131], v[172:175], v[44:47]
	v_mfma_f32_16x16x32_bf16 v[40:43], v[136:139], v[164:167], 0
	v_mfma_f32_16x16x32_bf16 v[40:43], v[140:143], v[172:175], v[40:43]
	v_mfma_f32_16x16x32_bf16 v[28:31], v[120:123], v[176:179], 0
	v_mfma_f32_16x16x32_bf16 v[28:31], v[128:131], v[184:187], v[28:31]
	v_mfma_f32_16x16x32_bf16 v[24:27], v[136:139], v[176:179], 0
	v_mfma_f32_16x16x32_bf16 v[24:27], v[140:143], v[184:187], v[24:27]
	v_mfma_f32_16x16x32_bf16 v[12:15], v[120:123], v[180:183], 0
	v_mfma_f32_16x16x32_bf16 v[12:15], v[128:131], v[188:191], v[12:15]
	v_mfma_f32_16x16x32_bf16 v[8:11], v[136:139], v[180:183], 0
	v_mfma_f32_16x16x32_bf16 v[8:11], v[140:143], v[188:191], v[8:11]
	s_setprio 0
	s_setprio 1
	v_mfma_f32_16x16x32_bf16 v[52:55], v[144:147], v[160:163], 0
	v_mfma_f32_16x16x32_bf16 v[52:55], v[148:151], v[168:171], v[52:55]
	v_mfma_f32_16x16x32_bf16 v[48:51], v[152:155], v[160:163], 0
	v_mfma_f32_16x16x32_bf16 v[48:51], v[156:159], v[168:171], v[48:51]
	v_mfma_f32_16x16x32_bf16 v[36:39], v[144:147], v[164:167], 0
	v_mfma_f32_16x16x32_bf16 v[36:39], v[148:151], v[172:175], v[36:39]
	v_mfma_f32_16x16x32_bf16 v[32:35], v[152:155], v[164:167], 0
	v_mfma_f32_16x16x32_bf16 v[32:35], v[156:159], v[172:175], v[32:35]
	v_mfma_f32_16x16x32_bf16 v[20:23], v[144:147], v[176:179], 0
	v_mfma_f32_16x16x32_bf16 v[20:23], v[148:151], v[184:187], v[20:23]
	v_mfma_f32_16x16x32_bf16 v[16:19], v[152:155], v[176:179], 0
	v_mfma_f32_16x16x32_bf16 v[16:19], v[156:159], v[184:187], v[16:19]
	v_mfma_f32_16x16x32_bf16 v[4:7], v[144:147], v[180:183], 0
	v_mfma_f32_16x16x32_bf16 v[4:7], v[148:151], v[188:191], v[4:7]
	v_mfma_f32_16x16x32_bf16 v[0:3], v[152:155], v[180:183], 0
	v_mfma_f32_16x16x32_bf16 v[0:3], v[156:159], v[188:191], v[0:3]
	s_setprio 0
	s_barrier
	s_add_i32 s67, 0, 0x18000
	s_add_i32 s68, 0, 0x1c000
	ds_read_b128 v[120:123], v245 offset:32768
	ds_read_b128 v[128:131], v246 offset:32768
	ds_read_b128 v[136:139], v230
	ds_read_b128 v[140:143], v231
	ds_read_b128 v[144:147], v245 offset:49152
	ds_read_b128 v[148:151], v246 offset:49152
	ds_read_b128 v[152:155], v232
	ds_read_b128 v[156:159], v233
	s_add_u32 s42, s42, 0xb0000
	s_addc_u32 s43, s43, 0
	s_mov_b32 m0, s46
	ds_read_b128 v[160:163], v228 offset:32768
	ds_read_b128 v[164:167], v228 offset:34816
	ds_read_b128 v[168:171], v229 offset:32768
	ds_read_b128 v[172:175], v229 offset:34816
	ds_read_b128 v[176:179], v228 offset:36864
	ds_read_b128 v[180:183], v228 offset:38912
	ds_read_b128 v[184:187], v229 offset:36864
	ds_read_b128 v[188:191], v229 offset:38912
	global_load_lds_dwordx4 v192, s[42:43]
	s_mov_b32 m0, s47
	s_nop 0
	global_load_lds_dwordx4 v196, s[42:43]
	s_waitcnt vmcnt(8)
	s_waitcnt lgkmcnt(0)
	s_barrier
	s_setprio 1
	s_waitcnt lgkmcnt(0)
	v_mfma_f32_16x16x32_bf16 v[132:135], v[120:123], v[160:163], v[132:135]
	v_mfma_f32_16x16x32_bf16 v[132:135], v[128:131], v[168:171], v[132:135]
	v_mfma_f32_16x16x32_bf16 v[124:127], v[136:139], v[160:163], v[124:127]
	v_mfma_f32_16x16x32_bf16 v[124:127], v[140:143], v[168:171], v[124:127]
	v_mfma_f32_16x16x32_bf16 v[108:111], v[120:123], v[164:167], v[108:111]
	v_mfma_f32_16x16x32_bf16 v[108:111], v[128:131], v[172:175], v[108:111]
	v_mfma_f32_16x16x32_bf16 v[104:107], v[136:139], v[164:167], v[104:107]
	v_mfma_f32_16x16x32_bf16 v[104:107], v[140:143], v[172:175], v[104:107]
	v_mfma_f32_16x16x32_bf16 v[92:95], v[120:123], v[176:179], v[92:95]
	v_mfma_f32_16x16x32_bf16 v[92:95], v[128:131], v[184:187], v[92:95]
	v_mfma_f32_16x16x32_bf16 v[88:91], v[136:139], v[176:179], v[88:91]
	v_mfma_f32_16x16x32_bf16 v[88:91], v[140:143], v[184:187], v[88:91]
	v_mfma_f32_16x16x32_bf16 v[76:79], v[120:123], v[180:183], v[76:79]
	v_mfma_f32_16x16x32_bf16 v[76:79], v[128:131], v[188:191], v[76:79]
	v_mfma_f32_16x16x32_bf16 v[72:75], v[136:139], v[180:183], v[72:75]
	v_mfma_f32_16x16x32_bf16 v[72:75], v[140:143], v[188:191], v[72:75]
	s_setprio 0
	s_setprio 1
	v_mfma_f32_16x16x32_bf16 v[116:119], v[144:147], v[160:163], v[116:119]
	v_mfma_f32_16x16x32_bf16 v[116:119], v[148:151], v[168:171], v[116:119]
	v_mfma_f32_16x16x32_bf16 v[112:115], v[152:155], v[160:163], v[112:115]
	v_mfma_f32_16x16x32_bf16 v[112:115], v[156:159], v[168:171], v[112:115]
	v_mfma_f32_16x16x32_bf16 v[100:103], v[144:147], v[164:167], v[100:103]
	v_mfma_f32_16x16x32_bf16 v[100:103], v[148:151], v[172:175], v[100:103]
	v_mfma_f32_16x16x32_bf16 v[96:99], v[152:155], v[164:167], v[96:99]
	v_mfma_f32_16x16x32_bf16 v[96:99], v[156:159], v[172:175], v[96:99]
	v_mfma_f32_16x16x32_bf16 v[84:87], v[144:147], v[176:179], v[84:87]
	v_mfma_f32_16x16x32_bf16 v[84:87], v[148:151], v[184:187], v[84:87]
	v_mfma_f32_16x16x32_bf16 v[80:83], v[152:155], v[176:179], v[80:83]
	v_mfma_f32_16x16x32_bf16 v[80:83], v[156:159], v[184:187], v[80:83]
	v_mfma_f32_16x16x32_bf16 v[68:71], v[144:147], v[180:183], v[68:71]
	v_mfma_f32_16x16x32_bf16 v[68:71], v[148:151], v[188:191], v[68:71]
	v_mfma_f32_16x16x32_bf16 v[64:67], v[152:155], v[180:183], v[64:67]
	v_mfma_f32_16x16x32_bf16 v[64:67], v[156:159], v[188:191], v[64:67]
	s_setprio 0
	s_barrier
	s_add_i32 s42, s67, s39
	s_add_i32 m0, s42, 0xffffff80
	ds_read_b128 v[160:163], v228 offset:49152
	ds_read_b128 v[164:167], v228 offset:51200
	ds_read_b128 v[168:171], v229 offset:49152
	ds_read_b128 v[172:175], v229 offset:51200
	ds_read_b128 v[176:179], v228 offset:53248
	ds_read_b128 v[180:183], v228 offset:55296
	ds_read_b128 v[184:187], v229 offset:53248
	ds_read_b128 v[188:191], v229 offset:55296
	global_load_lds_dwordx4 v194, s[40:41] offset:128
	s_add_i32 m0, s42, 0x1f80
	s_add_i32 s42, s68, s39
	global_load_lds_dwordx4 v198, s[40:41] offset:128
	s_add_u32 s40, s40, 0xb0080
	s_addc_u32 s41, s41, 0
	s_mov_b32 m0, s42
	s_nop 0
	global_load_lds_dwordx4 v194, s[40:41]
	s_add_i32 m0, s42, 0x2000
	s_nop 0
	global_load_lds_dwordx4 v198, s[40:41]
	s_add_i32 m0, s51, 0xffffff80
	s_nop 0
	global_load_lds_dwordx4 v192, s[98:99] offset:128
	s_add_i32 m0, s52, 0xffffff80
	s_nop 0
	global_load_lds_dwordx4 v196, s[98:99] offset:128
	s_waitcnt vmcnt(8)
	s_waitcnt lgkmcnt(0)
	s_barrier
	s_setprio 1
	s_waitcnt lgkmcnt(0)
	v_mfma_f32_16x16x32_bf16 v[60:63], v[120:123], v[160:163], v[60:63]
	v_mfma_f32_16x16x32_bf16 v[60:63], v[128:131], v[168:171], v[60:63]
	v_mfma_f32_16x16x32_bf16 v[56:59], v[136:139], v[160:163], v[56:59]
	v_mfma_f32_16x16x32_bf16 v[56:59], v[140:143], v[168:171], v[56:59]
	v_mfma_f32_16x16x32_bf16 v[44:47], v[120:123], v[164:167], v[44:47]
	v_mfma_f32_16x16x32_bf16 v[44:47], v[128:131], v[172:175], v[44:47]
	v_mfma_f32_16x16x32_bf16 v[40:43], v[136:139], v[164:167], v[40:43]
	v_mfma_f32_16x16x32_bf16 v[40:43], v[140:143], v[172:175], v[40:43]
	v_mfma_f32_16x16x32_bf16 v[28:31], v[120:123], v[176:179], v[28:31]
	v_mfma_f32_16x16x32_bf16 v[28:31], v[128:131], v[184:187], v[28:31]
	v_mfma_f32_16x16x32_bf16 v[24:27], v[136:139], v[176:179], v[24:27]
	v_mfma_f32_16x16x32_bf16 v[24:27], v[140:143], v[184:187], v[24:27]
	v_mfma_f32_16x16x32_bf16 v[12:15], v[120:123], v[180:183], v[12:15]
	v_mfma_f32_16x16x32_bf16 v[12:15], v[128:131], v[188:191], v[12:15]
	v_mfma_f32_16x16x32_bf16 v[8:11], v[136:139], v[180:183], v[8:11]
	v_mfma_f32_16x16x32_bf16 v[8:11], v[140:143], v[188:191], v[8:11]
	s_setprio 0
	s_setprio 1
	v_mfma_f32_16x16x32_bf16 v[52:55], v[144:147], v[160:163], v[52:55]
	v_mfma_f32_16x16x32_bf16 v[52:55], v[148:151], v[168:171], v[52:55]
	v_mfma_f32_16x16x32_bf16 v[48:51], v[152:155], v[160:163], v[48:51]
	v_mfma_f32_16x16x32_bf16 v[48:51], v[156:159], v[168:171], v[48:51]
	v_mfma_f32_16x16x32_bf16 v[36:39], v[144:147], v[164:167], v[36:39]
	v_mfma_f32_16x16x32_bf16 v[36:39], v[148:151], v[172:175], v[36:39]
	v_mfma_f32_16x16x32_bf16 v[32:35], v[152:155], v[164:167], v[32:35]
	v_mfma_f32_16x16x32_bf16 v[32:35], v[156:159], v[172:175], v[32:35]
	v_mfma_f32_16x16x32_bf16 v[20:23], v[144:147], v[176:179], v[20:23]
	v_mfma_f32_16x16x32_bf16 v[20:23], v[148:151], v[184:187], v[20:23]
	v_mfma_f32_16x16x32_bf16 v[16:19], v[152:155], v[176:179], v[16:19]
	v_mfma_f32_16x16x32_bf16 v[16:19], v[156:159], v[184:187], v[16:19]
	v_mfma_f32_16x16x32_bf16 v[4:7], v[144:147], v[180:183], v[4:7]
	v_mfma_f32_16x16x32_bf16 v[4:7], v[148:151], v[188:191], v[4:7]
	v_mfma_f32_16x16x32_bf16 v[0:3], v[152:155], v[180:183], v[0:3]
	v_mfma_f32_16x16x32_bf16 v[0:3], v[156:159], v[188:191], v[0:3]
	s_setprio 0
	s_barrier
	s_add_i32 s66, s66, 2
	s_add_u32 s4, s4, 0x100
	s_addc_u32 s5, s5, 0
	s_add_u32 s64, s64, 0x100
	s_addc_u32 s65, s65, 0
	s_cmp_gt_u32 s66, 41
	s_cbranch_scc0 .LBB0_1827
